# residual-epilogue stores (f32 stream, bf16 copy, ssq partials) marked non-temporal
# speedup vs baseline: 1.0038x; 1.0038x over previous
.LBB0_1141:
	v_readfirstlane_b32 s40, v204
	s_lshr_b32 s40, s40, 6
	s_and_b32 s41, s40, 1
	s_bfe_u32 s42, s40, 0x10001
	s_lshr_b32 s43, s40, 2
	s_lshl_b32 s44, s4, 1
	s_add_i32 s44, s44, s42
	s_lshl_b32 s45, s44, 7
	s_lshl_b32 s46, s41, 6
	s_add_i32 s45, s45, s46
	s_lshl_b32 s46, s43, 7
	s_add_i32 s46, s46, s2
	s_lshl_b32 s47, s44, 1
	s_add_i32 s47, s47, s41
	v_readlane_b32 s36, v251, 50
	v_readlane_b32 s37, v251, 51
	v_readlane_b32 s38, v250, 9
	v_readlane_b32 s39, v250, 10
	v_readlane_b32 s50, v250, 11
	v_readlane_b32 s51, v250, 12
	s_add_u32 s34, s50, 0xf900000
	s_addc_u32 s35, s51, 0
	s_add_u32 s50, s50, 0x5800000
	s_addc_u32 s51, s51, 0
	s_lshl_b32 s48, s46, 12
	s_lshl_b32 s49, s45, 2
	s_add_u32 s48, s48, s49
	s_add_u32 s36, s36, s48
	s_addc_u32 s37, s37, 0
	s_add_u32 s38, s38, s48
	s_addc_u32 s39, s39, 0
	s_lshr_b32 s48, s48, 1
	s_add_u32 s50, s50, s48
	s_addc_u32 s51, s51, 0
	s_lshl_b32 s48, s46, 6
	s_lshl_b32 s49, s47, 2
	s_add_u32 s48, s48, s49
	s_add_u32 s34, s34, s48
	s_addc_u32 s35, s35, 0
	v_and_b32_e32 v249, 63, v204
	v_and_b32_e32 v198, 31, v249
	v_lshrrev_b32_e32 v199, 5, v249
	v_and_b32_e32 v208, 15, v249
	v_lshrrev_b32_e32 v209, 4, v249
	s_lshl_b32 s40, s40, 14
	v_and_b32_e32 v238, 15, v198
	v_xor_b32_e32 v238, v238, v199
	v_lshl_add_u32 v239, v198, 8, s40
	v_xor_b32_e32 v228, 0, v238
	v_lshl_add_u32 v228, v228, 4, v239
	v_xor_b32_e32 v229, 2, v238
	v_lshl_add_u32 v229, v229, 4, v239
	v_xor_b32_e32 v230, 4, v238
	v_lshl_add_u32 v230, v230, 4, v239
	v_xor_b32_e32 v231, 6, v238
	v_lshl_add_u32 v231, v231, 4, v239
	v_xor_b32_e32 v232, 8, v238
	v_lshl_add_u32 v232, v232, 4, v239
	v_xor_b32_e32 v233, 10, v238
	v_lshl_add_u32 v233, v233, 4, v239
	v_xor_b32_e32 v234, 12, v238
	v_lshl_add_u32 v234, v234, 4, v239
	v_xor_b32_e32 v235, 14, v238
	v_lshl_add_u32 v235, v235, 4, v239
	v_lshl_add_u32 v239, v209, 8, s40
	v_add_u32_e32 v210, 0, v209
	v_xor_b32_e32 v210, v210, v208
	v_lshl_add_u32 v210, v210, 4, v239
	v_add_u32_e32 v211, 4, v209
	v_xor_b32_e32 v211, v211, v208
	v_lshl_add_u32 v211, v211, 4, v239
	v_add_u32_e32 v215, 8, v209
	v_xor_b32_e32 v215, v215, v208
	v_lshl_add_u32 v215, v215, 4, v239
	v_add_u32_e32 v237, 12, v209
	v_xor_b32_e32 v237, v237, v208
	v_lshl_add_u32 v237, v237, 4, v239
	v_lshlrev_b32_e32 v247, 12, v209
	v_lshl_add_u32 v247, v208, 4, v247
	v_lshrrev_b32_e32 v248, 1, v247
	v_lshlrev_b32_e32 v249, 6, v209
	s_mov_b32 s48, 0x00010001
	s_mov_b32 s49, 0x00010001
	global_load_dwordx4 v[130:133], v247, s[36:37]
	s_add_u32 s36, s36, 0x4000
	s_addc_u32 s37, s37, 0
	global_load_dwordx4 v[134:137], v247, s[36:37]
	s_add_u32 s36, s36, 0x4000
	s_addc_u32 s37, s37, 0
	global_load_dwordx4 v[138:141], v247, s[36:37]
	s_add_u32 s36, s36, 0x4000
	s_addc_u32 s37, s37, 0
	global_load_dwordx4 v[142:145], v247, s[36:37]
	s_add_u32 s36, s36, 0x4000
	s_addc_u32 s37, s37, 0
	global_load_dwordx4 v[146:149], v247, s[36:37]
	s_add_u32 s36, s36, 0x4000
	s_addc_u32 s37, s37, 0
	global_load_dwordx4 v[150:153], v247, s[36:37]
	s_add_u32 s36, s36, 0x4000
	s_addc_u32 s37, s37, 0
	global_load_dwordx4 v[154:157], v247, s[36:37]
	s_add_u32 s36, s36, 0x4000
	s_addc_u32 s37, s37, 0
	global_load_dwordx4 v[158:161], v247, s[36:37]
	s_add_u32 s36, s36, 0x4000
	s_addc_u32 s37, s37, 0
	global_load_dwordx4 v[162:165], v247, s[36:37]
	s_add_u32 s36, s36, 0x4000
	s_addc_u32 s37, s37, 0
	global_load_dwordx4 v[166:169], v247, s[36:37]
	s_add_u32 s36, s36, 0x4000
	s_addc_u32 s37, s37, 0
	global_load_dwordx4 v[170:173], v247, s[36:37]
	s_add_u32 s36, s36, 0x4000
	s_addc_u32 s37, s37, 0
	global_load_dwordx4 v[174:177], v247, s[36:37]
	s_add_u32 s36, s36, 0x4000
	s_addc_u32 s37, s37, 0
	global_load_dwordx4 v[200:203], v247, s[36:37]
	s_add_u32 s36, s36, 0x4000
	s_addc_u32 s37, s37, 0
	global_load_dwordx4 v[216:219], v247, s[36:37]
	s_add_u32 s36, s36, 0x4000
	s_addc_u32 s37, s37, 0
	global_load_dwordx4 v[220:223], v247, s[36:37]
	s_add_u32 s36, s36, 0x4000
	s_addc_u32 s37, s37, 0
	global_load_dwordx4 v[224:227], v247, s[36:37]
	s_add_u32 s36, s36, 0x4000
	s_addc_u32 s37, s37, 0
	ds_write_b128 v228, v[82:85]
	ds_write_b128 v229, v[86:89]
	ds_write_b128 v230, v[90:93]
	ds_write_b128 v231, v[94:97]
	ds_write_b128 v232, v[114:117]
	ds_write_b128 v233, v[118:121]
	ds_write_b128 v234, v[122:125]
	ds_write_b128 v235, v[126:129]
	ds_write_b128 v228, v[66:69] offset:8192
	ds_write_b128 v229, v[70:73] offset:8192
	ds_write_b128 v230, v[74:77] offset:8192
	ds_write_b128 v231, v[78:81] offset:8192
	ds_write_b128 v232, v[98:101] offset:8192
	ds_write_b128 v233, v[102:105] offset:8192
	ds_write_b128 v234, v[106:109] offset:8192
	ds_write_b128 v235, v[110:113] offset:8192
	global_load_dwordx4 v[82:85], v247, s[36:37]
	s_add_u32 s36, s36, 0x4000
	s_addc_u32 s37, s37, 0
	global_load_dwordx4 v[86:89], v247, s[36:37]
	s_add_u32 s36, s36, 0x4000
	s_addc_u32 s37, s37, 0
	global_load_dwordx4 v[90:93], v247, s[36:37]
	s_add_u32 s36, s36, 0x4000
	s_addc_u32 s37, s37, 0
	global_load_dwordx4 v[94:97], v247, s[36:37]
	s_add_u32 s36, s36, 0x4000
	s_addc_u32 s37, s37, 0
	global_load_dwordx4 v[114:117], v247, s[36:37]
	s_add_u32 s36, s36, 0x4000
	s_addc_u32 s37, s37, 0
	global_load_dwordx4 v[118:121], v247, s[36:37]
	s_add_u32 s36, s36, 0x4000
	s_addc_u32 s37, s37, 0
	global_load_dwordx4 v[122:125], v247, s[36:37]
	s_add_u32 s36, s36, 0x4000
	s_addc_u32 s37, s37, 0
	global_load_dwordx4 v[126:129], v247, s[36:37]
	s_add_u32 s36, s36, 0x4000
	s_addc_u32 s37, s37, 0
	global_load_dwordx4 v[66:69], v247, s[36:37]
	s_add_u32 s36, s36, 0x4000
	s_addc_u32 s37, s37, 0
	global_load_dwordx4 v[70:73], v247, s[36:37]
	s_add_u32 s36, s36, 0x4000
	s_addc_u32 s37, s37, 0
	global_load_dwordx4 v[74:77], v247, s[36:37]
	s_add_u32 s36, s36, 0x4000
	s_addc_u32 s37, s37, 0
	global_load_dwordx4 v[78:81], v247, s[36:37]
	s_add_u32 s36, s36, 0x4000
	s_addc_u32 s37, s37, 0
	global_load_dwordx4 v[98:101], v247, s[36:37]
	s_add_u32 s36, s36, 0x4000
	s_addc_u32 s37, s37, 0
	global_load_dwordx4 v[102:105], v247, s[36:37]
	s_add_u32 s36, s36, 0x4000
	s_addc_u32 s37, s37, 0
	global_load_dwordx4 v[106:109], v247, s[36:37]
	s_add_u32 s36, s36, 0x4000
	s_addc_u32 s37, s37, 0
	global_load_dwordx4 v[110:113], v247, s[36:37]
	s_add_u32 s36, s36, 0x4000
	s_addc_u32 s37, s37, 0
	s_waitcnt lgkmcnt(0)
	ds_read_b128 v[228:231], v210 offset:0
	ds_read_b128 v[238:241], v211 offset:1024
	s_waitcnt vmcnt(31) lgkmcnt(1)
	v_pk_add_f32 v[130:131], v[228:229], v[130:131]
	v_pk_add_f32 v[132:133], v[230:231], v[132:133]
	v_pk_mul_f32 v[232:233], v[130:131], v[130:131]
	v_pk_mul_f32 v[234:235], v[132:133], v[132:133]
	ds_read_b128 v[228:231], v215 offset:2048
	v_add_f32_e32 v236, v232, v233
	v_add_f32_e32 v236, v234, v236
	v_add_f32_e32 v236, v235, v236
	global_store_dwordx4 v247, v[130:133], s[38:39] nt
	v_cvt_pk_bf16_f32 v232, v130, v131
	v_cvt_pk_bf16_f32 v233, v132, v133
	v_add_f32_dpp v236, v236, v236 quad_perm:[1,0,3,2] row_mask:0xf bank_mask:0xf
	global_store_dwordx2 v248, v[232:233], s[50:51] nt
	s_add_u32 s38, s38, 0x4000
	s_addc_u32 s39, s39, 0
	v_add_f32_dpp v236, v236, v236 quad_perm:[2,3,0,1] row_mask:0xf bank_mask:0xf
	s_add_u32 s50, s50, 0x2000
	s_addc_u32 s51, s51, 0
	v_add_f32_dpp v236, v236, v236 row_half_mirror row_mask:0xf bank_mask:0xf
	s_nop 1
	v_add_f32_dpp v236, v236, v236 row_mirror row_mask:0xf bank_mask:0xf
	s_mov_b64 exec, s[48:49]
	global_store_dword v249, v236, s[34:35] offset:0
	s_mov_b64 exec, -1
	s_waitcnt vmcnt(33) lgkmcnt(1)
	v_pk_add_f32 v[134:135], v[238:239], v[134:135]
	v_pk_add_f32 v[136:137], v[240:241], v[136:137]
	v_pk_mul_f32 v[242:243], v[134:135], v[134:135]
	v_pk_mul_f32 v[244:245], v[136:137], v[136:137]
	ds_read_b128 v[238:241], v237 offset:3072
	v_add_f32_e32 v246, v242, v243
	v_add_f32_e32 v246, v244, v246
	v_add_f32_e32 v246, v245, v246
	global_store_dwordx4 v247, v[134:137], s[38:39] nt
	v_cvt_pk_bf16_f32 v242, v134, v135
	v_cvt_pk_bf16_f32 v243, v136, v137
	v_add_f32_dpp v246, v246, v246 quad_perm:[1,0,3,2] row_mask:0xf bank_mask:0xf
	global_store_dwordx2 v248, v[242:243], s[50:51] nt
	s_add_u32 s38, s38, 0x4000
	s_addc_u32 s39, s39, 0
	v_add_f32_dpp v246, v246, v246 quad_perm:[2,3,0,1] row_mask:0xf bank_mask:0xf
	s_add_u32 s50, s50, 0x2000
	s_addc_u32 s51, s51, 0
	v_add_f32_dpp v246, v246, v246 row_half_mirror row_mask:0xf bank_mask:0xf
	s_nop 1
	v_add_f32_dpp v246, v246, v246 row_mirror row_mask:0xf bank_mask:0xf
	s_mov_b64 exec, s[48:49]
	global_store_dword v249, v246, s[34:35] offset:256
	s_mov_b64 exec, -1
	s_waitcnt vmcnt(35) lgkmcnt(1)
	v_pk_add_f32 v[138:139], v[228:229], v[138:139]
	v_pk_add_f32 v[140:141], v[230:231], v[140:141]
	v_pk_mul_f32 v[232:233], v[138:139], v[138:139]
	v_pk_mul_f32 v[234:235], v[140:141], v[140:141]
	ds_read_b128 v[228:231], v210 offset:4096
	v_add_f32_e32 v236, v232, v233
	v_add_f32_e32 v236, v234, v236
	v_add_f32_e32 v236, v235, v236
	global_store_dwordx4 v247, v[138:141], s[38:39] nt
	v_cvt_pk_bf16_f32 v232, v138, v139
	v_cvt_pk_bf16_f32 v233, v140, v141
	v_add_f32_dpp v236, v236, v236 quad_perm:[1,0,3,2] row_mask:0xf bank_mask:0xf
	global_store_dwordx2 v248, v[232:233], s[50:51] nt
	s_add_u32 s38, s38, 0x4000
	s_addc_u32 s39, s39, 0
	v_add_f32_dpp v236, v236, v236 quad_perm:[2,3,0,1] row_mask:0xf bank_mask:0xf
	s_add_u32 s50, s50, 0x2000
	s_addc_u32 s51, s51, 0
	v_add_f32_dpp v236, v236, v236 row_half_mirror row_mask:0xf bank_mask:0xf
	s_nop 1
	v_add_f32_dpp v236, v236, v236 row_mirror row_mask:0xf bank_mask:0xf
	s_mov_b64 exec, s[48:49]
	global_store_dword v249, v236, s[34:35] offset:512
	s_mov_b64 exec, -1
	s_waitcnt vmcnt(37) lgkmcnt(1)
	v_pk_add_f32 v[142:143], v[238:239], v[142:143]
	v_pk_add_f32 v[144:145], v[240:241], v[144:145]
	v_pk_mul_f32 v[242:243], v[142:143], v[142:143]
	v_pk_mul_f32 v[244:245], v[144:145], v[144:145]
	ds_read_b128 v[238:241], v211 offset:5120
	v_add_f32_e32 v246, v242, v243
	v_add_f32_e32 v246, v244, v246
	v_add_f32_e32 v246, v245, v246
	global_store_dwordx4 v247, v[142:145], s[38:39] nt
	v_cvt_pk_bf16_f32 v242, v142, v143
	v_cvt_pk_bf16_f32 v243, v144, v145
	v_add_f32_dpp v246, v246, v246 quad_perm:[1,0,3,2] row_mask:0xf bank_mask:0xf
	global_store_dwordx2 v248, v[242:243], s[50:51] nt
	s_add_u32 s38, s38, 0x4000
	s_addc_u32 s39, s39, 0
	v_add_f32_dpp v246, v246, v246 quad_perm:[2,3,0,1] row_mask:0xf bank_mask:0xf
	s_add_u32 s50, s50, 0x2000
	s_addc_u32 s51, s51, 0
	v_add_f32_dpp v246, v246, v246 row_half_mirror row_mask:0xf bank_mask:0xf
	s_nop 1
	v_add_f32_dpp v246, v246, v246 row_mirror row_mask:0xf bank_mask:0xf
	s_mov_b64 exec, s[48:49]
	global_store_dword v249, v246, s[34:35] offset:768
	s_mov_b64 exec, -1
	s_waitcnt vmcnt(39) lgkmcnt(1)
	v_pk_add_f32 v[146:147], v[228:229], v[146:147]
	v_pk_add_f32 v[148:149], v[230:231], v[148:149]
	v_pk_mul_f32 v[232:233], v[146:147], v[146:147]
	v_pk_mul_f32 v[234:235], v[148:149], v[148:149]
	ds_read_b128 v[228:231], v215 offset:6144
	v_add_f32_e32 v236, v232, v233
	v_add_f32_e32 v236, v234, v236
	v_add_f32_e32 v236, v235, v236
	global_store_dwordx4 v247, v[146:149], s[38:39] nt
	v_cvt_pk_bf16_f32 v232, v146, v147
	v_cvt_pk_bf16_f32 v233, v148, v149
	v_add_f32_dpp v236, v236, v236 quad_perm:[1,0,3,2] row_mask:0xf bank_mask:0xf
	global_store_dwordx2 v248, v[232:233], s[50:51] nt
	s_add_u32 s38, s38, 0x4000
	s_addc_u32 s39, s39, 0
	v_add_f32_dpp v236, v236, v236 quad_perm:[2,3,0,1] row_mask:0xf bank_mask:0xf
	s_add_u32 s50, s50, 0x2000
	s_addc_u32 s51, s51, 0
	v_add_f32_dpp v236, v236, v236 row_half_mirror row_mask:0xf bank_mask:0xf
	s_nop 1
	v_add_f32_dpp v236, v236, v236 row_mirror row_mask:0xf bank_mask:0xf
	s_mov_b64 exec, s[48:49]
	global_store_dword v249, v236, s[34:35] offset:1024
	s_mov_b64 exec, -1
	s_waitcnt vmcnt(41) lgkmcnt(1)
	v_pk_add_f32 v[150:151], v[238:239], v[150:151]
	v_pk_add_f32 v[152:153], v[240:241], v[152:153]
	v_pk_mul_f32 v[242:243], v[150:151], v[150:151]
	v_pk_mul_f32 v[244:245], v[152:153], v[152:153]
	ds_read_b128 v[238:241], v237 offset:7168
	v_add_f32_e32 v246, v242, v243
	v_add_f32_e32 v246, v244, v246
	v_add_f32_e32 v246, v245, v246
	global_store_dwordx4 v247, v[150:153], s[38:39] nt
	v_cvt_pk_bf16_f32 v242, v150, v151
	v_cvt_pk_bf16_f32 v243, v152, v153
	v_add_f32_dpp v246, v246, v246 quad_perm:[1,0,3,2] row_mask:0xf bank_mask:0xf
	global_store_dwordx2 v248, v[242:243], s[50:51] nt
	s_add_u32 s38, s38, 0x4000
	s_addc_u32 s39, s39, 0
	v_add_f32_dpp v246, v246, v246 quad_perm:[2,3,0,1] row_mask:0xf bank_mask:0xf
	s_add_u32 s50, s50, 0x2000
	s_addc_u32 s51, s51, 0
	v_add_f32_dpp v246, v246, v246 row_half_mirror row_mask:0xf bank_mask:0xf
	s_nop 1
	v_add_f32_dpp v246, v246, v246 row_mirror row_mask:0xf bank_mask:0xf
	s_mov_b64 exec, s[48:49]
	global_store_dword v249, v246, s[34:35] offset:1280
	s_mov_b64 exec, -1
	s_waitcnt vmcnt(43) lgkmcnt(1)
	v_pk_add_f32 v[154:155], v[228:229], v[154:155]
	v_pk_add_f32 v[156:157], v[230:231], v[156:157]
	v_pk_mul_f32 v[232:233], v[154:155], v[154:155]
	v_pk_mul_f32 v[234:235], v[156:157], v[156:157]
	ds_read_b128 v[228:231], v210 offset:8192
	v_add_f32_e32 v236, v232, v233
	v_add_f32_e32 v236, v234, v236
	v_add_f32_e32 v236, v235, v236
	global_store_dwordx4 v247, v[154:157], s[38:39] nt
	v_cvt_pk_bf16_f32 v232, v154, v155
	v_cvt_pk_bf16_f32 v233, v156, v157
	v_add_f32_dpp v236, v236, v236 quad_perm:[1,0,3,2] row_mask:0xf bank_mask:0xf
	global_store_dwordx2 v248, v[232:233], s[50:51] nt
	s_add_u32 s38, s38, 0x4000
	s_addc_u32 s39, s39, 0
	v_add_f32_dpp v236, v236, v236 quad_perm:[2,3,0,1] row_mask:0xf bank_mask:0xf
	s_add_u32 s50, s50, 0x2000
	s_addc_u32 s51, s51, 0
	v_add_f32_dpp v236, v236, v236 row_half_mirror row_mask:0xf bank_mask:0xf
	s_nop 1
	v_add_f32_dpp v236, v236, v236 row_mirror row_mask:0xf bank_mask:0xf
	s_mov_b64 exec, s[48:49]
	global_store_dword v249, v236, s[34:35] offset:1536
	s_mov_b64 exec, -1
	s_waitcnt vmcnt(45) lgkmcnt(1)
	v_pk_add_f32 v[158:159], v[238:239], v[158:159]
	v_pk_add_f32 v[160:161], v[240:241], v[160:161]
	v_pk_mul_f32 v[242:243], v[158:159], v[158:159]
	v_pk_mul_f32 v[244:245], v[160:161], v[160:161]
	ds_read_b128 v[238:241], v211 offset:9216
	v_add_f32_e32 v246, v242, v243
	v_add_f32_e32 v246, v244, v246
	v_add_f32_e32 v246, v245, v246
	global_store_dwordx4 v247, v[158:161], s[38:39] nt
	v_cvt_pk_bf16_f32 v242, v158, v159
	v_cvt_pk_bf16_f32 v243, v160, v161
	v_add_f32_dpp v246, v246, v246 quad_perm:[1,0,3,2] row_mask:0xf bank_mask:0xf
	global_store_dwordx2 v248, v[242:243], s[50:51] nt
	s_add_u32 s38, s38, 0x4000
	s_addc_u32 s39, s39, 0
	v_add_f32_dpp v246, v246, v246 quad_perm:[2,3,0,1] row_mask:0xf bank_mask:0xf
	s_add_u32 s50, s50, 0x2000
	s_addc_u32 s51, s51, 0
	v_add_f32_dpp v246, v246, v246 row_half_mirror row_mask:0xf bank_mask:0xf
	s_nop 1
	v_add_f32_dpp v246, v246, v246 row_mirror row_mask:0xf bank_mask:0xf
	s_mov_b64 exec, s[48:49]
	global_store_dword v249, v246, s[34:35] offset:1792
	s_mov_b64 exec, -1
	s_waitcnt vmcnt(47) lgkmcnt(1)
	v_pk_add_f32 v[162:163], v[228:229], v[162:163]
	v_pk_add_f32 v[164:165], v[230:231], v[164:165]
	v_pk_mul_f32 v[232:233], v[162:163], v[162:163]
	v_pk_mul_f32 v[234:235], v[164:165], v[164:165]
	ds_read_b128 v[228:231], v215 offset:10240
	v_add_f32_e32 v236, v232, v233
	v_add_f32_e32 v236, v234, v236
	v_add_f32_e32 v236, v235, v236
	global_store_dwordx4 v247, v[162:165], s[38:39] nt
	v_cvt_pk_bf16_f32 v232, v162, v163
	v_cvt_pk_bf16_f32 v233, v164, v165
	v_add_f32_dpp v236, v236, v236 quad_perm:[1,0,3,2] row_mask:0xf bank_mask:0xf
	global_store_dwordx2 v248, v[232:233], s[50:51] nt
	s_add_u32 s38, s38, 0x4000
	s_addc_u32 s39, s39, 0
	v_add_f32_dpp v236, v236, v236 quad_perm:[2,3,0,1] row_mask:0xf bank_mask:0xf
	s_add_u32 s50, s50, 0x2000
	s_addc_u32 s51, s51, 0
	v_add_f32_dpp v236, v236, v236 row_half_mirror row_mask:0xf bank_mask:0xf
	s_nop 1
	v_add_f32_dpp v236, v236, v236 row_mirror row_mask:0xf bank_mask:0xf
	s_mov_b64 exec, s[48:49]
	global_store_dword v249, v236, s[34:35] offset:2048
	s_mov_b64 exec, -1
	s_waitcnt vmcnt(49) lgkmcnt(1)
	v_pk_add_f32 v[166:167], v[238:239], v[166:167]
	v_pk_add_f32 v[168:169], v[240:241], v[168:169]
	v_pk_mul_f32 v[242:243], v[166:167], v[166:167]
	v_pk_mul_f32 v[244:245], v[168:169], v[168:169]
	ds_read_b128 v[238:241], v237 offset:11264
	v_add_f32_e32 v246, v242, v243
	v_add_f32_e32 v246, v244, v246
	v_add_f32_e32 v246, v245, v246
	global_store_dwordx4 v247, v[166:169], s[38:39] nt
	v_cvt_pk_bf16_f32 v242, v166, v167
	v_cvt_pk_bf16_f32 v243, v168, v169
	v_add_f32_dpp v246, v246, v246 quad_perm:[1,0,3,2] row_mask:0xf bank_mask:0xf
	global_store_dwordx2 v248, v[242:243], s[50:51] nt
	s_add_u32 s38, s38, 0x4000
	s_addc_u32 s39, s39, 0
	v_add_f32_dpp v246, v246, v246 quad_perm:[2,3,0,1] row_mask:0xf bank_mask:0xf
	s_add_u32 s50, s50, 0x2000
	s_addc_u32 s51, s51, 0
	v_add_f32_dpp v246, v246, v246 row_half_mirror row_mask:0xf bank_mask:0xf
	s_nop 1
	v_add_f32_dpp v246, v246, v246 row_mirror row_mask:0xf bank_mask:0xf
	s_mov_b64 exec, s[48:49]
	global_store_dword v249, v246, s[34:35] offset:2304
	s_mov_b64 exec, -1
	s_waitcnt vmcnt(51) lgkmcnt(1)
	v_pk_add_f32 v[170:171], v[228:229], v[170:171]
	v_pk_add_f32 v[172:173], v[230:231], v[172:173]
	v_pk_mul_f32 v[232:233], v[170:171], v[170:171]
	v_pk_mul_f32 v[234:235], v[172:173], v[172:173]
	ds_read_b128 v[228:231], v210 offset:12288
	v_add_f32_e32 v236, v232, v233
	v_add_f32_e32 v236, v234, v236
	v_add_f32_e32 v236, v235, v236
	global_store_dwordx4 v247, v[170:173], s[38:39] nt
	v_cvt_pk_bf16_f32 v232, v170, v171
	v_cvt_pk_bf16_f32 v233, v172, v173
	v_add_f32_dpp v236, v236, v236 quad_perm:[1,0,3,2] row_mask:0xf bank_mask:0xf
	global_store_dwordx2 v248, v[232:233], s[50:51] nt
	s_add_u32 s38, s38, 0x4000
	s_addc_u32 s39, s39, 0
	v_add_f32_dpp v236, v236, v236 quad_perm:[2,3,0,1] row_mask:0xf bank_mask:0xf
	s_add_u32 s50, s50, 0x2000
	s_addc_u32 s51, s51, 0
	v_add_f32_dpp v236, v236, v236 row_half_mirror row_mask:0xf bank_mask:0xf
	s_nop 1
	v_add_f32_dpp v236, v236, v236 row_mirror row_mask:0xf bank_mask:0xf
	s_mov_b64 exec, s[48:49]
	global_store_dword v249, v236, s[34:35] offset:2560
	s_mov_b64 exec, -1
	s_waitcnt vmcnt(53) lgkmcnt(1)
	v_pk_add_f32 v[174:175], v[238:239], v[174:175]
	v_pk_add_f32 v[176:177], v[240:241], v[176:177]
	v_pk_mul_f32 v[242:243], v[174:175], v[174:175]
	v_pk_mul_f32 v[244:245], v[176:177], v[176:177]
	ds_read_b128 v[238:241], v211 offset:13312
	v_add_f32_e32 v246, v242, v243
	v_add_f32_e32 v246, v244, v246
	v_add_f32_e32 v246, v245, v246
	global_store_dwordx4 v247, v[174:177], s[38:39] nt
	v_cvt_pk_bf16_f32 v242, v174, v175
	v_cvt_pk_bf16_f32 v243, v176, v177
	v_add_f32_dpp v246, v246, v246 quad_perm:[1,0,3,2] row_mask:0xf bank_mask:0xf
	global_store_dwordx2 v248, v[242:243], s[50:51] nt
	s_add_u32 s38, s38, 0x4000
	s_addc_u32 s39, s39, 0
	v_add_f32_dpp v246, v246, v246 quad_perm:[2,3,0,1] row_mask:0xf bank_mask:0xf
	s_add_u32 s50, s50, 0x2000
	s_addc_u32 s51, s51, 0
	v_add_f32_dpp v246, v246, v246 row_half_mirror row_mask:0xf bank_mask:0xf
	s_nop 1
	v_add_f32_dpp v246, v246, v246 row_mirror row_mask:0xf bank_mask:0xf
	s_mov_b64 exec, s[48:49]
	global_store_dword v249, v246, s[34:35] offset:2816
	s_mov_b64 exec, -1
	s_waitcnt vmcnt(55) lgkmcnt(1)
	v_pk_add_f32 v[200:201], v[228:229], v[200:201]
	v_pk_add_f32 v[202:203], v[230:231], v[202:203]
	v_pk_mul_f32 v[232:233], v[200:201], v[200:201]
	v_pk_mul_f32 v[234:235], v[202:203], v[202:203]
	ds_read_b128 v[228:231], v215 offset:14336
	v_add_f32_e32 v236, v232, v233
	v_add_f32_e32 v236, v234, v236
	v_add_f32_e32 v236, v235, v236
	global_store_dwordx4 v247, v[200:203], s[38:39] nt
	v_cvt_pk_bf16_f32 v232, v200, v201
	v_cvt_pk_bf16_f32 v233, v202, v203
	v_add_f32_dpp v236, v236, v236 quad_perm:[1,0,3,2] row_mask:0xf bank_mask:0xf
	global_store_dwordx2 v248, v[232:233], s[50:51] nt
	s_add_u32 s38, s38, 0x4000
	s_addc_u32 s39, s39, 0
	v_add_f32_dpp v236, v236, v236 quad_perm:[2,3,0,1] row_mask:0xf bank_mask:0xf
	s_add_u32 s50, s50, 0x2000
	s_addc_u32 s51, s51, 0
	v_add_f32_dpp v236, v236, v236 row_half_mirror row_mask:0xf bank_mask:0xf
	s_nop 1
	v_add_f32_dpp v236, v236, v236 row_mirror row_mask:0xf bank_mask:0xf
	s_mov_b64 exec, s[48:49]
	global_store_dword v249, v236, s[34:35] offset:3072
	s_mov_b64 exec, -1
	s_waitcnt vmcnt(57) lgkmcnt(1)
	v_pk_add_f32 v[216:217], v[238:239], v[216:217]
	v_pk_add_f32 v[218:219], v[240:241], v[218:219]
	v_pk_mul_f32 v[242:243], v[216:217], v[216:217]
	v_pk_mul_f32 v[244:245], v[218:219], v[218:219]
	ds_read_b128 v[238:241], v237 offset:15360
	v_add_f32_e32 v246, v242, v243
	v_add_f32_e32 v246, v244, v246
	v_add_f32_e32 v246, v245, v246
	global_store_dwordx4 v247, v[216:219], s[38:39] nt
	v_cvt_pk_bf16_f32 v242, v216, v217
	v_cvt_pk_bf16_f32 v243, v218, v219
	v_add_f32_dpp v246, v246, v246 quad_perm:[1,0,3,2] row_mask:0xf bank_mask:0xf
	global_store_dwordx2 v248, v[242:243], s[50:51] nt
	s_add_u32 s38, s38, 0x4000
	s_addc_u32 s39, s39, 0
	v_add_f32_dpp v246, v246, v246 quad_perm:[2,3,0,1] row_mask:0xf bank_mask:0xf
	s_add_u32 s50, s50, 0x2000
	s_addc_u32 s51, s51, 0
	v_add_f32_dpp v246, v246, v246 row_half_mirror row_mask:0xf bank_mask:0xf
	s_nop 1
	v_add_f32_dpp v246, v246, v246 row_mirror row_mask:0xf bank_mask:0xf
	s_mov_b64 exec, s[48:49]
	global_store_dword v249, v246, s[34:35] offset:3328
	s_mov_b64 exec, -1
	s_waitcnt vmcnt(59) lgkmcnt(1)
	v_pk_add_f32 v[220:221], v[228:229], v[220:221]
	v_pk_add_f32 v[222:223], v[230:231], v[222:223]
	v_pk_mul_f32 v[232:233], v[220:221], v[220:221]
	v_pk_mul_f32 v[234:235], v[222:223], v[222:223]
	v_add_f32_e32 v236, v232, v233
	v_add_f32_e32 v236, v234, v236
	v_add_f32_e32 v236, v235, v236
	global_store_dwordx4 v247, v[220:223], s[38:39] nt
	v_cvt_pk_bf16_f32 v232, v220, v221
	v_cvt_pk_bf16_f32 v233, v222, v223
	v_add_f32_dpp v236, v236, v236 quad_perm:[1,0,3,2] row_mask:0xf bank_mask:0xf
	global_store_dwordx2 v248, v[232:233], s[50:51] nt
	s_add_u32 s38, s38, 0x4000
	s_addc_u32 s39, s39, 0
	v_add_f32_dpp v236, v236, v236 quad_perm:[2,3,0,1] row_mask:0xf bank_mask:0xf
	s_add_u32 s50, s50, 0x2000
	s_addc_u32 s51, s51, 0
	v_add_f32_dpp v236, v236, v236 row_half_mirror row_mask:0xf bank_mask:0xf
	s_nop 1
	v_add_f32_dpp v236, v236, v236 row_mirror row_mask:0xf bank_mask:0xf
	s_mov_b64 exec, s[48:49]
	global_store_dword v249, v236, s[34:35] offset:3584
	s_mov_b64 exec, -1
	s_waitcnt vmcnt(61) lgkmcnt(0)
	v_pk_add_f32 v[224:225], v[238:239], v[224:225]
	v_pk_add_f32 v[226:227], v[240:241], v[226:227]
	v_pk_mul_f32 v[242:243], v[224:225], v[224:225]
	v_pk_mul_f32 v[244:245], v[226:227], v[226:227]
	v_add_f32_e32 v246, v242, v243
	v_add_f32_e32 v246, v244, v246
	v_add_f32_e32 v246, v245, v246
	global_store_dwordx4 v247, v[224:227], s[38:39] nt
	v_cvt_pk_bf16_f32 v242, v224, v225
	v_cvt_pk_bf16_f32 v243, v226, v227
	v_add_f32_dpp v246, v246, v246 quad_perm:[1,0,3,2] row_mask:0xf bank_mask:0xf
	global_store_dwordx2 v248, v[242:243], s[50:51] nt
	s_add_u32 s38, s38, 0x4000
	s_addc_u32 s39, s39, 0
	v_add_f32_dpp v246, v246, v246 quad_perm:[2,3,0,1] row_mask:0xf bank_mask:0xf
	s_add_u32 s50, s50, 0x2000
	s_addc_u32 s51, s51, 0
	v_add_f32_dpp v246, v246, v246 row_half_mirror row_mask:0xf bank_mask:0xf
	s_nop 1
	v_add_f32_dpp v246, v246, v246 row_mirror row_mask:0xf bank_mask:0xf
	s_mov_b64 exec, s[48:49]
	global_store_dword v249, v246, s[34:35] offset:3840
	s_mov_b64 exec, -1
	s_add_u32 s34, s34, 0x1000
	s_addc_u32 s35, s35, 0
	v_and_b32_e32 v238, 15, v198
	v_xor_b32_e32 v238, v238, v199
	v_lshl_add_u32 v239, v198, 8, s40
	v_xor_b32_e32 v228, 0, v238
	v_lshl_add_u32 v228, v228, 4, v239
	v_xor_b32_e32 v229, 2, v238
	v_lshl_add_u32 v229, v229, 4, v239
	v_xor_b32_e32 v230, 4, v238
	v_lshl_add_u32 v230, v230, 4, v239
	v_xor_b32_e32 v231, 6, v238
	v_lshl_add_u32 v231, v231, 4, v239
	v_xor_b32_e32 v232, 8, v238
	v_lshl_add_u32 v232, v232, 4, v239
	v_xor_b32_e32 v233, 10, v238
	v_lshl_add_u32 v233, v233, 4, v239
	v_xor_b32_e32 v234, 12, v238
	v_lshl_add_u32 v234, v234, 4, v239
	v_xor_b32_e32 v235, 14, v238
	v_lshl_add_u32 v235, v235, 4, v239
	ds_write_b128 v228, v[18:21]
	ds_write_b128 v229, v[22:25]
	ds_write_b128 v230, v[26:29]
	ds_write_b128 v231, v[30:33]
	ds_write_b128 v232, v[50:53]
	ds_write_b128 v233, v[54:57]
	ds_write_b128 v234, v[58:61]
	ds_write_b128 v235, v[62:65]
	ds_write_b128 v228, v[2:5] offset:8192
	ds_write_b128 v229, v[6:9] offset:8192
	ds_write_b128 v230, v[10:13] offset:8192
	ds_write_b128 v231, v[14:17] offset:8192
	ds_write_b128 v232, v[34:37] offset:8192
	ds_write_b128 v233, v[38:41] offset:8192
	ds_write_b128 v234, v[42:45] offset:8192
	ds_write_b128 v235, v[46:49] offset:8192
	s_waitcnt lgkmcnt(0)
	ds_read_b128 v[228:231], v210 offset:0
	ds_read_b128 v[238:241], v211 offset:1024
	s_waitcnt vmcnt(63) lgkmcnt(1)
	v_pk_add_f32 v[82:83], v[228:229], v[82:83]
	v_pk_add_f32 v[84:85], v[230:231], v[84:85]
	v_pk_mul_f32 v[232:233], v[82:83], v[82:83]
	v_pk_mul_f32 v[234:235], v[84:85], v[84:85]
	ds_read_b128 v[228:231], v215 offset:2048
	v_add_f32_e32 v236, v232, v233
	v_add_f32_e32 v236, v234, v236
	v_add_f32_e32 v236, v235, v236
	global_store_dwordx4 v247, v[82:85], s[38:39] nt
	v_cvt_pk_bf16_f32 v232, v82, v83
	v_cvt_pk_bf16_f32 v233, v84, v85
	v_add_f32_dpp v236, v236, v236 quad_perm:[1,0,3,2] row_mask:0xf bank_mask:0xf
	global_store_dwordx2 v248, v[232:233], s[50:51] nt
	s_add_u32 s38, s38, 0x4000
	s_addc_u32 s39, s39, 0
	v_add_f32_dpp v236, v236, v236 quad_perm:[2,3,0,1] row_mask:0xf bank_mask:0xf
	s_add_u32 s50, s50, 0x2000
	s_addc_u32 s51, s51, 0
	v_add_f32_dpp v236, v236, v236 row_half_mirror row_mask:0xf bank_mask:0xf
	s_nop 1
	v_add_f32_dpp v236, v236, v236 row_mirror row_mask:0xf bank_mask:0xf
	s_mov_b64 exec, s[48:49]
	global_store_dword v249, v236, s[34:35] offset:0
	s_mov_b64 exec, -1
	s_waitcnt vmcnt(63) lgkmcnt(1)
	v_pk_add_f32 v[86:87], v[238:239], v[86:87]
	v_pk_add_f32 v[88:89], v[240:241], v[88:89]
	v_pk_mul_f32 v[242:243], v[86:87], v[86:87]
	v_pk_mul_f32 v[244:245], v[88:89], v[88:89]
	ds_read_b128 v[238:241], v237 offset:3072
	v_add_f32_e32 v246, v242, v243
	v_add_f32_e32 v246, v244, v246
	v_add_f32_e32 v246, v245, v246
	global_store_dwordx4 v247, v[86:89], s[38:39] nt
	v_cvt_pk_bf16_f32 v242, v86, v87
	v_cvt_pk_bf16_f32 v243, v88, v89
	v_add_f32_dpp v246, v246, v246 quad_perm:[1,0,3,2] row_mask:0xf bank_mask:0xf
	global_store_dwordx2 v248, v[242:243], s[50:51] nt
	s_add_u32 s38, s38, 0x4000
	s_addc_u32 s39, s39, 0
	v_add_f32_dpp v246, v246, v246 quad_perm:[2,3,0,1] row_mask:0xf bank_mask:0xf
	s_add_u32 s50, s50, 0x2000
	s_addc_u32 s51, s51, 0
	v_add_f32_dpp v246, v246, v246 row_half_mirror row_mask:0xf bank_mask:0xf
	s_nop 1
	v_add_f32_dpp v246, v246, v246 row_mirror row_mask:0xf bank_mask:0xf
	s_mov_b64 exec, s[48:49]
	global_store_dword v249, v246, s[34:35] offset:256
	s_mov_b64 exec, -1
	s_waitcnt vmcnt(63) lgkmcnt(1)
	v_pk_add_f32 v[90:91], v[228:229], v[90:91]
	v_pk_add_f32 v[92:93], v[230:231], v[92:93]
	v_pk_mul_f32 v[232:233], v[90:91], v[90:91]
	v_pk_mul_f32 v[234:235], v[92:93], v[92:93]
	ds_read_b128 v[228:231], v210 offset:4096
	v_add_f32_e32 v236, v232, v233
	v_add_f32_e32 v236, v234, v236
	v_add_f32_e32 v236, v235, v236
	global_store_dwordx4 v247, v[90:93], s[38:39] nt
	v_cvt_pk_bf16_f32 v232, v90, v91
	v_cvt_pk_bf16_f32 v233, v92, v93
	v_add_f32_dpp v236, v236, v236 quad_perm:[1,0,3,2] row_mask:0xf bank_mask:0xf
	global_store_dwordx2 v248, v[232:233], s[50:51] nt
	s_add_u32 s38, s38, 0x4000
	s_addc_u32 s39, s39, 0
	v_add_f32_dpp v236, v236, v236 quad_perm:[2,3,0,1] row_mask:0xf bank_mask:0xf
	s_add_u32 s50, s50, 0x2000
	s_addc_u32 s51, s51, 0
	v_add_f32_dpp v236, v236, v236 row_half_mirror row_mask:0xf bank_mask:0xf
	s_nop 1
	v_add_f32_dpp v236, v236, v236 row_mirror row_mask:0xf bank_mask:0xf
	s_mov_b64 exec, s[48:49]
	global_store_dword v249, v236, s[34:35] offset:512
	s_mov_b64 exec, -1
	s_waitcnt vmcnt(63) lgkmcnt(1)
	v_pk_add_f32 v[94:95], v[238:239], v[94:95]
	v_pk_add_f32 v[96:97], v[240:241], v[96:97]
	v_pk_mul_f32 v[242:243], v[94:95], v[94:95]
	v_pk_mul_f32 v[244:245], v[96:97], v[96:97]
	ds_read_b128 v[238:241], v211 offset:5120
	v_add_f32_e32 v246, v242, v243
	v_add_f32_e32 v246, v244, v246
	v_add_f32_e32 v246, v245, v246
	global_store_dwordx4 v247, v[94:97], s[38:39] nt
	v_cvt_pk_bf16_f32 v242, v94, v95
	v_cvt_pk_bf16_f32 v243, v96, v97
	v_add_f32_dpp v246, v246, v246 quad_perm:[1,0,3,2] row_mask:0xf bank_mask:0xf
	global_store_dwordx2 v248, v[242:243], s[50:51] nt
	s_add_u32 s38, s38, 0x4000
	s_addc_u32 s39, s39, 0
	v_add_f32_dpp v246, v246, v246 quad_perm:[2,3,0,1] row_mask:0xf bank_mask:0xf
	s_add_u32 s50, s50, 0x2000
	s_addc_u32 s51, s51, 0
	v_add_f32_dpp v246, v246, v246 row_half_mirror row_mask:0xf bank_mask:0xf
	s_nop 1
	v_add_f32_dpp v246, v246, v246 row_mirror row_mask:0xf bank_mask:0xf
	s_mov_b64 exec, s[48:49]
	global_store_dword v249, v246, s[34:35] offset:768
	s_mov_b64 exec, -1
	s_waitcnt vmcnt(63) lgkmcnt(1)
	v_pk_add_f32 v[114:115], v[228:229], v[114:115]
	v_pk_add_f32 v[116:117], v[230:231], v[116:117]
	v_pk_mul_f32 v[232:233], v[114:115], v[114:115]
	v_pk_mul_f32 v[234:235], v[116:117], v[116:117]
	ds_read_b128 v[228:231], v215 offset:6144
	v_add_f32_e32 v236, v232, v233
	v_add_f32_e32 v236, v234, v236
	v_add_f32_e32 v236, v235, v236
	global_store_dwordx4 v247, v[114:117], s[38:39] nt
	v_cvt_pk_bf16_f32 v232, v114, v115
	v_cvt_pk_bf16_f32 v233, v116, v117
	v_add_f32_dpp v236, v236, v236 quad_perm:[1,0,3,2] row_mask:0xf bank_mask:0xf
	global_store_dwordx2 v248, v[232:233], s[50:51] nt
	s_add_u32 s38, s38, 0x4000
	s_addc_u32 s39, s39, 0
	v_add_f32_dpp v236, v236, v236 quad_perm:[2,3,0,1] row_mask:0xf bank_mask:0xf
	s_add_u32 s50, s50, 0x2000
	s_addc_u32 s51, s51, 0
	v_add_f32_dpp v236, v236, v236 row_half_mirror row_mask:0xf bank_mask:0xf
	s_nop 1
	v_add_f32_dpp v236, v236, v236 row_mirror row_mask:0xf bank_mask:0xf
	s_mov_b64 exec, s[48:49]
	global_store_dword v249, v236, s[34:35] offset:1024
	s_mov_b64 exec, -1
	s_waitcnt vmcnt(63) lgkmcnt(1)
	v_pk_add_f32 v[118:119], v[238:239], v[118:119]
	v_pk_add_f32 v[120:121], v[240:241], v[120:121]
	v_pk_mul_f32 v[242:243], v[118:119], v[118:119]
	v_pk_mul_f32 v[244:245], v[120:121], v[120:121]
	ds_read_b128 v[238:241], v237 offset:7168
	v_add_f32_e32 v246, v242, v243
	v_add_f32_e32 v246, v244, v246
	v_add_f32_e32 v246, v245, v246
	global_store_dwordx4 v247, v[118:121], s[38:39] nt
	v_cvt_pk_bf16_f32 v242, v118, v119
	v_cvt_pk_bf16_f32 v243, v120, v121
	v_add_f32_dpp v246, v246, v246 quad_perm:[1,0,3,2] row_mask:0xf bank_mask:0xf
	global_store_dwordx2 v248, v[242:243], s[50:51] nt
	s_add_u32 s38, s38, 0x4000
	s_addc_u32 s39, s39, 0
	v_add_f32_dpp v246, v246, v246 quad_perm:[2,3,0,1] row_mask:0xf bank_mask:0xf
	s_add_u32 s50, s50, 0x2000
	s_addc_u32 s51, s51, 0
	v_add_f32_dpp v246, v246, v246 row_half_mirror row_mask:0xf bank_mask:0xf
	s_nop 1
	v_add_f32_dpp v246, v246, v246 row_mirror row_mask:0xf bank_mask:0xf
	s_mov_b64 exec, s[48:49]
	global_store_dword v249, v246, s[34:35] offset:1280
	s_mov_b64 exec, -1
	s_waitcnt vmcnt(63) lgkmcnt(1)
	v_pk_add_f32 v[122:123], v[228:229], v[122:123]
	v_pk_add_f32 v[124:125], v[230:231], v[124:125]
	v_pk_mul_f32 v[232:233], v[122:123], v[122:123]
	v_pk_mul_f32 v[234:235], v[124:125], v[124:125]
	ds_read_b128 v[228:231], v210 offset:8192
	v_add_f32_e32 v236, v232, v233
	v_add_f32_e32 v236, v234, v236
	v_add_f32_e32 v236, v235, v236
	global_store_dwordx4 v247, v[122:125], s[38:39] nt
	v_cvt_pk_bf16_f32 v232, v122, v123
	v_cvt_pk_bf16_f32 v233, v124, v125
	v_add_f32_dpp v236, v236, v236 quad_perm:[1,0,3,2] row_mask:0xf bank_mask:0xf
	global_store_dwordx2 v248, v[232:233], s[50:51] nt
	s_add_u32 s38, s38, 0x4000
	s_addc_u32 s39, s39, 0
	v_add_f32_dpp v236, v236, v236 quad_perm:[2,3,0,1] row_mask:0xf bank_mask:0xf
	s_add_u32 s50, s50, 0x2000
	s_addc_u32 s51, s51, 0
	v_add_f32_dpp v236, v236, v236 row_half_mirror row_mask:0xf bank_mask:0xf
	s_nop 1
	v_add_f32_dpp v236, v236, v236 row_mirror row_mask:0xf bank_mask:0xf
	s_mov_b64 exec, s[48:49]
	global_store_dword v249, v236, s[34:35] offset:1536
	s_mov_b64 exec, -1
	s_waitcnt vmcnt(63) lgkmcnt(1)
	v_pk_add_f32 v[126:127], v[238:239], v[126:127]
	v_pk_add_f32 v[128:129], v[240:241], v[128:129]
	v_pk_mul_f32 v[242:243], v[126:127], v[126:127]
	v_pk_mul_f32 v[244:245], v[128:129], v[128:129]
	ds_read_b128 v[238:241], v211 offset:9216
	v_add_f32_e32 v246, v242, v243
	v_add_f32_e32 v246, v244, v246
	v_add_f32_e32 v246, v245, v246
	global_store_dwordx4 v247, v[126:129], s[38:39] nt
	v_cvt_pk_bf16_f32 v242, v126, v127
	v_cvt_pk_bf16_f32 v243, v128, v129
	v_add_f32_dpp v246, v246, v246 quad_perm:[1,0,3,2] row_mask:0xf bank_mask:0xf
	global_store_dwordx2 v248, v[242:243], s[50:51] nt
	s_add_u32 s38, s38, 0x4000
	s_addc_u32 s39, s39, 0
	v_add_f32_dpp v246, v246, v246 quad_perm:[2,3,0,1] row_mask:0xf bank_mask:0xf
	s_add_u32 s50, s50, 0x2000
	s_addc_u32 s51, s51, 0
	v_add_f32_dpp v246, v246, v246 row_half_mirror row_mask:0xf bank_mask:0xf
	s_nop 1
	v_add_f32_dpp v246, v246, v246 row_mirror row_mask:0xf bank_mask:0xf
	s_mov_b64 exec, s[48:49]
	global_store_dword v249, v246, s[34:35] offset:1792
	s_mov_b64 exec, -1
	s_waitcnt vmcnt(63) lgkmcnt(1)
	v_pk_add_f32 v[66:67], v[228:229], v[66:67]
	v_pk_add_f32 v[68:69], v[230:231], v[68:69]
	v_pk_mul_f32 v[232:233], v[66:67], v[66:67]
	v_pk_mul_f32 v[234:235], v[68:69], v[68:69]
	ds_read_b128 v[228:231], v215 offset:10240
	v_add_f32_e32 v236, v232, v233
	v_add_f32_e32 v236, v234, v236
	v_add_f32_e32 v236, v235, v236
	global_store_dwordx4 v247, v[66:69], s[38:39] nt
	v_cvt_pk_bf16_f32 v232, v66, v67
	v_cvt_pk_bf16_f32 v233, v68, v69
	v_add_f32_dpp v236, v236, v236 quad_perm:[1,0,3,2] row_mask:0xf bank_mask:0xf
	global_store_dwordx2 v248, v[232:233], s[50:51] nt
	s_add_u32 s38, s38, 0x4000
	s_addc_u32 s39, s39, 0
	v_add_f32_dpp v236, v236, v236 quad_perm:[2,3,0,1] row_mask:0xf bank_mask:0xf
	s_add_u32 s50, s50, 0x2000
	s_addc_u32 s51, s51, 0
	v_add_f32_dpp v236, v236, v236 row_half_mirror row_mask:0xf bank_mask:0xf
	s_nop 1
	v_add_f32_dpp v236, v236, v236 row_mirror row_mask:0xf bank_mask:0xf
	s_mov_b64 exec, s[48:49]
	global_store_dword v249, v236, s[34:35] offset:2048
	s_mov_b64 exec, -1
	s_waitcnt vmcnt(63) lgkmcnt(1)
	v_pk_add_f32 v[70:71], v[238:239], v[70:71]
	v_pk_add_f32 v[72:73], v[240:241], v[72:73]
	v_pk_mul_f32 v[242:243], v[70:71], v[70:71]
	v_pk_mul_f32 v[244:245], v[72:73], v[72:73]
	ds_read_b128 v[238:241], v237 offset:11264
	v_add_f32_e32 v246, v242, v243
	v_add_f32_e32 v246, v244, v246
	v_add_f32_e32 v246, v245, v246
	global_store_dwordx4 v247, v[70:73], s[38:39] nt
	v_cvt_pk_bf16_f32 v242, v70, v71
	v_cvt_pk_bf16_f32 v243, v72, v73
	v_add_f32_dpp v246, v246, v246 quad_perm:[1,0,3,2] row_mask:0xf bank_mask:0xf
	global_store_dwordx2 v248, v[242:243], s[50:51] nt
	s_add_u32 s38, s38, 0x4000
	s_addc_u32 s39, s39, 0
	v_add_f32_dpp v246, v246, v246 quad_perm:[2,3,0,1] row_mask:0xf bank_mask:0xf
	s_add_u32 s50, s50, 0x2000
	s_addc_u32 s51, s51, 0
	v_add_f32_dpp v246, v246, v246 row_half_mirror row_mask:0xf bank_mask:0xf
	s_nop 1
	v_add_f32_dpp v246, v246, v246 row_mirror row_mask:0xf bank_mask:0xf
	s_mov_b64 exec, s[48:49]
	global_store_dword v249, v246, s[34:35] offset:2304
	s_mov_b64 exec, -1
	s_waitcnt vmcnt(63) lgkmcnt(1)
	v_pk_add_f32 v[74:75], v[228:229], v[74:75]
	v_pk_add_f32 v[76:77], v[230:231], v[76:77]
	v_pk_mul_f32 v[232:233], v[74:75], v[74:75]
	v_pk_mul_f32 v[234:235], v[76:77], v[76:77]
	ds_read_b128 v[228:231], v210 offset:12288
	v_add_f32_e32 v236, v232, v233
	v_add_f32_e32 v236, v234, v236
	v_add_f32_e32 v236, v235, v236
	global_store_dwordx4 v247, v[74:77], s[38:39] nt
	v_cvt_pk_bf16_f32 v232, v74, v75
	v_cvt_pk_bf16_f32 v233, v76, v77
	v_add_f32_dpp v236, v236, v236 quad_perm:[1,0,3,2] row_mask:0xf bank_mask:0xf
	global_store_dwordx2 v248, v[232:233], s[50:51] nt
	s_add_u32 s38, s38, 0x4000
	s_addc_u32 s39, s39, 0
	v_add_f32_dpp v236, v236, v236 quad_perm:[2,3,0,1] row_mask:0xf bank_mask:0xf
	s_add_u32 s50, s50, 0x2000
	s_addc_u32 s51, s51, 0
	v_add_f32_dpp v236, v236, v236 row_half_mirror row_mask:0xf bank_mask:0xf
	s_nop 1
	v_add_f32_dpp v236, v236, v236 row_mirror row_mask:0xf bank_mask:0xf
	s_mov_b64 exec, s[48:49]
	global_store_dword v249, v236, s[34:35] offset:2560
	s_mov_b64 exec, -1
	s_waitcnt vmcnt(63) lgkmcnt(1)
	v_pk_add_f32 v[78:79], v[238:239], v[78:79]
	v_pk_add_f32 v[80:81], v[240:241], v[80:81]
	v_pk_mul_f32 v[242:243], v[78:79], v[78:79]
	v_pk_mul_f32 v[244:245], v[80:81], v[80:81]
	ds_read_b128 v[238:241], v211 offset:13312
	v_add_f32_e32 v246, v242, v243
	v_add_f32_e32 v246, v244, v246
	v_add_f32_e32 v246, v245, v246
	global_store_dwordx4 v247, v[78:81], s[38:39] nt
	v_cvt_pk_bf16_f32 v242, v78, v79
	v_cvt_pk_bf16_f32 v243, v80, v81
	v_add_f32_dpp v246, v246, v246 quad_perm:[1,0,3,2] row_mask:0xf bank_mask:0xf
	global_store_dwordx2 v248, v[242:243], s[50:51] nt
	s_add_u32 s38, s38, 0x4000
	s_addc_u32 s39, s39, 0
	v_add_f32_dpp v246, v246, v246 quad_perm:[2,3,0,1] row_mask:0xf bank_mask:0xf
	s_add_u32 s50, s50, 0x2000
	s_addc_u32 s51, s51, 0
	v_add_f32_dpp v246, v246, v246 row_half_mirror row_mask:0xf bank_mask:0xf
	s_nop 1
	v_add_f32_dpp v246, v246, v246 row_mirror row_mask:0xf bank_mask:0xf
	s_mov_b64 exec, s[48:49]
	global_store_dword v249, v246, s[34:35] offset:2816
	s_mov_b64 exec, -1
	s_waitcnt vmcnt(63) lgkmcnt(1)
	v_pk_add_f32 v[98:99], v[228:229], v[98:99]
	v_pk_add_f32 v[100:101], v[230:231], v[100:101]
	v_pk_mul_f32 v[232:233], v[98:99], v[98:99]
	v_pk_mul_f32 v[234:235], v[100:101], v[100:101]
	ds_read_b128 v[228:231], v215 offset:14336
	v_add_f32_e32 v236, v232, v233
	v_add_f32_e32 v236, v234, v236
	v_add_f32_e32 v236, v235, v236
	global_store_dwordx4 v247, v[98:101], s[38:39] nt
	v_cvt_pk_bf16_f32 v232, v98, v99
	v_cvt_pk_bf16_f32 v233, v100, v101
	v_add_f32_dpp v236, v236, v236 quad_perm:[1,0,3,2] row_mask:0xf bank_mask:0xf
	global_store_dwordx2 v248, v[232:233], s[50:51] nt
	s_add_u32 s38, s38, 0x4000
	s_addc_u32 s39, s39, 0
	v_add_f32_dpp v236, v236, v236 quad_perm:[2,3,0,1] row_mask:0xf bank_mask:0xf
	s_add_u32 s50, s50, 0x2000
	s_addc_u32 s51, s51, 0
	v_add_f32_dpp v236, v236, v236 row_half_mirror row_mask:0xf bank_mask:0xf
	s_nop 1
	v_add_f32_dpp v236, v236, v236 row_mirror row_mask:0xf bank_mask:0xf
	s_mov_b64 exec, s[48:49]
	global_store_dword v249, v236, s[34:35] offset:3072
	s_mov_b64 exec, -1
	s_waitcnt vmcnt(63) lgkmcnt(1)
	v_pk_add_f32 v[102:103], v[238:239], v[102:103]
	v_pk_add_f32 v[104:105], v[240:241], v[104:105]
	v_pk_mul_f32 v[242:243], v[102:103], v[102:103]
	v_pk_mul_f32 v[244:245], v[104:105], v[104:105]
	ds_read_b128 v[238:241], v237 offset:15360
	v_add_f32_e32 v246, v242, v243
	v_add_f32_e32 v246, v244, v246
	v_add_f32_e32 v246, v245, v246
	global_store_dwordx4 v247, v[102:105], s[38:39] nt
	v_cvt_pk_bf16_f32 v242, v102, v103
	v_cvt_pk_bf16_f32 v243, v104, v105
	v_add_f32_dpp v246, v246, v246 quad_perm:[1,0,3,2] row_mask:0xf bank_mask:0xf
	global_store_dwordx2 v248, v[242:243], s[50:51] nt
	s_add_u32 s38, s38, 0x4000
	s_addc_u32 s39, s39, 0
	v_add_f32_dpp v246, v246, v246 quad_perm:[2,3,0,1] row_mask:0xf bank_mask:0xf
	s_add_u32 s50, s50, 0x2000
	s_addc_u32 s51, s51, 0
	v_add_f32_dpp v246, v246, v246 row_half_mirror row_mask:0xf bank_mask:0xf
	s_nop 1
	v_add_f32_dpp v246, v246, v246 row_mirror row_mask:0xf bank_mask:0xf
	s_mov_b64 exec, s[48:49]
	global_store_dword v249, v246, s[34:35] offset:3328
	s_mov_b64 exec, -1
	s_waitcnt vmcnt(63) lgkmcnt(1)
	v_pk_add_f32 v[106:107], v[228:229], v[106:107]
	v_pk_add_f32 v[108:109], v[230:231], v[108:109]
	v_pk_mul_f32 v[232:233], v[106:107], v[106:107]
	v_pk_mul_f32 v[234:235], v[108:109], v[108:109]
	v_add_f32_e32 v236, v232, v233
	v_add_f32_e32 v236, v234, v236
	v_add_f32_e32 v236, v235, v236
	global_store_dwordx4 v247, v[106:109], s[38:39] nt
	v_cvt_pk_bf16_f32 v232, v106, v107
	v_cvt_pk_bf16_f32 v233, v108, v109
	v_add_f32_dpp v236, v236, v236 quad_perm:[1,0,3,2] row_mask:0xf bank_mask:0xf
	global_store_dwordx2 v248, v[232:233], s[50:51] nt
	s_add_u32 s38, s38, 0x4000
	s_addc_u32 s39, s39, 0
	v_add_f32_dpp v236, v236, v236 quad_perm:[2,3,0,1] row_mask:0xf bank_mask:0xf
	s_add_u32 s50, s50, 0x2000
	s_addc_u32 s51, s51, 0
	v_add_f32_dpp v236, v236, v236 row_half_mirror row_mask:0xf bank_mask:0xf
	s_nop 1
	v_add_f32_dpp v236, v236, v236 row_mirror row_mask:0xf bank_mask:0xf
	s_mov_b64 exec, s[48:49]
	global_store_dword v249, v236, s[34:35] offset:3584
	s_mov_b64 exec, -1
	s_waitcnt vmcnt(63) lgkmcnt(0)
	v_pk_add_f32 v[110:111], v[238:239], v[110:111]
	v_pk_add_f32 v[112:113], v[240:241], v[112:113]
	v_pk_mul_f32 v[242:243], v[110:111], v[110:111]
	v_pk_mul_f32 v[244:245], v[112:113], v[112:113]
	v_add_f32_e32 v246, v242, v243
	v_add_f32_e32 v246, v244, v246
	v_add_f32_e32 v246, v245, v246
	global_store_dwordx4 v247, v[110:113], s[38:39] nt
	v_cvt_pk_bf16_f32 v242, v110, v111
	v_cvt_pk_bf16_f32 v243, v112, v113
	v_add_f32_dpp v246, v246, v246 quad_perm:[1,0,3,2] row_mask:0xf bank_mask:0xf
	global_store_dwordx2 v248, v[242:243], s[50:51] nt
	s_add_u32 s38, s38, 0x4000
	s_addc_u32 s39, s39, 0
	v_add_f32_dpp v246, v246, v246 quad_perm:[2,3,0,1] row_mask:0xf bank_mask:0xf
	s_add_u32 s50, s50, 0x2000
	s_addc_u32 s51, s51, 0
	v_add_f32_dpp v246, v246, v246 row_half_mirror row_mask:0xf bank_mask:0xf
	s_nop 1
	v_add_f32_dpp v246, v246, v246 row_mirror row_mask:0xf bank_mask:0xf
	s_mov_b64 exec, s[48:49]
	global_store_dword v249, v246, s[34:35] offset:3840
	s_mov_b64 exec, -1
	s_waitcnt lgkmcnt(0)
	s_branch .LBB0_1122

.LBB0_1526:
	v_readfirstlane_b32 s40, v204
	s_lshr_b32 s40, s40, 6
	s_and_b32 s41, s40, 1
	s_bfe_u32 s42, s40, 0x10001
	s_lshr_b32 s43, s40, 2
	s_lshl_b32 s44, s4, 1
	s_add_i32 s44, s44, s42
	s_lshl_b32 s45, s44, 7
	s_lshl_b32 s46, s41, 6
	s_add_i32 s45, s45, s46
	s_lshl_b32 s46, s43, 7
	s_add_i32 s46, s46, s2
	s_lshl_b32 s47, s44, 1
	s_add_i32 s47, s47, s41
	v_readlane_b32 s36, v251, 50
	v_readlane_b32 s37, v251, 51
	v_readlane_b32 s38, v250, 9
	v_readlane_b32 s39, v250, 10
	v_readlane_b32 s50, v250, 11
	v_readlane_b32 s51, v250, 12
	s_add_u32 s34, s50, 0xf900000
	s_addc_u32 s35, s51, 0
	s_add_u32 s50, s50, 0x5800000
	s_addc_u32 s51, s51, 0
	s_lshl_b32 s48, s46, 12
	s_lshl_b32 s49, s45, 2
	s_add_u32 s48, s48, s49
	s_add_u32 s36, s36, s48
	s_addc_u32 s37, s37, 0
	s_add_u32 s38, s38, s48
	s_addc_u32 s39, s39, 0
	s_lshr_b32 s48, s48, 1
	s_add_u32 s50, s50, s48
	s_addc_u32 s51, s51, 0
	s_lshl_b32 s48, s46, 6
	s_lshl_b32 s49, s47, 2
	s_add_u32 s48, s48, s49
	s_add_u32 s34, s34, s48
	s_addc_u32 s35, s35, 0
	v_and_b32_e32 v249, 63, v204
	v_and_b32_e32 v198, 31, v249
	v_lshrrev_b32_e32 v199, 5, v249
	v_and_b32_e32 v208, 15, v249
	v_lshrrev_b32_e32 v209, 4, v249
	s_lshl_b32 s40, s40, 14
	v_and_b32_e32 v238, 15, v198
	v_xor_b32_e32 v238, v238, v199
	v_lshl_add_u32 v239, v198, 8, s40
	v_xor_b32_e32 v228, 0, v238
	v_lshl_add_u32 v228, v228, 4, v239
	v_xor_b32_e32 v229, 2, v238
	v_lshl_add_u32 v229, v229, 4, v239
	v_xor_b32_e32 v230, 4, v238
	v_lshl_add_u32 v230, v230, 4, v239
	v_xor_b32_e32 v231, 6, v238
	v_lshl_add_u32 v231, v231, 4, v239
	v_xor_b32_e32 v232, 8, v238
	v_lshl_add_u32 v232, v232, 4, v239
	v_xor_b32_e32 v233, 10, v238
	v_lshl_add_u32 v233, v233, 4, v239
	v_xor_b32_e32 v234, 12, v238
	v_lshl_add_u32 v234, v234, 4, v239
	v_xor_b32_e32 v235, 14, v238
	v_lshl_add_u32 v235, v235, 4, v239
	v_lshl_add_u32 v239, v209, 8, s40
	v_add_u32_e32 v210, 0, v209
	v_xor_b32_e32 v210, v210, v208
	v_lshl_add_u32 v210, v210, 4, v239
	v_add_u32_e32 v211, 4, v209
	v_xor_b32_e32 v211, v211, v208
	v_lshl_add_u32 v211, v211, 4, v239
	v_add_u32_e32 v215, 8, v209
	v_xor_b32_e32 v215, v215, v208
	v_lshl_add_u32 v215, v215, 4, v239
	v_add_u32_e32 v237, 12, v209
	v_xor_b32_e32 v237, v237, v208
	v_lshl_add_u32 v237, v237, 4, v239
	v_lshlrev_b32_e32 v247, 12, v209
	v_lshl_add_u32 v247, v208, 4, v247
	v_lshrrev_b32_e32 v248, 1, v247
	v_lshlrev_b32_e32 v249, 6, v209
	s_mov_b32 s48, 0x00010001
	s_mov_b32 s49, 0x00010001
	global_load_dwordx4 v[130:133], v247, s[36:37]
	s_add_u32 s36, s36, 0x4000
	s_addc_u32 s37, s37, 0
	global_load_dwordx4 v[134:137], v247, s[36:37]
	s_add_u32 s36, s36, 0x4000
	s_addc_u32 s37, s37, 0
	global_load_dwordx4 v[138:141], v247, s[36:37]
	s_add_u32 s36, s36, 0x4000
	s_addc_u32 s37, s37, 0
	global_load_dwordx4 v[142:145], v247, s[36:37]
	s_add_u32 s36, s36, 0x4000
	s_addc_u32 s37, s37, 0
	global_load_dwordx4 v[146:149], v247, s[36:37]
	s_add_u32 s36, s36, 0x4000
	s_addc_u32 s37, s37, 0
	global_load_dwordx4 v[150:153], v247, s[36:37]
	s_add_u32 s36, s36, 0x4000
	s_addc_u32 s37, s37, 0
	global_load_dwordx4 v[154:157], v247, s[36:37]
	s_add_u32 s36, s36, 0x4000
	s_addc_u32 s37, s37, 0
	global_load_dwordx4 v[158:161], v247, s[36:37]
	s_add_u32 s36, s36, 0x4000
	s_addc_u32 s37, s37, 0
	global_load_dwordx4 v[162:165], v247, s[36:37]
	s_add_u32 s36, s36, 0x4000
	s_addc_u32 s37, s37, 0
	global_load_dwordx4 v[166:169], v247, s[36:37]
	s_add_u32 s36, s36, 0x4000
	s_addc_u32 s37, s37, 0
	global_load_dwordx4 v[170:173], v247, s[36:37]
	s_add_u32 s36, s36, 0x4000
	s_addc_u32 s37, s37, 0
	global_load_dwordx4 v[188:191], v247, s[36:37]
	s_add_u32 s36, s36, 0x4000
	s_addc_u32 s37, s37, 0
	global_load_dwordx4 v[200:203], v247, s[36:37]
	s_add_u32 s36, s36, 0x4000
	s_addc_u32 s37, s37, 0
	global_load_dwordx4 v[216:219], v247, s[36:37]
	s_add_u32 s36, s36, 0x4000
	s_addc_u32 s37, s37, 0
	global_load_dwordx4 v[220:223], v247, s[36:37]
	s_add_u32 s36, s36, 0x4000
	s_addc_u32 s37, s37, 0
	global_load_dwordx4 v[224:227], v247, s[36:37]
	s_add_u32 s36, s36, 0x4000
	s_addc_u32 s37, s37, 0
	ds_write_b128 v228, v[82:85]
	ds_write_b128 v229, v[86:89]
	ds_write_b128 v230, v[90:93]
	ds_write_b128 v231, v[94:97]
	ds_write_b128 v232, v[114:117]
	ds_write_b128 v233, v[118:121]
	ds_write_b128 v234, v[122:125]
	ds_write_b128 v235, v[126:129]
	ds_write_b128 v228, v[66:69] offset:8192
	ds_write_b128 v229, v[70:73] offset:8192
	ds_write_b128 v230, v[74:77] offset:8192
	ds_write_b128 v231, v[78:81] offset:8192
	ds_write_b128 v232, v[98:101] offset:8192
	ds_write_b128 v233, v[102:105] offset:8192
	ds_write_b128 v234, v[106:109] offset:8192
	ds_write_b128 v235, v[110:113] offset:8192
	global_load_dwordx4 v[82:85], v247, s[36:37]
	s_add_u32 s36, s36, 0x4000
	s_addc_u32 s37, s37, 0
	global_load_dwordx4 v[86:89], v247, s[36:37]
	s_add_u32 s36, s36, 0x4000
	s_addc_u32 s37, s37, 0
	global_load_dwordx4 v[90:93], v247, s[36:37]
	s_add_u32 s36, s36, 0x4000
	s_addc_u32 s37, s37, 0
	global_load_dwordx4 v[94:97], v247, s[36:37]
	s_add_u32 s36, s36, 0x4000
	s_addc_u32 s37, s37, 0
	global_load_dwordx4 v[114:117], v247, s[36:37]
	s_add_u32 s36, s36, 0x4000
	s_addc_u32 s37, s37, 0
	global_load_dwordx4 v[118:121], v247, s[36:37]
	s_add_u32 s36, s36, 0x4000
	s_addc_u32 s37, s37, 0
	global_load_dwordx4 v[122:125], v247, s[36:37]
	s_add_u32 s36, s36, 0x4000
	s_addc_u32 s37, s37, 0
	global_load_dwordx4 v[126:129], v247, s[36:37]
	s_add_u32 s36, s36, 0x4000
	s_addc_u32 s37, s37, 0
	global_load_dwordx4 v[66:69], v247, s[36:37]
	s_add_u32 s36, s36, 0x4000
	s_addc_u32 s37, s37, 0
	global_load_dwordx4 v[70:73], v247, s[36:37]
	s_add_u32 s36, s36, 0x4000
	s_addc_u32 s37, s37, 0
	global_load_dwordx4 v[74:77], v247, s[36:37]
	s_add_u32 s36, s36, 0x4000
	s_addc_u32 s37, s37, 0
	global_load_dwordx4 v[78:81], v247, s[36:37]
	s_add_u32 s36, s36, 0x4000
	s_addc_u32 s37, s37, 0
	global_load_dwordx4 v[98:101], v247, s[36:37]
	s_add_u32 s36, s36, 0x4000
	s_addc_u32 s37, s37, 0
	global_load_dwordx4 v[102:105], v247, s[36:37]
	s_add_u32 s36, s36, 0x4000
	s_addc_u32 s37, s37, 0
	global_load_dwordx4 v[106:109], v247, s[36:37]
	s_add_u32 s36, s36, 0x4000
	s_addc_u32 s37, s37, 0
	global_load_dwordx4 v[110:113], v247, s[36:37]
	s_add_u32 s36, s36, 0x4000
	s_addc_u32 s37, s37, 0
	s_waitcnt lgkmcnt(0)
	ds_read_b128 v[228:231], v210 offset:0
	ds_read_b128 v[238:241], v211 offset:1024
	s_waitcnt vmcnt(31) lgkmcnt(1)
	v_pk_add_f32 v[130:131], v[228:229], v[130:131]
	v_pk_add_f32 v[132:133], v[230:231], v[132:133]
	v_pk_mul_f32 v[232:233], v[130:131], v[130:131]
	v_pk_mul_f32 v[234:235], v[132:133], v[132:133]
	ds_read_b128 v[228:231], v215 offset:2048
	v_add_f32_e32 v236, v232, v233
	v_add_f32_e32 v236, v234, v236
	v_add_f32_e32 v236, v235, v236
	global_store_dwordx4 v247, v[130:133], s[38:39] nt
	v_cvt_pk_bf16_f32 v232, v130, v131
	v_cvt_pk_bf16_f32 v233, v132, v133
	v_add_f32_dpp v236, v236, v236 quad_perm:[1,0,3,2] row_mask:0xf bank_mask:0xf
	global_store_dwordx2 v248, v[232:233], s[50:51] nt
	s_add_u32 s38, s38, 0x4000
	s_addc_u32 s39, s39, 0
	v_add_f32_dpp v236, v236, v236 quad_perm:[2,3,0,1] row_mask:0xf bank_mask:0xf
	s_add_u32 s50, s50, 0x2000
	s_addc_u32 s51, s51, 0
	v_add_f32_dpp v236, v236, v236 row_half_mirror row_mask:0xf bank_mask:0xf
	s_nop 1
	v_add_f32_dpp v236, v236, v236 row_mirror row_mask:0xf bank_mask:0xf
	s_mov_b64 exec, s[48:49]
	global_store_dword v249, v236, s[34:35] offset:0
	s_mov_b64 exec, -1
	s_waitcnt vmcnt(33) lgkmcnt(1)
	v_pk_add_f32 v[134:135], v[238:239], v[134:135]
	v_pk_add_f32 v[136:137], v[240:241], v[136:137]
	v_pk_mul_f32 v[242:243], v[134:135], v[134:135]
	v_pk_mul_f32 v[244:245], v[136:137], v[136:137]
	ds_read_b128 v[238:241], v237 offset:3072
	v_add_f32_e32 v246, v242, v243
	v_add_f32_e32 v246, v244, v246
	v_add_f32_e32 v246, v245, v246
	global_store_dwordx4 v247, v[134:137], s[38:39] nt
	v_cvt_pk_bf16_f32 v242, v134, v135
	v_cvt_pk_bf16_f32 v243, v136, v137
	v_add_f32_dpp v246, v246, v246 quad_perm:[1,0,3,2] row_mask:0xf bank_mask:0xf
	global_store_dwordx2 v248, v[242:243], s[50:51] nt
	s_add_u32 s38, s38, 0x4000
	s_addc_u32 s39, s39, 0
	v_add_f32_dpp v246, v246, v246 quad_perm:[2,3,0,1] row_mask:0xf bank_mask:0xf
	s_add_u32 s50, s50, 0x2000
	s_addc_u32 s51, s51, 0
	v_add_f32_dpp v246, v246, v246 row_half_mirror row_mask:0xf bank_mask:0xf
	s_nop 1
	v_add_f32_dpp v246, v246, v246 row_mirror row_mask:0xf bank_mask:0xf
	s_mov_b64 exec, s[48:49]
	global_store_dword v249, v246, s[34:35] offset:256
	s_mov_b64 exec, -1
	s_waitcnt vmcnt(35) lgkmcnt(1)
	v_pk_add_f32 v[138:139], v[228:229], v[138:139]
	v_pk_add_f32 v[140:141], v[230:231], v[140:141]
	v_pk_mul_f32 v[232:233], v[138:139], v[138:139]
	v_pk_mul_f32 v[234:235], v[140:141], v[140:141]
	ds_read_b128 v[228:231], v210 offset:4096
	v_add_f32_e32 v236, v232, v233
	v_add_f32_e32 v236, v234, v236
	v_add_f32_e32 v236, v235, v236
	global_store_dwordx4 v247, v[138:141], s[38:39] nt
	v_cvt_pk_bf16_f32 v232, v138, v139
	v_cvt_pk_bf16_f32 v233, v140, v141
	v_add_f32_dpp v236, v236, v236 quad_perm:[1,0,3,2] row_mask:0xf bank_mask:0xf
	global_store_dwordx2 v248, v[232:233], s[50:51] nt
	s_add_u32 s38, s38, 0x4000
	s_addc_u32 s39, s39, 0
	v_add_f32_dpp v236, v236, v236 quad_perm:[2,3,0,1] row_mask:0xf bank_mask:0xf
	s_add_u32 s50, s50, 0x2000
	s_addc_u32 s51, s51, 0
	v_add_f32_dpp v236, v236, v236 row_half_mirror row_mask:0xf bank_mask:0xf
	s_nop 1
	v_add_f32_dpp v236, v236, v236 row_mirror row_mask:0xf bank_mask:0xf
	s_mov_b64 exec, s[48:49]
	global_store_dword v249, v236, s[34:35] offset:512
	s_mov_b64 exec, -1
	s_waitcnt vmcnt(37) lgkmcnt(1)
	v_pk_add_f32 v[142:143], v[238:239], v[142:143]
	v_pk_add_f32 v[144:145], v[240:241], v[144:145]
	v_pk_mul_f32 v[242:243], v[142:143], v[142:143]
	v_pk_mul_f32 v[244:245], v[144:145], v[144:145]
	ds_read_b128 v[238:241], v211 offset:5120
	v_add_f32_e32 v246, v242, v243
	v_add_f32_e32 v246, v244, v246
	v_add_f32_e32 v246, v245, v246
	global_store_dwordx4 v247, v[142:145], s[38:39] nt
	v_cvt_pk_bf16_f32 v242, v142, v143
	v_cvt_pk_bf16_f32 v243, v144, v145
	v_add_f32_dpp v246, v246, v246 quad_perm:[1,0,3,2] row_mask:0xf bank_mask:0xf
	global_store_dwordx2 v248, v[242:243], s[50:51] nt
	s_add_u32 s38, s38, 0x4000
	s_addc_u32 s39, s39, 0
	v_add_f32_dpp v246, v246, v246 quad_perm:[2,3,0,1] row_mask:0xf bank_mask:0xf
	s_add_u32 s50, s50, 0x2000
	s_addc_u32 s51, s51, 0
	v_add_f32_dpp v246, v246, v246 row_half_mirror row_mask:0xf bank_mask:0xf
	s_nop 1
	v_add_f32_dpp v246, v246, v246 row_mirror row_mask:0xf bank_mask:0xf
	s_mov_b64 exec, s[48:49]
	global_store_dword v249, v246, s[34:35] offset:768
	s_mov_b64 exec, -1
	s_waitcnt vmcnt(39) lgkmcnt(1)
	v_pk_add_f32 v[146:147], v[228:229], v[146:147]
	v_pk_add_f32 v[148:149], v[230:231], v[148:149]
	v_pk_mul_f32 v[232:233], v[146:147], v[146:147]
	v_pk_mul_f32 v[234:235], v[148:149], v[148:149]
	ds_read_b128 v[228:231], v215 offset:6144
	v_add_f32_e32 v236, v232, v233
	v_add_f32_e32 v236, v234, v236
	v_add_f32_e32 v236, v235, v236
	global_store_dwordx4 v247, v[146:149], s[38:39] nt
	v_cvt_pk_bf16_f32 v232, v146, v147
	v_cvt_pk_bf16_f32 v233, v148, v149
	v_add_f32_dpp v236, v236, v236 quad_perm:[1,0,3,2] row_mask:0xf bank_mask:0xf
	global_store_dwordx2 v248, v[232:233], s[50:51] nt
	s_add_u32 s38, s38, 0x4000
	s_addc_u32 s39, s39, 0
	v_add_f32_dpp v236, v236, v236 quad_perm:[2,3,0,1] row_mask:0xf bank_mask:0xf
	s_add_u32 s50, s50, 0x2000
	s_addc_u32 s51, s51, 0
	v_add_f32_dpp v236, v236, v236 row_half_mirror row_mask:0xf bank_mask:0xf
	s_nop 1
	v_add_f32_dpp v236, v236, v236 row_mirror row_mask:0xf bank_mask:0xf
	s_mov_b64 exec, s[48:49]
	global_store_dword v249, v236, s[34:35] offset:1024
	s_mov_b64 exec, -1
	s_waitcnt vmcnt(41) lgkmcnt(1)
	v_pk_add_f32 v[150:151], v[238:239], v[150:151]
	v_pk_add_f32 v[152:153], v[240:241], v[152:153]
	v_pk_mul_f32 v[242:243], v[150:151], v[150:151]
	v_pk_mul_f32 v[244:245], v[152:153], v[152:153]
	ds_read_b128 v[238:241], v237 offset:7168
	v_add_f32_e32 v246, v242, v243
	v_add_f32_e32 v246, v244, v246
	v_add_f32_e32 v246, v245, v246
	global_store_dwordx4 v247, v[150:153], s[38:39] nt
	v_cvt_pk_bf16_f32 v242, v150, v151
	v_cvt_pk_bf16_f32 v243, v152, v153
	v_add_f32_dpp v246, v246, v246 quad_perm:[1,0,3,2] row_mask:0xf bank_mask:0xf
	global_store_dwordx2 v248, v[242:243], s[50:51] nt
	s_add_u32 s38, s38, 0x4000
	s_addc_u32 s39, s39, 0
	v_add_f32_dpp v246, v246, v246 quad_perm:[2,3,0,1] row_mask:0xf bank_mask:0xf
	s_add_u32 s50, s50, 0x2000
	s_addc_u32 s51, s51, 0
	v_add_f32_dpp v246, v246, v246 row_half_mirror row_mask:0xf bank_mask:0xf
	s_nop 1
	v_add_f32_dpp v246, v246, v246 row_mirror row_mask:0xf bank_mask:0xf
	s_mov_b64 exec, s[48:49]
	global_store_dword v249, v246, s[34:35] offset:1280
	s_mov_b64 exec, -1
	s_waitcnt vmcnt(43) lgkmcnt(1)
	v_pk_add_f32 v[154:155], v[228:229], v[154:155]
	v_pk_add_f32 v[156:157], v[230:231], v[156:157]
	v_pk_mul_f32 v[232:233], v[154:155], v[154:155]
	v_pk_mul_f32 v[234:235], v[156:157], v[156:157]
	ds_read_b128 v[228:231], v210 offset:8192
	v_add_f32_e32 v236, v232, v233
	v_add_f32_e32 v236, v234, v236
	v_add_f32_e32 v236, v235, v236
	global_store_dwordx4 v247, v[154:157], s[38:39] nt
	v_cvt_pk_bf16_f32 v232, v154, v155
	v_cvt_pk_bf16_f32 v233, v156, v157
	v_add_f32_dpp v236, v236, v236 quad_perm:[1,0,3,2] row_mask:0xf bank_mask:0xf
	global_store_dwordx2 v248, v[232:233], s[50:51] nt
	s_add_u32 s38, s38, 0x4000
	s_addc_u32 s39, s39, 0
	v_add_f32_dpp v236, v236, v236 quad_perm:[2,3,0,1] row_mask:0xf bank_mask:0xf
	s_add_u32 s50, s50, 0x2000
	s_addc_u32 s51, s51, 0
	v_add_f32_dpp v236, v236, v236 row_half_mirror row_mask:0xf bank_mask:0xf
	s_nop 1
	v_add_f32_dpp v236, v236, v236 row_mirror row_mask:0xf bank_mask:0xf
	s_mov_b64 exec, s[48:49]
	global_store_dword v249, v236, s[34:35] offset:1536
	s_mov_b64 exec, -1
	s_waitcnt vmcnt(45) lgkmcnt(1)
	v_pk_add_f32 v[158:159], v[238:239], v[158:159]
	v_pk_add_f32 v[160:161], v[240:241], v[160:161]
	v_pk_mul_f32 v[242:243], v[158:159], v[158:159]
	v_pk_mul_f32 v[244:245], v[160:161], v[160:161]
	ds_read_b128 v[238:241], v211 offset:9216
	v_add_f32_e32 v246, v242, v243
	v_add_f32_e32 v246, v244, v246
	v_add_f32_e32 v246, v245, v246
	global_store_dwordx4 v247, v[158:161], s[38:39] nt
	v_cvt_pk_bf16_f32 v242, v158, v159
	v_cvt_pk_bf16_f32 v243, v160, v161
	v_add_f32_dpp v246, v246, v246 quad_perm:[1,0,3,2] row_mask:0xf bank_mask:0xf
	global_store_dwordx2 v248, v[242:243], s[50:51] nt
	s_add_u32 s38, s38, 0x4000
	s_addc_u32 s39, s39, 0
	v_add_f32_dpp v246, v246, v246 quad_perm:[2,3,0,1] row_mask:0xf bank_mask:0xf
	s_add_u32 s50, s50, 0x2000
	s_addc_u32 s51, s51, 0
	v_add_f32_dpp v246, v246, v246 row_half_mirror row_mask:0xf bank_mask:0xf
	s_nop 1
	v_add_f32_dpp v246, v246, v246 row_mirror row_mask:0xf bank_mask:0xf
	s_mov_b64 exec, s[48:49]
	global_store_dword v249, v246, s[34:35] offset:1792
	s_mov_b64 exec, -1
	s_waitcnt vmcnt(47) lgkmcnt(1)
	v_pk_add_f32 v[162:163], v[228:229], v[162:163]
	v_pk_add_f32 v[164:165], v[230:231], v[164:165]
	v_pk_mul_f32 v[232:233], v[162:163], v[162:163]
	v_pk_mul_f32 v[234:235], v[164:165], v[164:165]
	ds_read_b128 v[228:231], v215 offset:10240
	v_add_f32_e32 v236, v232, v233
	v_add_f32_e32 v236, v234, v236
	v_add_f32_e32 v236, v235, v236
	global_store_dwordx4 v247, v[162:165], s[38:39] nt
	v_cvt_pk_bf16_f32 v232, v162, v163
	v_cvt_pk_bf16_f32 v233, v164, v165
	v_add_f32_dpp v236, v236, v236 quad_perm:[1,0,3,2] row_mask:0xf bank_mask:0xf
	global_store_dwordx2 v248, v[232:233], s[50:51] nt
	s_add_u32 s38, s38, 0x4000
	s_addc_u32 s39, s39, 0
	v_add_f32_dpp v236, v236, v236 quad_perm:[2,3,0,1] row_mask:0xf bank_mask:0xf
	s_add_u32 s50, s50, 0x2000
	s_addc_u32 s51, s51, 0
	v_add_f32_dpp v236, v236, v236 row_half_mirror row_mask:0xf bank_mask:0xf
	s_nop 1
	v_add_f32_dpp v236, v236, v236 row_mirror row_mask:0xf bank_mask:0xf
	s_mov_b64 exec, s[48:49]
	global_store_dword v249, v236, s[34:35] offset:2048
	s_mov_b64 exec, -1
	s_waitcnt vmcnt(49) lgkmcnt(1)
	v_pk_add_f32 v[166:167], v[238:239], v[166:167]
	v_pk_add_f32 v[168:169], v[240:241], v[168:169]
	v_pk_mul_f32 v[242:243], v[166:167], v[166:167]
	v_pk_mul_f32 v[244:245], v[168:169], v[168:169]
	ds_read_b128 v[238:241], v237 offset:11264
	v_add_f32_e32 v246, v242, v243
	v_add_f32_e32 v246, v244, v246
	v_add_f32_e32 v246, v245, v246
	global_store_dwordx4 v247, v[166:169], s[38:39] nt
	v_cvt_pk_bf16_f32 v242, v166, v167
	v_cvt_pk_bf16_f32 v243, v168, v169
	v_add_f32_dpp v246, v246, v246 quad_perm:[1,0,3,2] row_mask:0xf bank_mask:0xf
	global_store_dwordx2 v248, v[242:243], s[50:51] nt
	s_add_u32 s38, s38, 0x4000
	s_addc_u32 s39, s39, 0
	v_add_f32_dpp v246, v246, v246 quad_perm:[2,3,0,1] row_mask:0xf bank_mask:0xf
	s_add_u32 s50, s50, 0x2000
	s_addc_u32 s51, s51, 0
	v_add_f32_dpp v246, v246, v246 row_half_mirror row_mask:0xf bank_mask:0xf
	s_nop 1
	v_add_f32_dpp v246, v246, v246 row_mirror row_mask:0xf bank_mask:0xf
	s_mov_b64 exec, s[48:49]
	global_store_dword v249, v246, s[34:35] offset:2304
	s_mov_b64 exec, -1
	s_waitcnt vmcnt(51) lgkmcnt(1)
	v_pk_add_f32 v[170:171], v[228:229], v[170:171]
	v_pk_add_f32 v[172:173], v[230:231], v[172:173]
	v_pk_mul_f32 v[232:233], v[170:171], v[170:171]
	v_pk_mul_f32 v[234:235], v[172:173], v[172:173]
	ds_read_b128 v[228:231], v210 offset:12288
	v_add_f32_e32 v236, v232, v233
	v_add_f32_e32 v236, v234, v236
	v_add_f32_e32 v236, v235, v236
	global_store_dwordx4 v247, v[170:173], s[38:39] nt
	v_cvt_pk_bf16_f32 v232, v170, v171
	v_cvt_pk_bf16_f32 v233, v172, v173
	v_add_f32_dpp v236, v236, v236 quad_perm:[1,0,3,2] row_mask:0xf bank_mask:0xf
	global_store_dwordx2 v248, v[232:233], s[50:51] nt
	s_add_u32 s38, s38, 0x4000
	s_addc_u32 s39, s39, 0
	v_add_f32_dpp v236, v236, v236 quad_perm:[2,3,0,1] row_mask:0xf bank_mask:0xf
	s_add_u32 s50, s50, 0x2000
	s_addc_u32 s51, s51, 0
	v_add_f32_dpp v236, v236, v236 row_half_mirror row_mask:0xf bank_mask:0xf
	s_nop 1
	v_add_f32_dpp v236, v236, v236 row_mirror row_mask:0xf bank_mask:0xf
	s_mov_b64 exec, s[48:49]
	global_store_dword v249, v236, s[34:35] offset:2560
	s_mov_b64 exec, -1
	s_waitcnt vmcnt(53) lgkmcnt(1)
	v_pk_add_f32 v[188:189], v[238:239], v[188:189]
	v_pk_add_f32 v[190:191], v[240:241], v[190:191]
	v_pk_mul_f32 v[242:243], v[188:189], v[188:189]
	v_pk_mul_f32 v[244:245], v[190:191], v[190:191]
	ds_read_b128 v[238:241], v211 offset:13312
	v_add_f32_e32 v246, v242, v243
	v_add_f32_e32 v246, v244, v246
	v_add_f32_e32 v246, v245, v246
	global_store_dwordx4 v247, v[188:191], s[38:39] nt
	v_cvt_pk_bf16_f32 v242, v188, v189
	v_cvt_pk_bf16_f32 v243, v190, v191
	v_add_f32_dpp v246, v246, v246 quad_perm:[1,0,3,2] row_mask:0xf bank_mask:0xf
	global_store_dwordx2 v248, v[242:243], s[50:51] nt
	s_add_u32 s38, s38, 0x4000
	s_addc_u32 s39, s39, 0
	v_add_f32_dpp v246, v246, v246 quad_perm:[2,3,0,1] row_mask:0xf bank_mask:0xf
	s_add_u32 s50, s50, 0x2000
	s_addc_u32 s51, s51, 0
	v_add_f32_dpp v246, v246, v246 row_half_mirror row_mask:0xf bank_mask:0xf
	s_nop 1
	v_add_f32_dpp v246, v246, v246 row_mirror row_mask:0xf bank_mask:0xf
	s_mov_b64 exec, s[48:49]
	global_store_dword v249, v246, s[34:35] offset:2816
	s_mov_b64 exec, -1
	s_waitcnt vmcnt(55) lgkmcnt(1)
	v_pk_add_f32 v[200:201], v[228:229], v[200:201]
	v_pk_add_f32 v[202:203], v[230:231], v[202:203]
	v_pk_mul_f32 v[232:233], v[200:201], v[200:201]
	v_pk_mul_f32 v[234:235], v[202:203], v[202:203]
	ds_read_b128 v[228:231], v215 offset:14336
	v_add_f32_e32 v236, v232, v233
	v_add_f32_e32 v236, v234, v236
	v_add_f32_e32 v236, v235, v236
	global_store_dwordx4 v247, v[200:203], s[38:39] nt
	v_cvt_pk_bf16_f32 v232, v200, v201
	v_cvt_pk_bf16_f32 v233, v202, v203
	v_add_f32_dpp v236, v236, v236 quad_perm:[1,0,3,2] row_mask:0xf bank_mask:0xf
	global_store_dwordx2 v248, v[232:233], s[50:51] nt
	s_add_u32 s38, s38, 0x4000
	s_addc_u32 s39, s39, 0
	v_add_f32_dpp v236, v236, v236 quad_perm:[2,3,0,1] row_mask:0xf bank_mask:0xf
	s_add_u32 s50, s50, 0x2000
	s_addc_u32 s51, s51, 0
	v_add_f32_dpp v236, v236, v236 row_half_mirror row_mask:0xf bank_mask:0xf
	s_nop 1
	v_add_f32_dpp v236, v236, v236 row_mirror row_mask:0xf bank_mask:0xf
	s_mov_b64 exec, s[48:49]
	global_store_dword v249, v236, s[34:35] offset:3072
	s_mov_b64 exec, -1
	s_waitcnt vmcnt(57) lgkmcnt(1)
	v_pk_add_f32 v[216:217], v[238:239], v[216:217]
	v_pk_add_f32 v[218:219], v[240:241], v[218:219]
	v_pk_mul_f32 v[242:243], v[216:217], v[216:217]
	v_pk_mul_f32 v[244:245], v[218:219], v[218:219]
	ds_read_b128 v[238:241], v237 offset:15360
	v_add_f32_e32 v246, v242, v243
	v_add_f32_e32 v246, v244, v246
	v_add_f32_e32 v246, v245, v246
	global_store_dwordx4 v247, v[216:219], s[38:39] nt
	v_cvt_pk_bf16_f32 v242, v216, v217
	v_cvt_pk_bf16_f32 v243, v218, v219
	v_add_f32_dpp v246, v246, v246 quad_perm:[1,0,3,2] row_mask:0xf bank_mask:0xf
	global_store_dwordx2 v248, v[242:243], s[50:51] nt
	s_add_u32 s38, s38, 0x4000
	s_addc_u32 s39, s39, 0
	v_add_f32_dpp v246, v246, v246 quad_perm:[2,3,0,1] row_mask:0xf bank_mask:0xf
	s_add_u32 s50, s50, 0x2000
	s_addc_u32 s51, s51, 0
	v_add_f32_dpp v246, v246, v246 row_half_mirror row_mask:0xf bank_mask:0xf
	s_nop 1
	v_add_f32_dpp v246, v246, v246 row_mirror row_mask:0xf bank_mask:0xf
	s_mov_b64 exec, s[48:49]
	global_store_dword v249, v246, s[34:35] offset:3328
	s_mov_b64 exec, -1
	s_waitcnt vmcnt(59) lgkmcnt(1)
	v_pk_add_f32 v[220:221], v[228:229], v[220:221]
	v_pk_add_f32 v[222:223], v[230:231], v[222:223]
	v_pk_mul_f32 v[232:233], v[220:221], v[220:221]
	v_pk_mul_f32 v[234:235], v[222:223], v[222:223]
	v_add_f32_e32 v236, v232, v233
	v_add_f32_e32 v236, v234, v236
	v_add_f32_e32 v236, v235, v236
	global_store_dwordx4 v247, v[220:223], s[38:39] nt
	v_cvt_pk_bf16_f32 v232, v220, v221
	v_cvt_pk_bf16_f32 v233, v222, v223
	v_add_f32_dpp v236, v236, v236 quad_perm:[1,0,3,2] row_mask:0xf bank_mask:0xf
	global_store_dwordx2 v248, v[232:233], s[50:51] nt
	s_add_u32 s38, s38, 0x4000
	s_addc_u32 s39, s39, 0
	v_add_f32_dpp v236, v236, v236 quad_perm:[2,3,0,1] row_mask:0xf bank_mask:0xf
	s_add_u32 s50, s50, 0x2000
	s_addc_u32 s51, s51, 0
	v_add_f32_dpp v236, v236, v236 row_half_mirror row_mask:0xf bank_mask:0xf
	s_nop 1
	v_add_f32_dpp v236, v236, v236 row_mirror row_mask:0xf bank_mask:0xf
	s_mov_b64 exec, s[48:49]
	global_store_dword v249, v236, s[34:35] offset:3584
	s_mov_b64 exec, -1
	s_waitcnt vmcnt(61) lgkmcnt(0)
	v_pk_add_f32 v[224:225], v[238:239], v[224:225]
	v_pk_add_f32 v[226:227], v[240:241], v[226:227]
	v_pk_mul_f32 v[242:243], v[224:225], v[224:225]
	v_pk_mul_f32 v[244:245], v[226:227], v[226:227]
	v_add_f32_e32 v246, v242, v243
	v_add_f32_e32 v246, v244, v246
	v_add_f32_e32 v246, v245, v246
	global_store_dwordx4 v247, v[224:227], s[38:39] nt
	v_cvt_pk_bf16_f32 v242, v224, v225
	v_cvt_pk_bf16_f32 v243, v226, v227
	v_add_f32_dpp v246, v246, v246 quad_perm:[1,0,3,2] row_mask:0xf bank_mask:0xf
	global_store_dwordx2 v248, v[242:243], s[50:51] nt
	s_add_u32 s38, s38, 0x4000
	s_addc_u32 s39, s39, 0
	v_add_f32_dpp v246, v246, v246 quad_perm:[2,3,0,1] row_mask:0xf bank_mask:0xf
	s_add_u32 s50, s50, 0x2000
	s_addc_u32 s51, s51, 0
	v_add_f32_dpp v246, v246, v246 row_half_mirror row_mask:0xf bank_mask:0xf
	s_nop 1
	v_add_f32_dpp v246, v246, v246 row_mirror row_mask:0xf bank_mask:0xf
	s_mov_b64 exec, s[48:49]
	global_store_dword v249, v246, s[34:35] offset:3840
	s_mov_b64 exec, -1
	s_add_u32 s34, s34, 0x1000
	s_addc_u32 s35, s35, 0
	v_and_b32_e32 v238, 15, v198
	v_xor_b32_e32 v238, v238, v199
	v_lshl_add_u32 v239, v198, 8, s40
	v_xor_b32_e32 v228, 0, v238
	v_lshl_add_u32 v228, v228, 4, v239
	v_xor_b32_e32 v229, 2, v238
	v_lshl_add_u32 v229, v229, 4, v239
	v_xor_b32_e32 v230, 4, v238
	v_lshl_add_u32 v230, v230, 4, v239
	v_xor_b32_e32 v231, 6, v238
	v_lshl_add_u32 v231, v231, 4, v239
	v_xor_b32_e32 v232, 8, v238
	v_lshl_add_u32 v232, v232, 4, v239
	v_xor_b32_e32 v233, 10, v238
	v_lshl_add_u32 v233, v233, 4, v239
	v_xor_b32_e32 v234, 12, v238
	v_lshl_add_u32 v234, v234, 4, v239
	v_xor_b32_e32 v235, 14, v238
	v_lshl_add_u32 v235, v235, 4, v239
	ds_write_b128 v228, v[18:21]
	ds_write_b128 v229, v[22:25]
	ds_write_b128 v230, v[26:29]
	ds_write_b128 v231, v[30:33]
	ds_write_b128 v232, v[50:53]
	ds_write_b128 v233, v[54:57]
	ds_write_b128 v234, v[58:61]
	ds_write_b128 v235, v[62:65]
	ds_write_b128 v228, v[2:5] offset:8192
	ds_write_b128 v229, v[6:9] offset:8192
	ds_write_b128 v230, v[10:13] offset:8192
	ds_write_b128 v231, v[14:17] offset:8192
	ds_write_b128 v232, v[34:37] offset:8192
	ds_write_b128 v233, v[38:41] offset:8192
	ds_write_b128 v234, v[42:45] offset:8192
	ds_write_b128 v235, v[46:49] offset:8192
	s_waitcnt lgkmcnt(0)
	ds_read_b128 v[228:231], v210 offset:0
	ds_read_b128 v[238:241], v211 offset:1024
	s_waitcnt vmcnt(63) lgkmcnt(1)
	v_pk_add_f32 v[82:83], v[228:229], v[82:83]
	v_pk_add_f32 v[84:85], v[230:231], v[84:85]
	v_pk_mul_f32 v[232:233], v[82:83], v[82:83]
	v_pk_mul_f32 v[234:235], v[84:85], v[84:85]
	ds_read_b128 v[228:231], v215 offset:2048
	v_add_f32_e32 v236, v232, v233
	v_add_f32_e32 v236, v234, v236
	v_add_f32_e32 v236, v235, v236
	global_store_dwordx4 v247, v[82:85], s[38:39] nt
	v_cvt_pk_bf16_f32 v232, v82, v83
	v_cvt_pk_bf16_f32 v233, v84, v85
	v_add_f32_dpp v236, v236, v236 quad_perm:[1,0,3,2] row_mask:0xf bank_mask:0xf
	global_store_dwordx2 v248, v[232:233], s[50:51] nt
	s_add_u32 s38, s38, 0x4000
	s_addc_u32 s39, s39, 0
	v_add_f32_dpp v236, v236, v236 quad_perm:[2,3,0,1] row_mask:0xf bank_mask:0xf
	s_add_u32 s50, s50, 0x2000
	s_addc_u32 s51, s51, 0
	v_add_f32_dpp v236, v236, v236 row_half_mirror row_mask:0xf bank_mask:0xf
	s_nop 1
	v_add_f32_dpp v236, v236, v236 row_mirror row_mask:0xf bank_mask:0xf
	s_mov_b64 exec, s[48:49]
	global_store_dword v249, v236, s[34:35] offset:0
	s_mov_b64 exec, -1
	s_waitcnt vmcnt(63) lgkmcnt(1)
	v_pk_add_f32 v[86:87], v[238:239], v[86:87]
	v_pk_add_f32 v[88:89], v[240:241], v[88:89]
	v_pk_mul_f32 v[242:243], v[86:87], v[86:87]
	v_pk_mul_f32 v[244:245], v[88:89], v[88:89]
	ds_read_b128 v[238:241], v237 offset:3072
	v_add_f32_e32 v246, v242, v243
	v_add_f32_e32 v246, v244, v246
	v_add_f32_e32 v246, v245, v246
	global_store_dwordx4 v247, v[86:89], s[38:39] nt
	v_cvt_pk_bf16_f32 v242, v86, v87
	v_cvt_pk_bf16_f32 v243, v88, v89
	v_add_f32_dpp v246, v246, v246 quad_perm:[1,0,3,2] row_mask:0xf bank_mask:0xf
	global_store_dwordx2 v248, v[242:243], s[50:51] nt
	s_add_u32 s38, s38, 0x4000
	s_addc_u32 s39, s39, 0
	v_add_f32_dpp v246, v246, v246 quad_perm:[2,3,0,1] row_mask:0xf bank_mask:0xf
	s_add_u32 s50, s50, 0x2000
	s_addc_u32 s51, s51, 0
	v_add_f32_dpp v246, v246, v246 row_half_mirror row_mask:0xf bank_mask:0xf
	s_nop 1
	v_add_f32_dpp v246, v246, v246 row_mirror row_mask:0xf bank_mask:0xf
	s_mov_b64 exec, s[48:49]
	global_store_dword v249, v246, s[34:35] offset:256
	s_mov_b64 exec, -1
	s_waitcnt vmcnt(63) lgkmcnt(1)
	v_pk_add_f32 v[90:91], v[228:229], v[90:91]
	v_pk_add_f32 v[92:93], v[230:231], v[92:93]
	v_pk_mul_f32 v[232:233], v[90:91], v[90:91]
	v_pk_mul_f32 v[234:235], v[92:93], v[92:93]
	ds_read_b128 v[228:231], v210 offset:4096
	v_add_f32_e32 v236, v232, v233
	v_add_f32_e32 v236, v234, v236
	v_add_f32_e32 v236, v235, v236
	global_store_dwordx4 v247, v[90:93], s[38:39] nt
	v_cvt_pk_bf16_f32 v232, v90, v91
	v_cvt_pk_bf16_f32 v233, v92, v93
	v_add_f32_dpp v236, v236, v236 quad_perm:[1,0,3,2] row_mask:0xf bank_mask:0xf
	global_store_dwordx2 v248, v[232:233], s[50:51] nt
	s_add_u32 s38, s38, 0x4000
	s_addc_u32 s39, s39, 0
	v_add_f32_dpp v236, v236, v236 quad_perm:[2,3,0,1] row_mask:0xf bank_mask:0xf
	s_add_u32 s50, s50, 0x2000
	s_addc_u32 s51, s51, 0
	v_add_f32_dpp v236, v236, v236 row_half_mirror row_mask:0xf bank_mask:0xf
	s_nop 1
	v_add_f32_dpp v236, v236, v236 row_mirror row_mask:0xf bank_mask:0xf
	s_mov_b64 exec, s[48:49]
	global_store_dword v249, v236, s[34:35] offset:512
	s_mov_b64 exec, -1
	s_waitcnt vmcnt(63) lgkmcnt(1)
	v_pk_add_f32 v[94:95], v[238:239], v[94:95]
	v_pk_add_f32 v[96:97], v[240:241], v[96:97]
	v_pk_mul_f32 v[242:243], v[94:95], v[94:95]
	v_pk_mul_f32 v[244:245], v[96:97], v[96:97]
	ds_read_b128 v[238:241], v211 offset:5120
	v_add_f32_e32 v246, v242, v243
	v_add_f32_e32 v246, v244, v246
	v_add_f32_e32 v246, v245, v246
	global_store_dwordx4 v247, v[94:97], s[38:39] nt
	v_cvt_pk_bf16_f32 v242, v94, v95
	v_cvt_pk_bf16_f32 v243, v96, v97
	v_add_f32_dpp v246, v246, v246 quad_perm:[1,0,3,2] row_mask:0xf bank_mask:0xf
	global_store_dwordx2 v248, v[242:243], s[50:51] nt
	s_add_u32 s38, s38, 0x4000
	s_addc_u32 s39, s39, 0
	v_add_f32_dpp v246, v246, v246 quad_perm:[2,3,0,1] row_mask:0xf bank_mask:0xf
	s_add_u32 s50, s50, 0x2000
	s_addc_u32 s51, s51, 0
	v_add_f32_dpp v246, v246, v246 row_half_mirror row_mask:0xf bank_mask:0xf
	s_nop 1
	v_add_f32_dpp v246, v246, v246 row_mirror row_mask:0xf bank_mask:0xf
	s_mov_b64 exec, s[48:49]
	global_store_dword v249, v246, s[34:35] offset:768
	s_mov_b64 exec, -1
	s_waitcnt vmcnt(63) lgkmcnt(1)
	v_pk_add_f32 v[114:115], v[228:229], v[114:115]
	v_pk_add_f32 v[116:117], v[230:231], v[116:117]
	v_pk_mul_f32 v[232:233], v[114:115], v[114:115]
	v_pk_mul_f32 v[234:235], v[116:117], v[116:117]
	ds_read_b128 v[228:231], v215 offset:6144
	v_add_f32_e32 v236, v232, v233
	v_add_f32_e32 v236, v234, v236
	v_add_f32_e32 v236, v235, v236
	global_store_dwordx4 v247, v[114:117], s[38:39] nt
	v_cvt_pk_bf16_f32 v232, v114, v115
	v_cvt_pk_bf16_f32 v233, v116, v117
	v_add_f32_dpp v236, v236, v236 quad_perm:[1,0,3,2] row_mask:0xf bank_mask:0xf
	global_store_dwordx2 v248, v[232:233], s[50:51] nt
	s_add_u32 s38, s38, 0x4000
	s_addc_u32 s39, s39, 0
	v_add_f32_dpp v236, v236, v236 quad_perm:[2,3,0,1] row_mask:0xf bank_mask:0xf
	s_add_u32 s50, s50, 0x2000
	s_addc_u32 s51, s51, 0
	v_add_f32_dpp v236, v236, v236 row_half_mirror row_mask:0xf bank_mask:0xf
	s_nop 1
	v_add_f32_dpp v236, v236, v236 row_mirror row_mask:0xf bank_mask:0xf
	s_mov_b64 exec, s[48:49]
	global_store_dword v249, v236, s[34:35] offset:1024
	s_mov_b64 exec, -1
	s_waitcnt vmcnt(63) lgkmcnt(1)
	v_pk_add_f32 v[118:119], v[238:239], v[118:119]
	v_pk_add_f32 v[120:121], v[240:241], v[120:121]
	v_pk_mul_f32 v[242:243], v[118:119], v[118:119]
	v_pk_mul_f32 v[244:245], v[120:121], v[120:121]
	ds_read_b128 v[238:241], v237 offset:7168
	v_add_f32_e32 v246, v242, v243
	v_add_f32_e32 v246, v244, v246
	v_add_f32_e32 v246, v245, v246
	global_store_dwordx4 v247, v[118:121], s[38:39] nt
	v_cvt_pk_bf16_f32 v242, v118, v119
	v_cvt_pk_bf16_f32 v243, v120, v121
	v_add_f32_dpp v246, v246, v246 quad_perm:[1,0,3,2] row_mask:0xf bank_mask:0xf
	global_store_dwordx2 v248, v[242:243], s[50:51] nt
	s_add_u32 s38, s38, 0x4000
	s_addc_u32 s39, s39, 0
	v_add_f32_dpp v246, v246, v246 quad_perm:[2,3,0,1] row_mask:0xf bank_mask:0xf
	s_add_u32 s50, s50, 0x2000
	s_addc_u32 s51, s51, 0
	v_add_f32_dpp v246, v246, v246 row_half_mirror row_mask:0xf bank_mask:0xf
	s_nop 1
	v_add_f32_dpp v246, v246, v246 row_mirror row_mask:0xf bank_mask:0xf
	s_mov_b64 exec, s[48:49]
	global_store_dword v249, v246, s[34:35] offset:1280
	s_mov_b64 exec, -1
	s_waitcnt vmcnt(63) lgkmcnt(1)
	v_pk_add_f32 v[122:123], v[228:229], v[122:123]
	v_pk_add_f32 v[124:125], v[230:231], v[124:125]
	v_pk_mul_f32 v[232:233], v[122:123], v[122:123]
	v_pk_mul_f32 v[234:235], v[124:125], v[124:125]
	ds_read_b128 v[228:231], v210 offset:8192
	v_add_f32_e32 v236, v232, v233
	v_add_f32_e32 v236, v234, v236
	v_add_f32_e32 v236, v235, v236
	global_store_dwordx4 v247, v[122:125], s[38:39] nt
	v_cvt_pk_bf16_f32 v232, v122, v123
	v_cvt_pk_bf16_f32 v233, v124, v125
	v_add_f32_dpp v236, v236, v236 quad_perm:[1,0,3,2] row_mask:0xf bank_mask:0xf
	global_store_dwordx2 v248, v[232:233], s[50:51] nt
	s_add_u32 s38, s38, 0x4000
	s_addc_u32 s39, s39, 0
	v_add_f32_dpp v236, v236, v236 quad_perm:[2,3,0,1] row_mask:0xf bank_mask:0xf
	s_add_u32 s50, s50, 0x2000
	s_addc_u32 s51, s51, 0
	v_add_f32_dpp v236, v236, v236 row_half_mirror row_mask:0xf bank_mask:0xf
	s_nop 1
	v_add_f32_dpp v236, v236, v236 row_mirror row_mask:0xf bank_mask:0xf
	s_mov_b64 exec, s[48:49]
	global_store_dword v249, v236, s[34:35] offset:1536
	s_mov_b64 exec, -1
	s_waitcnt vmcnt(63) lgkmcnt(1)
	v_pk_add_f32 v[126:127], v[238:239], v[126:127]
	v_pk_add_f32 v[128:129], v[240:241], v[128:129]
	v_pk_mul_f32 v[242:243], v[126:127], v[126:127]
	v_pk_mul_f32 v[244:245], v[128:129], v[128:129]
	ds_read_b128 v[238:241], v211 offset:9216
	v_add_f32_e32 v246, v242, v243
	v_add_f32_e32 v246, v244, v246
	v_add_f32_e32 v246, v245, v246
	global_store_dwordx4 v247, v[126:129], s[38:39] nt
	v_cvt_pk_bf16_f32 v242, v126, v127
	v_cvt_pk_bf16_f32 v243, v128, v129
	v_add_f32_dpp v246, v246, v246 quad_perm:[1,0,3,2] row_mask:0xf bank_mask:0xf
	global_store_dwordx2 v248, v[242:243], s[50:51] nt
	s_add_u32 s38, s38, 0x4000
	s_addc_u32 s39, s39, 0
	v_add_f32_dpp v246, v246, v246 quad_perm:[2,3,0,1] row_mask:0xf bank_mask:0xf
	s_add_u32 s50, s50, 0x2000
	s_addc_u32 s51, s51, 0
	v_add_f32_dpp v246, v246, v246 row_half_mirror row_mask:0xf bank_mask:0xf
	s_nop 1
	v_add_f32_dpp v246, v246, v246 row_mirror row_mask:0xf bank_mask:0xf
	s_mov_b64 exec, s[48:49]
	global_store_dword v249, v246, s[34:35] offset:1792
	s_mov_b64 exec, -1
	s_waitcnt vmcnt(63) lgkmcnt(1)
	v_pk_add_f32 v[66:67], v[228:229], v[66:67]
	v_pk_add_f32 v[68:69], v[230:231], v[68:69]
	v_pk_mul_f32 v[232:233], v[66:67], v[66:67]
	v_pk_mul_f32 v[234:235], v[68:69], v[68:69]
	ds_read_b128 v[228:231], v215 offset:10240
	v_add_f32_e32 v236, v232, v233
	v_add_f32_e32 v236, v234, v236
	v_add_f32_e32 v236, v235, v236
	global_store_dwordx4 v247, v[66:69], s[38:39] nt
	v_cvt_pk_bf16_f32 v232, v66, v67
	v_cvt_pk_bf16_f32 v233, v68, v69
	v_add_f32_dpp v236, v236, v236 quad_perm:[1,0,3,2] row_mask:0xf bank_mask:0xf
	global_store_dwordx2 v248, v[232:233], s[50:51] nt
	s_add_u32 s38, s38, 0x4000
	s_addc_u32 s39, s39, 0
	v_add_f32_dpp v236, v236, v236 quad_perm:[2,3,0,1] row_mask:0xf bank_mask:0xf
	s_add_u32 s50, s50, 0x2000
	s_addc_u32 s51, s51, 0
	v_add_f32_dpp v236, v236, v236 row_half_mirror row_mask:0xf bank_mask:0xf
	s_nop 1
	v_add_f32_dpp v236, v236, v236 row_mirror row_mask:0xf bank_mask:0xf
	s_mov_b64 exec, s[48:49]
	global_store_dword v249, v236, s[34:35] offset:2048
	s_mov_b64 exec, -1
	s_waitcnt vmcnt(63) lgkmcnt(1)
	v_pk_add_f32 v[70:71], v[238:239], v[70:71]
	v_pk_add_f32 v[72:73], v[240:241], v[72:73]
	v_pk_mul_f32 v[242:243], v[70:71], v[70:71]
	v_pk_mul_f32 v[244:245], v[72:73], v[72:73]
	ds_read_b128 v[238:241], v237 offset:11264
	v_add_f32_e32 v246, v242, v243
	v_add_f32_e32 v246, v244, v246
	v_add_f32_e32 v246, v245, v246
	global_store_dwordx4 v247, v[70:73], s[38:39] nt
	v_cvt_pk_bf16_f32 v242, v70, v71
	v_cvt_pk_bf16_f32 v243, v72, v73
	v_add_f32_dpp v246, v246, v246 quad_perm:[1,0,3,2] row_mask:0xf bank_mask:0xf
	global_store_dwordx2 v248, v[242:243], s[50:51] nt
	s_add_u32 s38, s38, 0x4000
	s_addc_u32 s39, s39, 0
	v_add_f32_dpp v246, v246, v246 quad_perm:[2,3,0,1] row_mask:0xf bank_mask:0xf
	s_add_u32 s50, s50, 0x2000
	s_addc_u32 s51, s51, 0
	v_add_f32_dpp v246, v246, v246 row_half_mirror row_mask:0xf bank_mask:0xf
	s_nop 1
	v_add_f32_dpp v246, v246, v246 row_mirror row_mask:0xf bank_mask:0xf
	s_mov_b64 exec, s[48:49]
	global_store_dword v249, v246, s[34:35] offset:2304
	s_mov_b64 exec, -1
	s_waitcnt vmcnt(63) lgkmcnt(1)
	v_pk_add_f32 v[74:75], v[228:229], v[74:75]
	v_pk_add_f32 v[76:77], v[230:231], v[76:77]
	v_pk_mul_f32 v[232:233], v[74:75], v[74:75]
	v_pk_mul_f32 v[234:235], v[76:77], v[76:77]
	ds_read_b128 v[228:231], v210 offset:12288
	v_add_f32_e32 v236, v232, v233
	v_add_f32_e32 v236, v234, v236
	v_add_f32_e32 v236, v235, v236
	global_store_dwordx4 v247, v[74:77], s[38:39] nt
	v_cvt_pk_bf16_f32 v232, v74, v75
	v_cvt_pk_bf16_f32 v233, v76, v77
	v_add_f32_dpp v236, v236, v236 quad_perm:[1,0,3,2] row_mask:0xf bank_mask:0xf
	global_store_dwordx2 v248, v[232:233], s[50:51] nt
	s_add_u32 s38, s38, 0x4000
	s_addc_u32 s39, s39, 0
	v_add_f32_dpp v236, v236, v236 quad_perm:[2,3,0,1] row_mask:0xf bank_mask:0xf
	s_add_u32 s50, s50, 0x2000
	s_addc_u32 s51, s51, 0
	v_add_f32_dpp v236, v236, v236 row_half_mirror row_mask:0xf bank_mask:0xf
	s_nop 1
	v_add_f32_dpp v236, v236, v236 row_mirror row_mask:0xf bank_mask:0xf
	s_mov_b64 exec, s[48:49]
	global_store_dword v249, v236, s[34:35] offset:2560
	s_mov_b64 exec, -1
	s_waitcnt vmcnt(63) lgkmcnt(1)
	v_pk_add_f32 v[78:79], v[238:239], v[78:79]
	v_pk_add_f32 v[80:81], v[240:241], v[80:81]
	v_pk_mul_f32 v[242:243], v[78:79], v[78:79]
	v_pk_mul_f32 v[244:245], v[80:81], v[80:81]
	ds_read_b128 v[238:241], v211 offset:13312
	v_add_f32_e32 v246, v242, v243
	v_add_f32_e32 v246, v244, v246
	v_add_f32_e32 v246, v245, v246
	global_store_dwordx4 v247, v[78:81], s[38:39] nt
	v_cvt_pk_bf16_f32 v242, v78, v79
	v_cvt_pk_bf16_f32 v243, v80, v81
	v_add_f32_dpp v246, v246, v246 quad_perm:[1,0,3,2] row_mask:0xf bank_mask:0xf
	global_store_dwordx2 v248, v[242:243], s[50:51] nt
	s_add_u32 s38, s38, 0x4000
	s_addc_u32 s39, s39, 0
	v_add_f32_dpp v246, v246, v246 quad_perm:[2,3,0,1] row_mask:0xf bank_mask:0xf
	s_add_u32 s50, s50, 0x2000
	s_addc_u32 s51, s51, 0
	v_add_f32_dpp v246, v246, v246 row_half_mirror row_mask:0xf bank_mask:0xf
	s_nop 1
	v_add_f32_dpp v246, v246, v246 row_mirror row_mask:0xf bank_mask:0xf
	s_mov_b64 exec, s[48:49]
	global_store_dword v249, v246, s[34:35] offset:2816
	s_mov_b64 exec, -1
	s_waitcnt vmcnt(63) lgkmcnt(1)
	v_pk_add_f32 v[98:99], v[228:229], v[98:99]
	v_pk_add_f32 v[100:101], v[230:231], v[100:101]
	v_pk_mul_f32 v[232:233], v[98:99], v[98:99]
	v_pk_mul_f32 v[234:235], v[100:101], v[100:101]
	ds_read_b128 v[228:231], v215 offset:14336
	v_add_f32_e32 v236, v232, v233
	v_add_f32_e32 v236, v234, v236
	v_add_f32_e32 v236, v235, v236
	global_store_dwordx4 v247, v[98:101], s[38:39] nt
	v_cvt_pk_bf16_f32 v232, v98, v99
	v_cvt_pk_bf16_f32 v233, v100, v101
	v_add_f32_dpp v236, v236, v236 quad_perm:[1,0,3,2] row_mask:0xf bank_mask:0xf
	global_store_dwordx2 v248, v[232:233], s[50:51] nt
	s_add_u32 s38, s38, 0x4000
	s_addc_u32 s39, s39, 0
	v_add_f32_dpp v236, v236, v236 quad_perm:[2,3,0,1] row_mask:0xf bank_mask:0xf
	s_add_u32 s50, s50, 0x2000
	s_addc_u32 s51, s51, 0
	v_add_f32_dpp v236, v236, v236 row_half_mirror row_mask:0xf bank_mask:0xf
	s_nop 1
	v_add_f32_dpp v236, v236, v236 row_mirror row_mask:0xf bank_mask:0xf
	s_mov_b64 exec, s[48:49]
	global_store_dword v249, v236, s[34:35] offset:3072
	s_mov_b64 exec, -1
	s_waitcnt vmcnt(63) lgkmcnt(1)
	v_pk_add_f32 v[102:103], v[238:239], v[102:103]
	v_pk_add_f32 v[104:105], v[240:241], v[104:105]
	v_pk_mul_f32 v[242:243], v[102:103], v[102:103]
	v_pk_mul_f32 v[244:245], v[104:105], v[104:105]
	ds_read_b128 v[238:241], v237 offset:15360
	v_add_f32_e32 v246, v242, v243
	v_add_f32_e32 v246, v244, v246
	v_add_f32_e32 v246, v245, v246
	global_store_dwordx4 v247, v[102:105], s[38:39] nt
	v_cvt_pk_bf16_f32 v242, v102, v103
	v_cvt_pk_bf16_f32 v243, v104, v105
	v_add_f32_dpp v246, v246, v246 quad_perm:[1,0,3,2] row_mask:0xf bank_mask:0xf
	global_store_dwordx2 v248, v[242:243], s[50:51] nt
	s_add_u32 s38, s38, 0x4000
	s_addc_u32 s39, s39, 0
	v_add_f32_dpp v246, v246, v246 quad_perm:[2,3,0,1] row_mask:0xf bank_mask:0xf
	s_add_u32 s50, s50, 0x2000
	s_addc_u32 s51, s51, 0
	v_add_f32_dpp v246, v246, v246 row_half_mirror row_mask:0xf bank_mask:0xf
	s_nop 1
	v_add_f32_dpp v246, v246, v246 row_mirror row_mask:0xf bank_mask:0xf
	s_mov_b64 exec, s[48:49]
	global_store_dword v249, v246, s[34:35] offset:3328
	s_mov_b64 exec, -1
	s_waitcnt vmcnt(63) lgkmcnt(1)
	v_pk_add_f32 v[106:107], v[228:229], v[106:107]
	v_pk_add_f32 v[108:109], v[230:231], v[108:109]
	v_pk_mul_f32 v[232:233], v[106:107], v[106:107]
	v_pk_mul_f32 v[234:235], v[108:109], v[108:109]
	v_add_f32_e32 v236, v232, v233
	v_add_f32_e32 v236, v234, v236
	v_add_f32_e32 v236, v235, v236
	global_store_dwordx4 v247, v[106:109], s[38:39] nt
	v_cvt_pk_bf16_f32 v232, v106, v107
	v_cvt_pk_bf16_f32 v233, v108, v109
	v_add_f32_dpp v236, v236, v236 quad_perm:[1,0,3,2] row_mask:0xf bank_mask:0xf
	global_store_dwordx2 v248, v[232:233], s[50:51] nt
	s_add_u32 s38, s38, 0x4000
	s_addc_u32 s39, s39, 0
	v_add_f32_dpp v236, v236, v236 quad_perm:[2,3,0,1] row_mask:0xf bank_mask:0xf
	s_add_u32 s50, s50, 0x2000
	s_addc_u32 s51, s51, 0
	v_add_f32_dpp v236, v236, v236 row_half_mirror row_mask:0xf bank_mask:0xf
	s_nop 1
	v_add_f32_dpp v236, v236, v236 row_mirror row_mask:0xf bank_mask:0xf
	s_mov_b64 exec, s[48:49]
	global_store_dword v249, v236, s[34:35] offset:3584
	s_mov_b64 exec, -1
	s_waitcnt vmcnt(63) lgkmcnt(0)
	v_pk_add_f32 v[110:111], v[238:239], v[110:111]
	v_pk_add_f32 v[112:113], v[240:241], v[112:113]
	v_pk_mul_f32 v[242:243], v[110:111], v[110:111]
	v_pk_mul_f32 v[244:245], v[112:113], v[112:113]
	v_add_f32_e32 v246, v242, v243
	v_add_f32_e32 v246, v244, v246
	v_add_f32_e32 v246, v245, v246
	global_store_dwordx4 v247, v[110:113], s[38:39] nt
	v_cvt_pk_bf16_f32 v242, v110, v111
	v_cvt_pk_bf16_f32 v243, v112, v113
	v_add_f32_dpp v246, v246, v246 quad_perm:[1,0,3,2] row_mask:0xf bank_mask:0xf
	global_store_dwordx2 v248, v[242:243], s[50:51] nt
	s_add_u32 s38, s38, 0x4000
	s_addc_u32 s39, s39, 0
	v_add_f32_dpp v246, v246, v246 quad_perm:[2,3,0,1] row_mask:0xf bank_mask:0xf
	s_add_u32 s50, s50, 0x2000
	s_addc_u32 s51, s51, 0
	v_add_f32_dpp v246, v246, v246 row_half_mirror row_mask:0xf bank_mask:0xf
	s_nop 1
	v_add_f32_dpp v246, v246, v246 row_mirror row_mask:0xf bank_mask:0xf
	s_mov_b64 exec, s[48:49]
	global_store_dword v249, v246, s[34:35] offset:3840
	s_mov_b64 exec, -1
	s_waitcnt lgkmcnt(0)
	s_branch .LBB0_1507

.LBB0_1696:
	v_readlane_b32 s40, v251, 47
	s_nop 0
	s_cmp_eq_u32 s40, 3
	s_cbranch_scc1 .Lres_mlp2_last
	v_readfirstlane_b32 s40, v204
	s_lshr_b32 s40, s40, 6
	s_and_b32 s41, s40, 1
	s_bfe_u32 s42, s40, 0x10001
	s_lshr_b32 s43, s40, 2
	s_lshl_b32 s44, s4, 1
	s_add_i32 s44, s44, s42
	s_lshl_b32 s45, s44, 7
	s_lshl_b32 s46, s41, 6
	s_add_i32 s45, s45, s46
	s_lshl_b32 s46, s43, 7
	s_add_i32 s46, s46, s2
	s_lshl_b32 s47, s44, 1
	s_add_i32 s47, s47, s41
	v_readlane_b32 s36, v250, 9
	v_readlane_b32 s37, v250, 10
	s_mov_b64 s[38:39], s[36:37]
	v_readlane_b32 s50, v250, 11
	v_readlane_b32 s51, v250, 12
	s_add_u32 s34, s50, 0xf900000
	s_addc_u32 s35, s51, 0
	s_add_u32 s50, s50, 0x5800000
	s_addc_u32 s51, s51, 0
	s_lshl_b32 s48, s46, 12
	s_lshl_b32 s49, s45, 2
	s_add_u32 s48, s48, s49
	s_add_u32 s36, s36, s48
	s_addc_u32 s37, s37, 0
	s_add_u32 s38, s38, s48
	s_addc_u32 s39, s39, 0
	s_lshr_b32 s48, s48, 1
	s_add_u32 s50, s50, s48
	s_addc_u32 s51, s51, 0
	s_lshl_b32 s48, s46, 6
	s_lshl_b32 s49, s47, 2
	s_add_u32 s48, s48, s49
	s_add_u32 s34, s34, s48
	s_addc_u32 s35, s35, 0
	v_and_b32_e32 v249, 63, v204
	v_and_b32_e32 v170, 31, v249
	v_lshrrev_b32_e32 v171, 5, v249
	v_and_b32_e32 v208, 15, v249
	v_lshrrev_b32_e32 v209, 4, v249
	s_lshl_b32 s40, s40, 14
	v_and_b32_e32 v238, 15, v170
	v_xor_b32_e32 v238, v238, v171
	v_lshl_add_u32 v239, v170, 8, s40
	v_xor_b32_e32 v228, 0, v238
	v_lshl_add_u32 v228, v228, 4, v239
	v_xor_b32_e32 v229, 2, v238
	v_lshl_add_u32 v229, v229, 4, v239
	v_xor_b32_e32 v230, 4, v238
	v_lshl_add_u32 v230, v230, 4, v239
	v_xor_b32_e32 v231, 6, v238
	v_lshl_add_u32 v231, v231, 4, v239
	v_xor_b32_e32 v232, 8, v238
	v_lshl_add_u32 v232, v232, 4, v239
	v_xor_b32_e32 v233, 10, v238
	v_lshl_add_u32 v233, v233, 4, v239
	v_xor_b32_e32 v234, 12, v238
	v_lshl_add_u32 v234, v234, 4, v239
	v_xor_b32_e32 v235, 14, v238
	v_lshl_add_u32 v235, v235, 4, v239
	v_lshl_add_u32 v239, v209, 8, s40
	v_add_u32_e32 v210, 0, v209
	v_xor_b32_e32 v210, v210, v208
	v_lshl_add_u32 v210, v210, 4, v239
	v_add_u32_e32 v211, 4, v209
	v_xor_b32_e32 v211, v211, v208
	v_lshl_add_u32 v211, v211, 4, v239
	v_add_u32_e32 v215, 8, v209
	v_xor_b32_e32 v215, v215, v208
	v_lshl_add_u32 v215, v215, 4, v239
	v_add_u32_e32 v237, 12, v209
	v_xor_b32_e32 v237, v237, v208
	v_lshl_add_u32 v237, v237, 4, v239
	v_lshlrev_b32_e32 v247, 12, v209
	v_lshl_add_u32 v247, v208, 4, v247
	v_lshrrev_b32_e32 v248, 1, v247
	v_lshlrev_b32_e32 v249, 6, v209
	s_mov_b32 s48, 0x00010001
	s_mov_b32 s49, 0x00010001
	global_load_dwordx4 v[130:133], v247, s[36:37]
	s_add_u32 s36, s36, 0x4000
	s_addc_u32 s37, s37, 0
	global_load_dwordx4 v[134:137], v247, s[36:37]
	s_add_u32 s36, s36, 0x4000
	s_addc_u32 s37, s37, 0
	global_load_dwordx4 v[138:141], v247, s[36:37]
	s_add_u32 s36, s36, 0x4000
	s_addc_u32 s37, s37, 0
	global_load_dwordx4 v[142:145], v247, s[36:37]
	s_add_u32 s36, s36, 0x4000
	s_addc_u32 s37, s37, 0
	global_load_dwordx4 v[146:149], v247, s[36:37]
	s_add_u32 s36, s36, 0x4000
	s_addc_u32 s37, s37, 0
	global_load_dwordx4 v[150:153], v247, s[36:37]
	s_add_u32 s36, s36, 0x4000
	s_addc_u32 s37, s37, 0
	global_load_dwordx4 v[154:157], v247, s[36:37]
	s_add_u32 s36, s36, 0x4000
	s_addc_u32 s37, s37, 0
	global_load_dwordx4 v[158:161], v247, s[36:37]
	s_add_u32 s36, s36, 0x4000
	s_addc_u32 s37, s37, 0
	global_load_dwordx4 v[162:165], v247, s[36:37]
	s_add_u32 s36, s36, 0x4000
	s_addc_u32 s37, s37, 0
	global_load_dwordx4 v[166:169], v247, s[36:37]
	s_add_u32 s36, s36, 0x4000
	s_addc_u32 s37, s37, 0
	global_load_dwordx4 v[192:195], v247, s[36:37]
	s_add_u32 s36, s36, 0x4000
	s_addc_u32 s37, s37, 0
	global_load_dwordx4 v[196:199], v247, s[36:37]
	s_add_u32 s36, s36, 0x4000
	s_addc_u32 s37, s37, 0
	global_load_dwordx4 v[200:203], v247, s[36:37]
	s_add_u32 s36, s36, 0x4000
	s_addc_u32 s37, s37, 0
	global_load_dwordx4 v[216:219], v247, s[36:37]
	s_add_u32 s36, s36, 0x4000
	s_addc_u32 s37, s37, 0
	global_load_dwordx4 v[220:223], v247, s[36:37]
	s_add_u32 s36, s36, 0x4000
	s_addc_u32 s37, s37, 0
	global_load_dwordx4 v[224:227], v247, s[36:37]
	s_add_u32 s36, s36, 0x4000
	s_addc_u32 s37, s37, 0
	ds_write_b128 v228, v[66:69]
	ds_write_b128 v229, v[70:73]
	ds_write_b128 v230, v[74:77]
	ds_write_b128 v231, v[78:81]
	ds_write_b128 v232, v[114:117]
	ds_write_b128 v233, v[118:121]
	ds_write_b128 v234, v[122:125]
	ds_write_b128 v235, v[126:129]
	ds_write_b128 v228, v[82:85] offset:8192
	ds_write_b128 v229, v[86:89] offset:8192
	ds_write_b128 v230, v[90:93] offset:8192
	ds_write_b128 v231, v[94:97] offset:8192
	ds_write_b128 v232, v[98:101] offset:8192
	ds_write_b128 v233, v[102:105] offset:8192
	ds_write_b128 v234, v[106:109] offset:8192
	ds_write_b128 v235, v[110:113] offset:8192
	global_load_dwordx4 v[66:69], v247, s[36:37]
	s_add_u32 s36, s36, 0x4000
	s_addc_u32 s37, s37, 0
	global_load_dwordx4 v[70:73], v247, s[36:37]
	s_add_u32 s36, s36, 0x4000
	s_addc_u32 s37, s37, 0
	global_load_dwordx4 v[74:77], v247, s[36:37]
	s_add_u32 s36, s36, 0x4000
	s_addc_u32 s37, s37, 0
	global_load_dwordx4 v[78:81], v247, s[36:37]
	s_add_u32 s36, s36, 0x4000
	s_addc_u32 s37, s37, 0
	global_load_dwordx4 v[114:117], v247, s[36:37]
	s_add_u32 s36, s36, 0x4000
	s_addc_u32 s37, s37, 0
	global_load_dwordx4 v[118:121], v247, s[36:37]
	s_add_u32 s36, s36, 0x4000
	s_addc_u32 s37, s37, 0
	global_load_dwordx4 v[122:125], v247, s[36:37]
	s_add_u32 s36, s36, 0x4000
	s_addc_u32 s37, s37, 0
	global_load_dwordx4 v[126:129], v247, s[36:37]
	s_add_u32 s36, s36, 0x4000
	s_addc_u32 s37, s37, 0
	global_load_dwordx4 v[82:85], v247, s[36:37]
	s_add_u32 s36, s36, 0x4000
	s_addc_u32 s37, s37, 0
	global_load_dwordx4 v[86:89], v247, s[36:37]
	s_add_u32 s36, s36, 0x4000
	s_addc_u32 s37, s37, 0
	global_load_dwordx4 v[90:93], v247, s[36:37]
	s_add_u32 s36, s36, 0x4000
	s_addc_u32 s37, s37, 0
	global_load_dwordx4 v[94:97], v247, s[36:37]
	s_add_u32 s36, s36, 0x4000
	s_addc_u32 s37, s37, 0
	global_load_dwordx4 v[98:101], v247, s[36:37]
	s_add_u32 s36, s36, 0x4000
	s_addc_u32 s37, s37, 0
	global_load_dwordx4 v[102:105], v247, s[36:37]
	s_add_u32 s36, s36, 0x4000
	s_addc_u32 s37, s37, 0
	global_load_dwordx4 v[106:109], v247, s[36:37]
	s_add_u32 s36, s36, 0x4000
	s_addc_u32 s37, s37, 0
	global_load_dwordx4 v[110:113], v247, s[36:37]
	s_add_u32 s36, s36, 0x4000
	s_addc_u32 s37, s37, 0
	s_waitcnt lgkmcnt(0)
	ds_read_b128 v[228:231], v210 offset:0
	ds_read_b128 v[238:241], v211 offset:1024
	s_waitcnt vmcnt(31) lgkmcnt(1)
	v_pk_add_f32 v[130:131], v[228:229], v[130:131]
	v_pk_add_f32 v[132:133], v[230:231], v[132:133]
	v_pk_mul_f32 v[232:233], v[130:131], v[130:131]
	v_pk_mul_f32 v[234:235], v[132:133], v[132:133]
	ds_read_b128 v[228:231], v215 offset:2048
	v_add_f32_e32 v236, v232, v233
	v_add_f32_e32 v236, v234, v236
	v_add_f32_e32 v236, v235, v236
	global_store_dwordx4 v247, v[130:133], s[38:39] nt
	v_cvt_pk_bf16_f32 v232, v130, v131
	v_cvt_pk_bf16_f32 v233, v132, v133
	v_add_f32_dpp v236, v236, v236 quad_perm:[1,0,3,2] row_mask:0xf bank_mask:0xf
	global_store_dwordx2 v248, v[232:233], s[50:51] nt
	s_add_u32 s38, s38, 0x4000
	s_addc_u32 s39, s39, 0
	v_add_f32_dpp v236, v236, v236 quad_perm:[2,3,0,1] row_mask:0xf bank_mask:0xf
	s_add_u32 s50, s50, 0x2000
	s_addc_u32 s51, s51, 0
	v_add_f32_dpp v236, v236, v236 row_half_mirror row_mask:0xf bank_mask:0xf
	s_nop 1
	v_add_f32_dpp v236, v236, v236 row_mirror row_mask:0xf bank_mask:0xf
	s_mov_b64 exec, s[48:49]
	global_store_dword v249, v236, s[34:35] offset:0
	s_mov_b64 exec, -1
	s_waitcnt vmcnt(33) lgkmcnt(1)
	v_pk_add_f32 v[134:135], v[238:239], v[134:135]
	v_pk_add_f32 v[136:137], v[240:241], v[136:137]
	v_pk_mul_f32 v[242:243], v[134:135], v[134:135]
	v_pk_mul_f32 v[244:245], v[136:137], v[136:137]
	ds_read_b128 v[238:241], v237 offset:3072
	v_add_f32_e32 v246, v242, v243
	v_add_f32_e32 v246, v244, v246
	v_add_f32_e32 v246, v245, v246
	global_store_dwordx4 v247, v[134:137], s[38:39] nt
	v_cvt_pk_bf16_f32 v242, v134, v135
	v_cvt_pk_bf16_f32 v243, v136, v137
	v_add_f32_dpp v246, v246, v246 quad_perm:[1,0,3,2] row_mask:0xf bank_mask:0xf
	global_store_dwordx2 v248, v[242:243], s[50:51] nt
	s_add_u32 s38, s38, 0x4000
	s_addc_u32 s39, s39, 0
	v_add_f32_dpp v246, v246, v246 quad_perm:[2,3,0,1] row_mask:0xf bank_mask:0xf
	s_add_u32 s50, s50, 0x2000
	s_addc_u32 s51, s51, 0
	v_add_f32_dpp v246, v246, v246 row_half_mirror row_mask:0xf bank_mask:0xf
	s_nop 1
	v_add_f32_dpp v246, v246, v246 row_mirror row_mask:0xf bank_mask:0xf
	s_mov_b64 exec, s[48:49]
	global_store_dword v249, v246, s[34:35] offset:256
	s_mov_b64 exec, -1
	s_waitcnt vmcnt(35) lgkmcnt(1)
	v_pk_add_f32 v[138:139], v[228:229], v[138:139]
	v_pk_add_f32 v[140:141], v[230:231], v[140:141]
	v_pk_mul_f32 v[232:233], v[138:139], v[138:139]
	v_pk_mul_f32 v[234:235], v[140:141], v[140:141]
	ds_read_b128 v[228:231], v210 offset:4096
	v_add_f32_e32 v236, v232, v233
	v_add_f32_e32 v236, v234, v236
	v_add_f32_e32 v236, v235, v236
	global_store_dwordx4 v247, v[138:141], s[38:39] nt
	v_cvt_pk_bf16_f32 v232, v138, v139
	v_cvt_pk_bf16_f32 v233, v140, v141
	v_add_f32_dpp v236, v236, v236 quad_perm:[1,0,3,2] row_mask:0xf bank_mask:0xf
	global_store_dwordx2 v248, v[232:233], s[50:51] nt
	s_add_u32 s38, s38, 0x4000
	s_addc_u32 s39, s39, 0
	v_add_f32_dpp v236, v236, v236 quad_perm:[2,3,0,1] row_mask:0xf bank_mask:0xf
	s_add_u32 s50, s50, 0x2000
	s_addc_u32 s51, s51, 0
	v_add_f32_dpp v236, v236, v236 row_half_mirror row_mask:0xf bank_mask:0xf
	s_nop 1
	v_add_f32_dpp v236, v236, v236 row_mirror row_mask:0xf bank_mask:0xf
	s_mov_b64 exec, s[48:49]
	global_store_dword v249, v236, s[34:35] offset:512
	s_mov_b64 exec, -1
	s_waitcnt vmcnt(37) lgkmcnt(1)
	v_pk_add_f32 v[142:143], v[238:239], v[142:143]
	v_pk_add_f32 v[144:145], v[240:241], v[144:145]
	v_pk_mul_f32 v[242:243], v[142:143], v[142:143]
	v_pk_mul_f32 v[244:245], v[144:145], v[144:145]
	ds_read_b128 v[238:241], v211 offset:5120
	v_add_f32_e32 v246, v242, v243
	v_add_f32_e32 v246, v244, v246
	v_add_f32_e32 v246, v245, v246
	global_store_dwordx4 v247, v[142:145], s[38:39] nt
	v_cvt_pk_bf16_f32 v242, v142, v143
	v_cvt_pk_bf16_f32 v243, v144, v145
	v_add_f32_dpp v246, v246, v246 quad_perm:[1,0,3,2] row_mask:0xf bank_mask:0xf
	global_store_dwordx2 v248, v[242:243], s[50:51] nt
	s_add_u32 s38, s38, 0x4000
	s_addc_u32 s39, s39, 0
	v_add_f32_dpp v246, v246, v246 quad_perm:[2,3,0,1] row_mask:0xf bank_mask:0xf
	s_add_u32 s50, s50, 0x2000
	s_addc_u32 s51, s51, 0
	v_add_f32_dpp v246, v246, v246 row_half_mirror row_mask:0xf bank_mask:0xf
	s_nop 1
	v_add_f32_dpp v246, v246, v246 row_mirror row_mask:0xf bank_mask:0xf
	s_mov_b64 exec, s[48:49]
	global_store_dword v249, v246, s[34:35] offset:768
	s_mov_b64 exec, -1
	s_waitcnt vmcnt(39) lgkmcnt(1)
	v_pk_add_f32 v[146:147], v[228:229], v[146:147]
	v_pk_add_f32 v[148:149], v[230:231], v[148:149]
	v_pk_mul_f32 v[232:233], v[146:147], v[146:147]
	v_pk_mul_f32 v[234:235], v[148:149], v[148:149]
	ds_read_b128 v[228:231], v215 offset:6144
	v_add_f32_e32 v236, v232, v233
	v_add_f32_e32 v236, v234, v236
	v_add_f32_e32 v236, v235, v236
	global_store_dwordx4 v247, v[146:149], s[38:39] nt
	v_cvt_pk_bf16_f32 v232, v146, v147
	v_cvt_pk_bf16_f32 v233, v148, v149
	v_add_f32_dpp v236, v236, v236 quad_perm:[1,0,3,2] row_mask:0xf bank_mask:0xf
	global_store_dwordx2 v248, v[232:233], s[50:51] nt
	s_add_u32 s38, s38, 0x4000
	s_addc_u32 s39, s39, 0
	v_add_f32_dpp v236, v236, v236 quad_perm:[2,3,0,1] row_mask:0xf bank_mask:0xf
	s_add_u32 s50, s50, 0x2000
	s_addc_u32 s51, s51, 0
	v_add_f32_dpp v236, v236, v236 row_half_mirror row_mask:0xf bank_mask:0xf
	s_nop 1
	v_add_f32_dpp v236, v236, v236 row_mirror row_mask:0xf bank_mask:0xf
	s_mov_b64 exec, s[48:49]
	global_store_dword v249, v236, s[34:35] offset:1024
	s_mov_b64 exec, -1
	s_waitcnt vmcnt(41) lgkmcnt(1)
	v_pk_add_f32 v[150:151], v[238:239], v[150:151]
	v_pk_add_f32 v[152:153], v[240:241], v[152:153]
	v_pk_mul_f32 v[242:243], v[150:151], v[150:151]
	v_pk_mul_f32 v[244:245], v[152:153], v[152:153]
	ds_read_b128 v[238:241], v237 offset:7168
	v_add_f32_e32 v246, v242, v243
	v_add_f32_e32 v246, v244, v246
	v_add_f32_e32 v246, v245, v246
	global_store_dwordx4 v247, v[150:153], s[38:39] nt
	v_cvt_pk_bf16_f32 v242, v150, v151
	v_cvt_pk_bf16_f32 v243, v152, v153
	v_add_f32_dpp v246, v246, v246 quad_perm:[1,0,3,2] row_mask:0xf bank_mask:0xf
	global_store_dwordx2 v248, v[242:243], s[50:51] nt
	s_add_u32 s38, s38, 0x4000
	s_addc_u32 s39, s39, 0
	v_add_f32_dpp v246, v246, v246 quad_perm:[2,3,0,1] row_mask:0xf bank_mask:0xf
	s_add_u32 s50, s50, 0x2000
	s_addc_u32 s51, s51, 0
	v_add_f32_dpp v246, v246, v246 row_half_mirror row_mask:0xf bank_mask:0xf
	s_nop 1
	v_add_f32_dpp v246, v246, v246 row_mirror row_mask:0xf bank_mask:0xf
	s_mov_b64 exec, s[48:49]
	global_store_dword v249, v246, s[34:35] offset:1280
	s_mov_b64 exec, -1
	s_waitcnt vmcnt(43) lgkmcnt(1)
	v_pk_add_f32 v[154:155], v[228:229], v[154:155]
	v_pk_add_f32 v[156:157], v[230:231], v[156:157]
	v_pk_mul_f32 v[232:233], v[154:155], v[154:155]
	v_pk_mul_f32 v[234:235], v[156:157], v[156:157]
	ds_read_b128 v[228:231], v210 offset:8192
	v_add_f32_e32 v236, v232, v233
	v_add_f32_e32 v236, v234, v236
	v_add_f32_e32 v236, v235, v236
	global_store_dwordx4 v247, v[154:157], s[38:39] nt
	v_cvt_pk_bf16_f32 v232, v154, v155
	v_cvt_pk_bf16_f32 v233, v156, v157
	v_add_f32_dpp v236, v236, v236 quad_perm:[1,0,3,2] row_mask:0xf bank_mask:0xf
	global_store_dwordx2 v248, v[232:233], s[50:51] nt
	s_add_u32 s38, s38, 0x4000
	s_addc_u32 s39, s39, 0
	v_add_f32_dpp v236, v236, v236 quad_perm:[2,3,0,1] row_mask:0xf bank_mask:0xf
	s_add_u32 s50, s50, 0x2000
	s_addc_u32 s51, s51, 0
	v_add_f32_dpp v236, v236, v236 row_half_mirror row_mask:0xf bank_mask:0xf
	s_nop 1
	v_add_f32_dpp v236, v236, v236 row_mirror row_mask:0xf bank_mask:0xf
	s_mov_b64 exec, s[48:49]
	global_store_dword v249, v236, s[34:35] offset:1536
	s_mov_b64 exec, -1
	s_waitcnt vmcnt(45) lgkmcnt(1)
	v_pk_add_f32 v[158:159], v[238:239], v[158:159]
	v_pk_add_f32 v[160:161], v[240:241], v[160:161]
	v_pk_mul_f32 v[242:243], v[158:159], v[158:159]
	v_pk_mul_f32 v[244:245], v[160:161], v[160:161]
	ds_read_b128 v[238:241], v211 offset:9216
	v_add_f32_e32 v246, v242, v243
	v_add_f32_e32 v246, v244, v246
	v_add_f32_e32 v246, v245, v246
	global_store_dwordx4 v247, v[158:161], s[38:39] nt
	v_cvt_pk_bf16_f32 v242, v158, v159
	v_cvt_pk_bf16_f32 v243, v160, v161
	v_add_f32_dpp v246, v246, v246 quad_perm:[1,0,3,2] row_mask:0xf bank_mask:0xf
	global_store_dwordx2 v248, v[242:243], s[50:51] nt
	s_add_u32 s38, s38, 0x4000
	s_addc_u32 s39, s39, 0
	v_add_f32_dpp v246, v246, v246 quad_perm:[2,3,0,1] row_mask:0xf bank_mask:0xf
	s_add_u32 s50, s50, 0x2000
	s_addc_u32 s51, s51, 0
	v_add_f32_dpp v246, v246, v246 row_half_mirror row_mask:0xf bank_mask:0xf
	s_nop 1
	v_add_f32_dpp v246, v246, v246 row_mirror row_mask:0xf bank_mask:0xf
	s_mov_b64 exec, s[48:49]
	global_store_dword v249, v246, s[34:35] offset:1792
	s_mov_b64 exec, -1
	s_waitcnt vmcnt(47) lgkmcnt(1)
	v_pk_add_f32 v[162:163], v[228:229], v[162:163]
	v_pk_add_f32 v[164:165], v[230:231], v[164:165]
	v_pk_mul_f32 v[232:233], v[162:163], v[162:163]
	v_pk_mul_f32 v[234:235], v[164:165], v[164:165]
	ds_read_b128 v[228:231], v215 offset:10240
	v_add_f32_e32 v236, v232, v233
	v_add_f32_e32 v236, v234, v236
	v_add_f32_e32 v236, v235, v236
	global_store_dwordx4 v247, v[162:165], s[38:39] nt
	v_cvt_pk_bf16_f32 v232, v162, v163
	v_cvt_pk_bf16_f32 v233, v164, v165
	v_add_f32_dpp v236, v236, v236 quad_perm:[1,0,3,2] row_mask:0xf bank_mask:0xf
	global_store_dwordx2 v248, v[232:233], s[50:51] nt
	s_add_u32 s38, s38, 0x4000
	s_addc_u32 s39, s39, 0
	v_add_f32_dpp v236, v236, v236 quad_perm:[2,3,0,1] row_mask:0xf bank_mask:0xf
	s_add_u32 s50, s50, 0x2000
	s_addc_u32 s51, s51, 0
	v_add_f32_dpp v236, v236, v236 row_half_mirror row_mask:0xf bank_mask:0xf
	s_nop 1
	v_add_f32_dpp v236, v236, v236 row_mirror row_mask:0xf bank_mask:0xf
	s_mov_b64 exec, s[48:49]
	global_store_dword v249, v236, s[34:35] offset:2048
	s_mov_b64 exec, -1
	s_waitcnt vmcnt(49) lgkmcnt(1)
	v_pk_add_f32 v[166:167], v[238:239], v[166:167]
	v_pk_add_f32 v[168:169], v[240:241], v[168:169]
	v_pk_mul_f32 v[242:243], v[166:167], v[166:167]
	v_pk_mul_f32 v[244:245], v[168:169], v[168:169]
	ds_read_b128 v[238:241], v237 offset:11264
	v_add_f32_e32 v246, v242, v243
	v_add_f32_e32 v246, v244, v246
	v_add_f32_e32 v246, v245, v246
	global_store_dwordx4 v247, v[166:169], s[38:39] nt
	v_cvt_pk_bf16_f32 v242, v166, v167
	v_cvt_pk_bf16_f32 v243, v168, v169
	v_add_f32_dpp v246, v246, v246 quad_perm:[1,0,3,2] row_mask:0xf bank_mask:0xf
	global_store_dwordx2 v248, v[242:243], s[50:51] nt
	s_add_u32 s38, s38, 0x4000
	s_addc_u32 s39, s39, 0
	v_add_f32_dpp v246, v246, v246 quad_perm:[2,3,0,1] row_mask:0xf bank_mask:0xf
	s_add_u32 s50, s50, 0x2000
	s_addc_u32 s51, s51, 0
	v_add_f32_dpp v246, v246, v246 row_half_mirror row_mask:0xf bank_mask:0xf
	s_nop 1
	v_add_f32_dpp v246, v246, v246 row_mirror row_mask:0xf bank_mask:0xf
	s_mov_b64 exec, s[48:49]
	global_store_dword v249, v246, s[34:35] offset:2304
	s_mov_b64 exec, -1
	s_waitcnt vmcnt(51) lgkmcnt(1)
	v_pk_add_f32 v[192:193], v[228:229], v[192:193]
	v_pk_add_f32 v[194:195], v[230:231], v[194:195]
	v_pk_mul_f32 v[232:233], v[192:193], v[192:193]
	v_pk_mul_f32 v[234:235], v[194:195], v[194:195]
	ds_read_b128 v[228:231], v210 offset:12288
	v_add_f32_e32 v236, v232, v233
	v_add_f32_e32 v236, v234, v236
	v_add_f32_e32 v236, v235, v236
	global_store_dwordx4 v247, v[192:195], s[38:39] nt
	v_cvt_pk_bf16_f32 v232, v192, v193
	v_cvt_pk_bf16_f32 v233, v194, v195
	v_add_f32_dpp v236, v236, v236 quad_perm:[1,0,3,2] row_mask:0xf bank_mask:0xf
	global_store_dwordx2 v248, v[232:233], s[50:51] nt
	s_add_u32 s38, s38, 0x4000
	s_addc_u32 s39, s39, 0
	v_add_f32_dpp v236, v236, v236 quad_perm:[2,3,0,1] row_mask:0xf bank_mask:0xf
	s_add_u32 s50, s50, 0x2000
	s_addc_u32 s51, s51, 0
	v_add_f32_dpp v236, v236, v236 row_half_mirror row_mask:0xf bank_mask:0xf
	s_nop 1
	v_add_f32_dpp v236, v236, v236 row_mirror row_mask:0xf bank_mask:0xf
	s_mov_b64 exec, s[48:49]
	global_store_dword v249, v236, s[34:35] offset:2560
	s_mov_b64 exec, -1
	s_waitcnt vmcnt(53) lgkmcnt(1)
	v_pk_add_f32 v[196:197], v[238:239], v[196:197]
	v_pk_add_f32 v[198:199], v[240:241], v[198:199]
	v_pk_mul_f32 v[242:243], v[196:197], v[196:197]
	v_pk_mul_f32 v[244:245], v[198:199], v[198:199]
	ds_read_b128 v[238:241], v211 offset:13312
	v_add_f32_e32 v246, v242, v243
	v_add_f32_e32 v246, v244, v246
	v_add_f32_e32 v246, v245, v246
	global_store_dwordx4 v247, v[196:199], s[38:39] nt
	v_cvt_pk_bf16_f32 v242, v196, v197
	v_cvt_pk_bf16_f32 v243, v198, v199
	v_add_f32_dpp v246, v246, v246 quad_perm:[1,0,3,2] row_mask:0xf bank_mask:0xf
	global_store_dwordx2 v248, v[242:243], s[50:51] nt
	s_add_u32 s38, s38, 0x4000
	s_addc_u32 s39, s39, 0
	v_add_f32_dpp v246, v246, v246 quad_perm:[2,3,0,1] row_mask:0xf bank_mask:0xf
	s_add_u32 s50, s50, 0x2000
	s_addc_u32 s51, s51, 0
	v_add_f32_dpp v246, v246, v246 row_half_mirror row_mask:0xf bank_mask:0xf
	s_nop 1
	v_add_f32_dpp v246, v246, v246 row_mirror row_mask:0xf bank_mask:0xf
	s_mov_b64 exec, s[48:49]
	global_store_dword v249, v246, s[34:35] offset:2816
	s_mov_b64 exec, -1
	s_waitcnt vmcnt(55) lgkmcnt(1)
	v_pk_add_f32 v[200:201], v[228:229], v[200:201]
	v_pk_add_f32 v[202:203], v[230:231], v[202:203]
	v_pk_mul_f32 v[232:233], v[200:201], v[200:201]
	v_pk_mul_f32 v[234:235], v[202:203], v[202:203]
	ds_read_b128 v[228:231], v215 offset:14336
	v_add_f32_e32 v236, v232, v233
	v_add_f32_e32 v236, v234, v236
	v_add_f32_e32 v236, v235, v236
	global_store_dwordx4 v247, v[200:203], s[38:39] nt
	v_cvt_pk_bf16_f32 v232, v200, v201
	v_cvt_pk_bf16_f32 v233, v202, v203
	v_add_f32_dpp v236, v236, v236 quad_perm:[1,0,3,2] row_mask:0xf bank_mask:0xf
	global_store_dwordx2 v248, v[232:233], s[50:51] nt
	s_add_u32 s38, s38, 0x4000
	s_addc_u32 s39, s39, 0
	v_add_f32_dpp v236, v236, v236 quad_perm:[2,3,0,1] row_mask:0xf bank_mask:0xf
	s_add_u32 s50, s50, 0x2000
	s_addc_u32 s51, s51, 0
	v_add_f32_dpp v236, v236, v236 row_half_mirror row_mask:0xf bank_mask:0xf
	s_nop 1
	v_add_f32_dpp v236, v236, v236 row_mirror row_mask:0xf bank_mask:0xf
	s_mov_b64 exec, s[48:49]
	global_store_dword v249, v236, s[34:35] offset:3072
	s_mov_b64 exec, -1
	s_waitcnt vmcnt(57) lgkmcnt(1)
	v_pk_add_f32 v[216:217], v[238:239], v[216:217]
	v_pk_add_f32 v[218:219], v[240:241], v[218:219]
	v_pk_mul_f32 v[242:243], v[216:217], v[216:217]
	v_pk_mul_f32 v[244:245], v[218:219], v[218:219]
	ds_read_b128 v[238:241], v237 offset:15360
	v_add_f32_e32 v246, v242, v243
	v_add_f32_e32 v246, v244, v246
	v_add_f32_e32 v246, v245, v246
	global_store_dwordx4 v247, v[216:219], s[38:39] nt
	v_cvt_pk_bf16_f32 v242, v216, v217
	v_cvt_pk_bf16_f32 v243, v218, v219
	v_add_f32_dpp v246, v246, v246 quad_perm:[1,0,3,2] row_mask:0xf bank_mask:0xf
	global_store_dwordx2 v248, v[242:243], s[50:51] nt
	s_add_u32 s38, s38, 0x4000
	s_addc_u32 s39, s39, 0
	v_add_f32_dpp v246, v246, v246 quad_perm:[2,3,0,1] row_mask:0xf bank_mask:0xf
	s_add_u32 s50, s50, 0x2000
	s_addc_u32 s51, s51, 0
	v_add_f32_dpp v246, v246, v246 row_half_mirror row_mask:0xf bank_mask:0xf
	s_nop 1
	v_add_f32_dpp v246, v246, v246 row_mirror row_mask:0xf bank_mask:0xf
	s_mov_b64 exec, s[48:49]
	global_store_dword v249, v246, s[34:35] offset:3328
	s_mov_b64 exec, -1
	s_waitcnt vmcnt(59) lgkmcnt(1)
	v_pk_add_f32 v[220:221], v[228:229], v[220:221]
	v_pk_add_f32 v[222:223], v[230:231], v[222:223]
	v_pk_mul_f32 v[232:233], v[220:221], v[220:221]
	v_pk_mul_f32 v[234:235], v[222:223], v[222:223]
	v_add_f32_e32 v236, v232, v233
	v_add_f32_e32 v236, v234, v236
	v_add_f32_e32 v236, v235, v236
	global_store_dwordx4 v247, v[220:223], s[38:39] nt
	v_cvt_pk_bf16_f32 v232, v220, v221
	v_cvt_pk_bf16_f32 v233, v222, v223
	v_add_f32_dpp v236, v236, v236 quad_perm:[1,0,3,2] row_mask:0xf bank_mask:0xf
	global_store_dwordx2 v248, v[232:233], s[50:51] nt
	s_add_u32 s38, s38, 0x4000
	s_addc_u32 s39, s39, 0
	v_add_f32_dpp v236, v236, v236 quad_perm:[2,3,0,1] row_mask:0xf bank_mask:0xf
	s_add_u32 s50, s50, 0x2000
	s_addc_u32 s51, s51, 0
	v_add_f32_dpp v236, v236, v236 row_half_mirror row_mask:0xf bank_mask:0xf
	s_nop 1
	v_add_f32_dpp v236, v236, v236 row_mirror row_mask:0xf bank_mask:0xf
	s_mov_b64 exec, s[48:49]
	global_store_dword v249, v236, s[34:35] offset:3584
	s_mov_b64 exec, -1
	s_waitcnt vmcnt(61) lgkmcnt(0)
	v_pk_add_f32 v[224:225], v[238:239], v[224:225]
	v_pk_add_f32 v[226:227], v[240:241], v[226:227]
	v_pk_mul_f32 v[242:243], v[224:225], v[224:225]
	v_pk_mul_f32 v[244:245], v[226:227], v[226:227]
	v_add_f32_e32 v246, v242, v243
	v_add_f32_e32 v246, v244, v246
	v_add_f32_e32 v246, v245, v246
	global_store_dwordx4 v247, v[224:227], s[38:39] nt
	v_cvt_pk_bf16_f32 v242, v224, v225
	v_cvt_pk_bf16_f32 v243, v226, v227
	v_add_f32_dpp v246, v246, v246 quad_perm:[1,0,3,2] row_mask:0xf bank_mask:0xf
	global_store_dwordx2 v248, v[242:243], s[50:51] nt
	s_add_u32 s38, s38, 0x4000
	s_addc_u32 s39, s39, 0
	v_add_f32_dpp v246, v246, v246 quad_perm:[2,3,0,1] row_mask:0xf bank_mask:0xf
	s_add_u32 s50, s50, 0x2000
	s_addc_u32 s51, s51, 0
	v_add_f32_dpp v246, v246, v246 row_half_mirror row_mask:0xf bank_mask:0xf
	s_nop 1
	v_add_f32_dpp v246, v246, v246 row_mirror row_mask:0xf bank_mask:0xf
	s_mov_b64 exec, s[48:49]
	global_store_dword v249, v246, s[34:35] offset:3840
	s_mov_b64 exec, -1
	s_add_u32 s34, s34, 0x1000
	s_addc_u32 s35, s35, 0
	v_and_b32_e32 v238, 15, v170
	v_xor_b32_e32 v238, v238, v171
	v_lshl_add_u32 v239, v170, 8, s40
	v_xor_b32_e32 v228, 0, v238
	v_lshl_add_u32 v228, v228, 4, v239
	v_xor_b32_e32 v229, 2, v238
	v_lshl_add_u32 v229, v229, 4, v239
	v_xor_b32_e32 v230, 4, v238
	v_lshl_add_u32 v230, v230, 4, v239
	v_xor_b32_e32 v231, 6, v238
	v_lshl_add_u32 v231, v231, 4, v239
	v_xor_b32_e32 v232, 8, v238
	v_lshl_add_u32 v232, v232, 4, v239
	v_xor_b32_e32 v233, 10, v238
	v_lshl_add_u32 v233, v233, 4, v239
	v_xor_b32_e32 v234, 12, v238
	v_lshl_add_u32 v234, v234, 4, v239
	v_xor_b32_e32 v235, 14, v238
	v_lshl_add_u32 v235, v235, 4, v239
	ds_write_b128 v228, v[18:21]
	ds_write_b128 v229, v[22:25]
	ds_write_b128 v230, v[26:29]
	ds_write_b128 v231, v[30:33]
	ds_write_b128 v232, v[50:53]
	ds_write_b128 v233, v[54:57]
	ds_write_b128 v234, v[58:61]
	ds_write_b128 v235, v[62:65]
	ds_write_b128 v228, v[2:5] offset:8192
	ds_write_b128 v229, v[6:9] offset:8192
	ds_write_b128 v230, v[10:13] offset:8192
	ds_write_b128 v231, v[14:17] offset:8192
	ds_write_b128 v232, v[34:37] offset:8192
	ds_write_b128 v233, v[38:41] offset:8192
	ds_write_b128 v234, v[42:45] offset:8192
	ds_write_b128 v235, v[46:49] offset:8192
	s_waitcnt lgkmcnt(0)
	ds_read_b128 v[228:231], v210 offset:0
	ds_read_b128 v[238:241], v211 offset:1024
	s_waitcnt vmcnt(63) lgkmcnt(1)
	v_pk_add_f32 v[66:67], v[228:229], v[66:67]
	v_pk_add_f32 v[68:69], v[230:231], v[68:69]
	v_pk_mul_f32 v[232:233], v[66:67], v[66:67]
	v_pk_mul_f32 v[234:235], v[68:69], v[68:69]
	ds_read_b128 v[228:231], v215 offset:2048
	v_add_f32_e32 v236, v232, v233
	v_add_f32_e32 v236, v234, v236
	v_add_f32_e32 v236, v235, v236
	global_store_dwordx4 v247, v[66:69], s[38:39] nt
	v_cvt_pk_bf16_f32 v232, v66, v67
	v_cvt_pk_bf16_f32 v233, v68, v69
	v_add_f32_dpp v236, v236, v236 quad_perm:[1,0,3,2] row_mask:0xf bank_mask:0xf
	global_store_dwordx2 v248, v[232:233], s[50:51] nt
	s_add_u32 s38, s38, 0x4000
	s_addc_u32 s39, s39, 0
	v_add_f32_dpp v236, v236, v236 quad_perm:[2,3,0,1] row_mask:0xf bank_mask:0xf
	s_add_u32 s50, s50, 0x2000
	s_addc_u32 s51, s51, 0
	v_add_f32_dpp v236, v236, v236 row_half_mirror row_mask:0xf bank_mask:0xf
	s_nop 1
	v_add_f32_dpp v236, v236, v236 row_mirror row_mask:0xf bank_mask:0xf
	s_mov_b64 exec, s[48:49]
	global_store_dword v249, v236, s[34:35] offset:0
	s_mov_b64 exec, -1
	s_waitcnt vmcnt(63) lgkmcnt(1)
	v_pk_add_f32 v[70:71], v[238:239], v[70:71]
	v_pk_add_f32 v[72:73], v[240:241], v[72:73]
	v_pk_mul_f32 v[242:243], v[70:71], v[70:71]
	v_pk_mul_f32 v[244:245], v[72:73], v[72:73]
	ds_read_b128 v[238:241], v237 offset:3072
	v_add_f32_e32 v246, v242, v243
	v_add_f32_e32 v246, v244, v246
	v_add_f32_e32 v246, v245, v246
	global_store_dwordx4 v247, v[70:73], s[38:39] nt
	v_cvt_pk_bf16_f32 v242, v70, v71
	v_cvt_pk_bf16_f32 v243, v72, v73
	v_add_f32_dpp v246, v246, v246 quad_perm:[1,0,3,2] row_mask:0xf bank_mask:0xf
	global_store_dwordx2 v248, v[242:243], s[50:51] nt
	s_add_u32 s38, s38, 0x4000
	s_addc_u32 s39, s39, 0
	v_add_f32_dpp v246, v246, v246 quad_perm:[2,3,0,1] row_mask:0xf bank_mask:0xf
	s_add_u32 s50, s50, 0x2000
	s_addc_u32 s51, s51, 0
	v_add_f32_dpp v246, v246, v246 row_half_mirror row_mask:0xf bank_mask:0xf
	s_nop 1
	v_add_f32_dpp v246, v246, v246 row_mirror row_mask:0xf bank_mask:0xf
	s_mov_b64 exec, s[48:49]
	global_store_dword v249, v246, s[34:35] offset:256
	s_mov_b64 exec, -1
	s_waitcnt vmcnt(63) lgkmcnt(1)
	v_pk_add_f32 v[74:75], v[228:229], v[74:75]
	v_pk_add_f32 v[76:77], v[230:231], v[76:77]
	v_pk_mul_f32 v[232:233], v[74:75], v[74:75]
	v_pk_mul_f32 v[234:235], v[76:77], v[76:77]
	ds_read_b128 v[228:231], v210 offset:4096
	v_add_f32_e32 v236, v232, v233
	v_add_f32_e32 v236, v234, v236
	v_add_f32_e32 v236, v235, v236
	global_store_dwordx4 v247, v[74:77], s[38:39] nt
	v_cvt_pk_bf16_f32 v232, v74, v75
	v_cvt_pk_bf16_f32 v233, v76, v77
	v_add_f32_dpp v236, v236, v236 quad_perm:[1,0,3,2] row_mask:0xf bank_mask:0xf
	global_store_dwordx2 v248, v[232:233], s[50:51] nt
	s_add_u32 s38, s38, 0x4000
	s_addc_u32 s39, s39, 0
	v_add_f32_dpp v236, v236, v236 quad_perm:[2,3,0,1] row_mask:0xf bank_mask:0xf
	s_add_u32 s50, s50, 0x2000
	s_addc_u32 s51, s51, 0
	v_add_f32_dpp v236, v236, v236 row_half_mirror row_mask:0xf bank_mask:0xf
	s_nop 1
	v_add_f32_dpp v236, v236, v236 row_mirror row_mask:0xf bank_mask:0xf
	s_mov_b64 exec, s[48:49]
	global_store_dword v249, v236, s[34:35] offset:512
	s_mov_b64 exec, -1
	s_waitcnt vmcnt(63) lgkmcnt(1)
	v_pk_add_f32 v[78:79], v[238:239], v[78:79]
	v_pk_add_f32 v[80:81], v[240:241], v[80:81]
	v_pk_mul_f32 v[242:243], v[78:79], v[78:79]
	v_pk_mul_f32 v[244:245], v[80:81], v[80:81]
	ds_read_b128 v[238:241], v211 offset:5120
	v_add_f32_e32 v246, v242, v243
	v_add_f32_e32 v246, v244, v246
	v_add_f32_e32 v246, v245, v246
	global_store_dwordx4 v247, v[78:81], s[38:39] nt
	v_cvt_pk_bf16_f32 v242, v78, v79
	v_cvt_pk_bf16_f32 v243, v80, v81
	v_add_f32_dpp v246, v246, v246 quad_perm:[1,0,3,2] row_mask:0xf bank_mask:0xf
	global_store_dwordx2 v248, v[242:243], s[50:51] nt
	s_add_u32 s38, s38, 0x4000
	s_addc_u32 s39, s39, 0
	v_add_f32_dpp v246, v246, v246 quad_perm:[2,3,0,1] row_mask:0xf bank_mask:0xf
	s_add_u32 s50, s50, 0x2000
	s_addc_u32 s51, s51, 0
	v_add_f32_dpp v246, v246, v246 row_half_mirror row_mask:0xf bank_mask:0xf
	s_nop 1
	v_add_f32_dpp v246, v246, v246 row_mirror row_mask:0xf bank_mask:0xf
	s_mov_b64 exec, s[48:49]
	global_store_dword v249, v246, s[34:35] offset:768
	s_mov_b64 exec, -1
	s_waitcnt vmcnt(63) lgkmcnt(1)
	v_pk_add_f32 v[114:115], v[228:229], v[114:115]
	v_pk_add_f32 v[116:117], v[230:231], v[116:117]
	v_pk_mul_f32 v[232:233], v[114:115], v[114:115]
	v_pk_mul_f32 v[234:235], v[116:117], v[116:117]
	ds_read_b128 v[228:231], v215 offset:6144
	v_add_f32_e32 v236, v232, v233
	v_add_f32_e32 v236, v234, v236
	v_add_f32_e32 v236, v235, v236
	global_store_dwordx4 v247, v[114:117], s[38:39] nt
	v_cvt_pk_bf16_f32 v232, v114, v115
	v_cvt_pk_bf16_f32 v233, v116, v117
	v_add_f32_dpp v236, v236, v236 quad_perm:[1,0,3,2] row_mask:0xf bank_mask:0xf
	global_store_dwordx2 v248, v[232:233], s[50:51] nt
	s_add_u32 s38, s38, 0x4000
	s_addc_u32 s39, s39, 0
	v_add_f32_dpp v236, v236, v236 quad_perm:[2,3,0,1] row_mask:0xf bank_mask:0xf
	s_add_u32 s50, s50, 0x2000
	s_addc_u32 s51, s51, 0
	v_add_f32_dpp v236, v236, v236 row_half_mirror row_mask:0xf bank_mask:0xf
	s_nop 1
	v_add_f32_dpp v236, v236, v236 row_mirror row_mask:0xf bank_mask:0xf
	s_mov_b64 exec, s[48:49]
	global_store_dword v249, v236, s[34:35] offset:1024
	s_mov_b64 exec, -1
	s_waitcnt vmcnt(63) lgkmcnt(1)
	v_pk_add_f32 v[118:119], v[238:239], v[118:119]
	v_pk_add_f32 v[120:121], v[240:241], v[120:121]
	v_pk_mul_f32 v[242:243], v[118:119], v[118:119]
	v_pk_mul_f32 v[244:245], v[120:121], v[120:121]
	ds_read_b128 v[238:241], v237 offset:7168
	v_add_f32_e32 v246, v242, v243
	v_add_f32_e32 v246, v244, v246
	v_add_f32_e32 v246, v245, v246
	global_store_dwordx4 v247, v[118:121], s[38:39] nt
	v_cvt_pk_bf16_f32 v242, v118, v119
	v_cvt_pk_bf16_f32 v243, v120, v121
	v_add_f32_dpp v246, v246, v246 quad_perm:[1,0,3,2] row_mask:0xf bank_mask:0xf
	global_store_dwordx2 v248, v[242:243], s[50:51] nt
	s_add_u32 s38, s38, 0x4000
	s_addc_u32 s39, s39, 0
	v_add_f32_dpp v246, v246, v246 quad_perm:[2,3,0,1] row_mask:0xf bank_mask:0xf
	s_add_u32 s50, s50, 0x2000
	s_addc_u32 s51, s51, 0
	v_add_f32_dpp v246, v246, v246 row_half_mirror row_mask:0xf bank_mask:0xf
	s_nop 1
	v_add_f32_dpp v246, v246, v246 row_mirror row_mask:0xf bank_mask:0xf
	s_mov_b64 exec, s[48:49]
	global_store_dword v249, v246, s[34:35] offset:1280
	s_mov_b64 exec, -1
	s_waitcnt vmcnt(63) lgkmcnt(1)
	v_pk_add_f32 v[122:123], v[228:229], v[122:123]
	v_pk_add_f32 v[124:125], v[230:231], v[124:125]
	v_pk_mul_f32 v[232:233], v[122:123], v[122:123]
	v_pk_mul_f32 v[234:235], v[124:125], v[124:125]
	ds_read_b128 v[228:231], v210 offset:8192
	v_add_f32_e32 v236, v232, v233
	v_add_f32_e32 v236, v234, v236
	v_add_f32_e32 v236, v235, v236
	global_store_dwordx4 v247, v[122:125], s[38:39] nt
	v_cvt_pk_bf16_f32 v232, v122, v123
	v_cvt_pk_bf16_f32 v233, v124, v125
	v_add_f32_dpp v236, v236, v236 quad_perm:[1,0,3,2] row_mask:0xf bank_mask:0xf
	global_store_dwordx2 v248, v[232:233], s[50:51] nt
	s_add_u32 s38, s38, 0x4000
	s_addc_u32 s39, s39, 0
	v_add_f32_dpp v236, v236, v236 quad_perm:[2,3,0,1] row_mask:0xf bank_mask:0xf
	s_add_u32 s50, s50, 0x2000
	s_addc_u32 s51, s51, 0
	v_add_f32_dpp v236, v236, v236 row_half_mirror row_mask:0xf bank_mask:0xf
	s_nop 1
	v_add_f32_dpp v236, v236, v236 row_mirror row_mask:0xf bank_mask:0xf
	s_mov_b64 exec, s[48:49]
	global_store_dword v249, v236, s[34:35] offset:1536
	s_mov_b64 exec, -1
	s_waitcnt vmcnt(63) lgkmcnt(1)
	v_pk_add_f32 v[126:127], v[238:239], v[126:127]
	v_pk_add_f32 v[128:129], v[240:241], v[128:129]
	v_pk_mul_f32 v[242:243], v[126:127], v[126:127]
	v_pk_mul_f32 v[244:245], v[128:129], v[128:129]
	ds_read_b128 v[238:241], v211 offset:9216
	v_add_f32_e32 v246, v242, v243
	v_add_f32_e32 v246, v244, v246
	v_add_f32_e32 v246, v245, v246
	global_store_dwordx4 v247, v[126:129], s[38:39] nt
	v_cvt_pk_bf16_f32 v242, v126, v127
	v_cvt_pk_bf16_f32 v243, v128, v129
	v_add_f32_dpp v246, v246, v246 quad_perm:[1,0,3,2] row_mask:0xf bank_mask:0xf
	global_store_dwordx2 v248, v[242:243], s[50:51] nt
	s_add_u32 s38, s38, 0x4000
	s_addc_u32 s39, s39, 0
	v_add_f32_dpp v246, v246, v246 quad_perm:[2,3,0,1] row_mask:0xf bank_mask:0xf
	s_add_u32 s50, s50, 0x2000
	s_addc_u32 s51, s51, 0
	v_add_f32_dpp v246, v246, v246 row_half_mirror row_mask:0xf bank_mask:0xf
	s_nop 1
	v_add_f32_dpp v246, v246, v246 row_mirror row_mask:0xf bank_mask:0xf
	s_mov_b64 exec, s[48:49]
	global_store_dword v249, v246, s[34:35] offset:1792
	s_mov_b64 exec, -1
	s_waitcnt vmcnt(63) lgkmcnt(1)
	v_pk_add_f32 v[82:83], v[228:229], v[82:83]
	v_pk_add_f32 v[84:85], v[230:231], v[84:85]
	v_pk_mul_f32 v[232:233], v[82:83], v[82:83]
	v_pk_mul_f32 v[234:235], v[84:85], v[84:85]
	ds_read_b128 v[228:231], v215 offset:10240
	v_add_f32_e32 v236, v232, v233
	v_add_f32_e32 v236, v234, v236
	v_add_f32_e32 v236, v235, v236
	global_store_dwordx4 v247, v[82:85], s[38:39] nt
	v_cvt_pk_bf16_f32 v232, v82, v83
	v_cvt_pk_bf16_f32 v233, v84, v85
	v_add_f32_dpp v236, v236, v236 quad_perm:[1,0,3,2] row_mask:0xf bank_mask:0xf
	global_store_dwordx2 v248, v[232:233], s[50:51] nt
	s_add_u32 s38, s38, 0x4000
	s_addc_u32 s39, s39, 0
	v_add_f32_dpp v236, v236, v236 quad_perm:[2,3,0,1] row_mask:0xf bank_mask:0xf
	s_add_u32 s50, s50, 0x2000
	s_addc_u32 s51, s51, 0
	v_add_f32_dpp v236, v236, v236 row_half_mirror row_mask:0xf bank_mask:0xf
	s_nop 1
	v_add_f32_dpp v236, v236, v236 row_mirror row_mask:0xf bank_mask:0xf
	s_mov_b64 exec, s[48:49]
	global_store_dword v249, v236, s[34:35] offset:2048
	s_mov_b64 exec, -1
	s_waitcnt vmcnt(63) lgkmcnt(1)
	v_pk_add_f32 v[86:87], v[238:239], v[86:87]
	v_pk_add_f32 v[88:89], v[240:241], v[88:89]
	v_pk_mul_f32 v[242:243], v[86:87], v[86:87]
	v_pk_mul_f32 v[244:245], v[88:89], v[88:89]
	ds_read_b128 v[238:241], v237 offset:11264
	v_add_f32_e32 v246, v242, v243
	v_add_f32_e32 v246, v244, v246
	v_add_f32_e32 v246, v245, v246
	global_store_dwordx4 v247, v[86:89], s[38:39] nt
	v_cvt_pk_bf16_f32 v242, v86, v87
	v_cvt_pk_bf16_f32 v243, v88, v89
	v_add_f32_dpp v246, v246, v246 quad_perm:[1,0,3,2] row_mask:0xf bank_mask:0xf
	global_store_dwordx2 v248, v[242:243], s[50:51] nt
	s_add_u32 s38, s38, 0x4000
	s_addc_u32 s39, s39, 0
	v_add_f32_dpp v246, v246, v246 quad_perm:[2,3,0,1] row_mask:0xf bank_mask:0xf
	s_add_u32 s50, s50, 0x2000
	s_addc_u32 s51, s51, 0
	v_add_f32_dpp v246, v246, v246 row_half_mirror row_mask:0xf bank_mask:0xf
	s_nop 1
	v_add_f32_dpp v246, v246, v246 row_mirror row_mask:0xf bank_mask:0xf
	s_mov_b64 exec, s[48:49]
	global_store_dword v249, v246, s[34:35] offset:2304
	s_mov_b64 exec, -1
	s_waitcnt vmcnt(63) lgkmcnt(1)
	v_pk_add_f32 v[90:91], v[228:229], v[90:91]
	v_pk_add_f32 v[92:93], v[230:231], v[92:93]
	v_pk_mul_f32 v[232:233], v[90:91], v[90:91]
	v_pk_mul_f32 v[234:235], v[92:93], v[92:93]
	ds_read_b128 v[228:231], v210 offset:12288
	v_add_f32_e32 v236, v232, v233
	v_add_f32_e32 v236, v234, v236
	v_add_f32_e32 v236, v235, v236
	global_store_dwordx4 v247, v[90:93], s[38:39] nt
	v_cvt_pk_bf16_f32 v232, v90, v91
	v_cvt_pk_bf16_f32 v233, v92, v93
	v_add_f32_dpp v236, v236, v236 quad_perm:[1,0,3,2] row_mask:0xf bank_mask:0xf
	global_store_dwordx2 v248, v[232:233], s[50:51] nt
	s_add_u32 s38, s38, 0x4000
	s_addc_u32 s39, s39, 0
	v_add_f32_dpp v236, v236, v236 quad_perm:[2,3,0,1] row_mask:0xf bank_mask:0xf
	s_add_u32 s50, s50, 0x2000
	s_addc_u32 s51, s51, 0
	v_add_f32_dpp v236, v236, v236 row_half_mirror row_mask:0xf bank_mask:0xf
	s_nop 1
	v_add_f32_dpp v236, v236, v236 row_mirror row_mask:0xf bank_mask:0xf
	s_mov_b64 exec, s[48:49]
	global_store_dword v249, v236, s[34:35] offset:2560
	s_mov_b64 exec, -1
	s_waitcnt vmcnt(63) lgkmcnt(1)
	v_pk_add_f32 v[94:95], v[238:239], v[94:95]
	v_pk_add_f32 v[96:97], v[240:241], v[96:97]
	v_pk_mul_f32 v[242:243], v[94:95], v[94:95]
	v_pk_mul_f32 v[244:245], v[96:97], v[96:97]
	ds_read_b128 v[238:241], v211 offset:13312
	v_add_f32_e32 v246, v242, v243
	v_add_f32_e32 v246, v244, v246
	v_add_f32_e32 v246, v245, v246
	global_store_dwordx4 v247, v[94:97], s[38:39] nt
	v_cvt_pk_bf16_f32 v242, v94, v95
	v_cvt_pk_bf16_f32 v243, v96, v97
	v_add_f32_dpp v246, v246, v246 quad_perm:[1,0,3,2] row_mask:0xf bank_mask:0xf
	global_store_dwordx2 v248, v[242:243], s[50:51] nt
	s_add_u32 s38, s38, 0x4000
	s_addc_u32 s39, s39, 0
	v_add_f32_dpp v246, v246, v246 quad_perm:[2,3,0,1] row_mask:0xf bank_mask:0xf
	s_add_u32 s50, s50, 0x2000
	s_addc_u32 s51, s51, 0
	v_add_f32_dpp v246, v246, v246 row_half_mirror row_mask:0xf bank_mask:0xf
	s_nop 1
	v_add_f32_dpp v246, v246, v246 row_mirror row_mask:0xf bank_mask:0xf
	s_mov_b64 exec, s[48:49]
	global_store_dword v249, v246, s[34:35] offset:2816
	s_mov_b64 exec, -1
	s_waitcnt vmcnt(63) lgkmcnt(1)
	v_pk_add_f32 v[98:99], v[228:229], v[98:99]
	v_pk_add_f32 v[100:101], v[230:231], v[100:101]
	v_pk_mul_f32 v[232:233], v[98:99], v[98:99]
	v_pk_mul_f32 v[234:235], v[100:101], v[100:101]
	ds_read_b128 v[228:231], v215 offset:14336
	v_add_f32_e32 v236, v232, v233
	v_add_f32_e32 v236, v234, v236
	v_add_f32_e32 v236, v235, v236
	global_store_dwordx4 v247, v[98:101], s[38:39] nt
	v_cvt_pk_bf16_f32 v232, v98, v99
	v_cvt_pk_bf16_f32 v233, v100, v101
	v_add_f32_dpp v236, v236, v236 quad_perm:[1,0,3,2] row_mask:0xf bank_mask:0xf
	global_store_dwordx2 v248, v[232:233], s[50:51] nt
	s_add_u32 s38, s38, 0x4000
	s_addc_u32 s39, s39, 0
	v_add_f32_dpp v236, v236, v236 quad_perm:[2,3,0,1] row_mask:0xf bank_mask:0xf
	s_add_u32 s50, s50, 0x2000
	s_addc_u32 s51, s51, 0
	v_add_f32_dpp v236, v236, v236 row_half_mirror row_mask:0xf bank_mask:0xf
	s_nop 1
	v_add_f32_dpp v236, v236, v236 row_mirror row_mask:0xf bank_mask:0xf
	s_mov_b64 exec, s[48:49]
	global_store_dword v249, v236, s[34:35] offset:3072
	s_mov_b64 exec, -1
	s_waitcnt vmcnt(63) lgkmcnt(1)
	v_pk_add_f32 v[102:103], v[238:239], v[102:103]
	v_pk_add_f32 v[104:105], v[240:241], v[104:105]
	v_pk_mul_f32 v[242:243], v[102:103], v[102:103]
	v_pk_mul_f32 v[244:245], v[104:105], v[104:105]
	ds_read_b128 v[238:241], v237 offset:15360
	v_add_f32_e32 v246, v242, v243
	v_add_f32_e32 v246, v244, v246
	v_add_f32_e32 v246, v245, v246
	global_store_dwordx4 v247, v[102:105], s[38:39] nt
	v_cvt_pk_bf16_f32 v242, v102, v103
	v_cvt_pk_bf16_f32 v243, v104, v105
	v_add_f32_dpp v246, v246, v246 quad_perm:[1,0,3,2] row_mask:0xf bank_mask:0xf
	global_store_dwordx2 v248, v[242:243], s[50:51] nt
	s_add_u32 s38, s38, 0x4000
	s_addc_u32 s39, s39, 0
	v_add_f32_dpp v246, v246, v246 quad_perm:[2,3,0,1] row_mask:0xf bank_mask:0xf
	s_add_u32 s50, s50, 0x2000
	s_addc_u32 s51, s51, 0
	v_add_f32_dpp v246, v246, v246 row_half_mirror row_mask:0xf bank_mask:0xf
	s_nop 1
	v_add_f32_dpp v246, v246, v246 row_mirror row_mask:0xf bank_mask:0xf
	s_mov_b64 exec, s[48:49]
	global_store_dword v249, v246, s[34:35] offset:3328
	s_mov_b64 exec, -1
	s_waitcnt vmcnt(63) lgkmcnt(1)
	v_pk_add_f32 v[106:107], v[228:229], v[106:107]
	v_pk_add_f32 v[108:109], v[230:231], v[108:109]
	v_pk_mul_f32 v[232:233], v[106:107], v[106:107]
	v_pk_mul_f32 v[234:235], v[108:109], v[108:109]
	v_add_f32_e32 v236, v232, v233
	v_add_f32_e32 v236, v234, v236
	v_add_f32_e32 v236, v235, v236
	global_store_dwordx4 v247, v[106:109], s[38:39] nt
	v_cvt_pk_bf16_f32 v232, v106, v107
	v_cvt_pk_bf16_f32 v233, v108, v109
	v_add_f32_dpp v236, v236, v236 quad_perm:[1,0,3,2] row_mask:0xf bank_mask:0xf
	global_store_dwordx2 v248, v[232:233], s[50:51] nt
	s_add_u32 s38, s38, 0x4000
	s_addc_u32 s39, s39, 0
	v_add_f32_dpp v236, v236, v236 quad_perm:[2,3,0,1] row_mask:0xf bank_mask:0xf
	s_add_u32 s50, s50, 0x2000
	s_addc_u32 s51, s51, 0
	v_add_f32_dpp v236, v236, v236 row_half_mirror row_mask:0xf bank_mask:0xf
	s_nop 1
	v_add_f32_dpp v236, v236, v236 row_mirror row_mask:0xf bank_mask:0xf
	s_mov_b64 exec, s[48:49]
	global_store_dword v249, v236, s[34:35] offset:3584
	s_mov_b64 exec, -1
	s_waitcnt vmcnt(63) lgkmcnt(0)
	v_pk_add_f32 v[110:111], v[238:239], v[110:111]
	v_pk_add_f32 v[112:113], v[240:241], v[112:113]
	v_pk_mul_f32 v[242:243], v[110:111], v[110:111]
	v_pk_mul_f32 v[244:245], v[112:113], v[112:113]
	v_add_f32_e32 v246, v242, v243
	v_add_f32_e32 v246, v244, v246
	v_add_f32_e32 v246, v245, v246
	global_store_dwordx4 v247, v[110:113], s[38:39] nt
	v_cvt_pk_bf16_f32 v242, v110, v111
	v_cvt_pk_bf16_f32 v243, v112, v113
	v_add_f32_dpp v246, v246, v246 quad_perm:[1,0,3,2] row_mask:0xf bank_mask:0xf
	global_store_dwordx2 v248, v[242:243], s[50:51] nt
	s_add_u32 s38, s38, 0x4000
	s_addc_u32 s39, s39, 0
	v_add_f32_dpp v246, v246, v246 quad_perm:[2,3,0,1] row_mask:0xf bank_mask:0xf
	s_add_u32 s50, s50, 0x2000
	s_addc_u32 s51, s51, 0
	v_add_f32_dpp v246, v246, v246 row_half_mirror row_mask:0xf bank_mask:0xf
	s_nop 1
	v_add_f32_dpp v246, v246, v246 row_mirror row_mask:0xf bank_mask:0xf
	s_mov_b64 exec, s[48:49]
	global_store_dword v249, v246, s[34:35] offset:3840
	s_mov_b64 exec, -1
	s_waitcnt lgkmcnt(0)
	s_branch .LBB0_1677
.Lres_mlp2_last:
	v_readfirstlane_b32 s40, v204
	s_lshr_b32 s40, s40, 6
	s_and_b32 s41, s40, 1
	s_bfe_u32 s42, s40, 0x10001
	s_lshr_b32 s43, s40, 2
	s_lshl_b32 s44, s4, 1
	s_add_i32 s44, s44, s42
	s_lshl_b32 s45, s44, 7
	s_lshl_b32 s46, s41, 6
	s_add_i32 s45, s45, s46
	s_lshl_b32 s46, s43, 7
	s_add_i32 s46, s46, s2
	s_lshl_b32 s47, s44, 1
	s_add_i32 s47, s47, s41
	v_readlane_b32 s36, v250, 9
	v_readlane_b32 s37, v250, 10
	s_mov_b64 s[38:39], s[36:37]
	v_readlane_b32 s50, v250, 11
	v_readlane_b32 s51, v250, 12
	s_add_u32 s34, s50, 0xf900000
	s_addc_u32 s35, s51, 0
	s_add_u32 s50, s50, 0x5800000
	s_addc_u32 s51, s51, 0
	s_lshl_b32 s48, s46, 12
	s_lshl_b32 s49, s45, 2
	s_add_u32 s48, s48, s49
	s_add_u32 s36, s36, s48
	s_addc_u32 s37, s37, 0
	s_add_u32 s38, s38, s48
	s_addc_u32 s39, s39, 0
	s_lshr_b32 s48, s48, 1
	s_add_u32 s50, s50, s48
	s_addc_u32 s51, s51, 0
	s_lshl_b32 s48, s46, 6
	s_lshl_b32 s49, s47, 2
	s_add_u32 s48, s48, s49
	s_add_u32 s34, s34, s48
	s_addc_u32 s35, s35, 0
	v_and_b32_e32 v249, 63, v204
	v_and_b32_e32 v170, 31, v249
	v_lshrrev_b32_e32 v171, 5, v249
	v_and_b32_e32 v208, 15, v249
	v_lshrrev_b32_e32 v209, 4, v249
	s_lshl_b32 s40, s40, 14
	v_and_b32_e32 v238, 15, v170
	v_xor_b32_e32 v238, v238, v171
	v_lshl_add_u32 v239, v170, 8, s40
	v_xor_b32_e32 v228, 0, v238
	v_lshl_add_u32 v228, v228, 4, v239
	v_xor_b32_e32 v229, 2, v238
	v_lshl_add_u32 v229, v229, 4, v239
	v_xor_b32_e32 v230, 4, v238
	v_lshl_add_u32 v230, v230, 4, v239
	v_xor_b32_e32 v231, 6, v238
	v_lshl_add_u32 v231, v231, 4, v239
	v_xor_b32_e32 v232, 8, v238
	v_lshl_add_u32 v232, v232, 4, v239
	v_xor_b32_e32 v233, 10, v238
	v_lshl_add_u32 v233, v233, 4, v239
	v_xor_b32_e32 v234, 12, v238
	v_lshl_add_u32 v234, v234, 4, v239
	v_xor_b32_e32 v235, 14, v238
	v_lshl_add_u32 v235, v235, 4, v239
	v_lshl_add_u32 v239, v209, 8, s40
	v_add_u32_e32 v210, 0, v209
	v_xor_b32_e32 v210, v210, v208
	v_lshl_add_u32 v210, v210, 4, v239
	v_add_u32_e32 v211, 4, v209
	v_xor_b32_e32 v211, v211, v208
	v_lshl_add_u32 v211, v211, 4, v239
	v_add_u32_e32 v215, 8, v209
	v_xor_b32_e32 v215, v215, v208
	v_lshl_add_u32 v215, v215, 4, v239
	v_add_u32_e32 v237, 12, v209
	v_xor_b32_e32 v237, v237, v208
	v_lshl_add_u32 v237, v237, 4, v239
	v_lshlrev_b32_e32 v247, 12, v209
	v_lshl_add_u32 v247, v208, 4, v247
	v_lshrrev_b32_e32 v248, 1, v247
	v_lshlrev_b32_e32 v249, 6, v209
	s_mov_b32 s48, 0x00010001
	s_mov_b32 s49, 0x00010001
	global_load_dwordx4 v[130:133], v247, s[36:37]
	s_add_u32 s36, s36, 0x4000
	s_addc_u32 s37, s37, 0
	global_load_dwordx4 v[134:137], v247, s[36:37]
	s_add_u32 s36, s36, 0x4000
	s_addc_u32 s37, s37, 0
	global_load_dwordx4 v[138:141], v247, s[36:37]
	s_add_u32 s36, s36, 0x4000
	s_addc_u32 s37, s37, 0
	global_load_dwordx4 v[142:145], v247, s[36:37]
	s_add_u32 s36, s36, 0x4000
	s_addc_u32 s37, s37, 0
	global_load_dwordx4 v[146:149], v247, s[36:37]
	s_add_u32 s36, s36, 0x4000
	s_addc_u32 s37, s37, 0
	global_load_dwordx4 v[150:153], v247, s[36:37]
	s_add_u32 s36, s36, 0x4000
	s_addc_u32 s37, s37, 0
	global_load_dwordx4 v[154:157], v247, s[36:37]
	s_add_u32 s36, s36, 0x4000
	s_addc_u32 s37, s37, 0
	global_load_dwordx4 v[158:161], v247, s[36:37]
	s_add_u32 s36, s36, 0x4000
	s_addc_u32 s37, s37, 0
	global_load_dwordx4 v[162:165], v247, s[36:37]
	s_add_u32 s36, s36, 0x4000
	s_addc_u32 s37, s37, 0
	global_load_dwordx4 v[166:169], v247, s[36:37]
	s_add_u32 s36, s36, 0x4000
	s_addc_u32 s37, s37, 0
	global_load_dwordx4 v[192:195], v247, s[36:37]
	s_add_u32 s36, s36, 0x4000
	s_addc_u32 s37, s37, 0
	global_load_dwordx4 v[196:199], v247, s[36:37]
	s_add_u32 s36, s36, 0x4000
	s_addc_u32 s37, s37, 0
	global_load_dwordx4 v[200:203], v247, s[36:37]
	s_add_u32 s36, s36, 0x4000
	s_addc_u32 s37, s37, 0
	global_load_dwordx4 v[216:219], v247, s[36:37]
	s_add_u32 s36, s36, 0x4000
	s_addc_u32 s37, s37, 0
	global_load_dwordx4 v[220:223], v247, s[36:37]
	s_add_u32 s36, s36, 0x4000
	s_addc_u32 s37, s37, 0
	global_load_dwordx4 v[224:227], v247, s[36:37]
	s_add_u32 s36, s36, 0x4000
	s_addc_u32 s37, s37, 0
	ds_write_b128 v228, v[66:69]
	ds_write_b128 v229, v[70:73]
	ds_write_b128 v230, v[74:77]
	ds_write_b128 v231, v[78:81]
	ds_write_b128 v232, v[114:117]
	ds_write_b128 v233, v[118:121]
	ds_write_b128 v234, v[122:125]
	ds_write_b128 v235, v[126:129]
	ds_write_b128 v228, v[82:85] offset:8192
	ds_write_b128 v229, v[86:89] offset:8192
	ds_write_b128 v230, v[90:93] offset:8192
	ds_write_b128 v231, v[94:97] offset:8192
	ds_write_b128 v232, v[98:101] offset:8192
	ds_write_b128 v233, v[102:105] offset:8192
	ds_write_b128 v234, v[106:109] offset:8192
	ds_write_b128 v235, v[110:113] offset:8192
	global_load_dwordx4 v[66:69], v247, s[36:37]
	s_add_u32 s36, s36, 0x4000
	s_addc_u32 s37, s37, 0
	global_load_dwordx4 v[70:73], v247, s[36:37]
	s_add_u32 s36, s36, 0x4000
	s_addc_u32 s37, s37, 0
	global_load_dwordx4 v[74:77], v247, s[36:37]
	s_add_u32 s36, s36, 0x4000
	s_addc_u32 s37, s37, 0
	global_load_dwordx4 v[78:81], v247, s[36:37]
	s_add_u32 s36, s36, 0x4000
	s_addc_u32 s37, s37, 0
	global_load_dwordx4 v[114:117], v247, s[36:37]
	s_add_u32 s36, s36, 0x4000
	s_addc_u32 s37, s37, 0
	global_load_dwordx4 v[118:121], v247, s[36:37]
	s_add_u32 s36, s36, 0x4000
	s_addc_u32 s37, s37, 0
	global_load_dwordx4 v[122:125], v247, s[36:37]
	s_add_u32 s36, s36, 0x4000
	s_addc_u32 s37, s37, 0
	global_load_dwordx4 v[126:129], v247, s[36:37]
	s_add_u32 s36, s36, 0x4000
	s_addc_u32 s37, s37, 0
	global_load_dwordx4 v[82:85], v247, s[36:37]
	s_add_u32 s36, s36, 0x4000
	s_addc_u32 s37, s37, 0
	global_load_dwordx4 v[86:89], v247, s[36:37]
	s_add_u32 s36, s36, 0x4000
	s_addc_u32 s37, s37, 0
	global_load_dwordx4 v[90:93], v247, s[36:37]
	s_add_u32 s36, s36, 0x4000
	s_addc_u32 s37, s37, 0
	global_load_dwordx4 v[94:97], v247, s[36:37]
	s_add_u32 s36, s36, 0x4000
	s_addc_u32 s37, s37, 0
	global_load_dwordx4 v[98:101], v247, s[36:37]
	s_add_u32 s36, s36, 0x4000
	s_addc_u32 s37, s37, 0
	global_load_dwordx4 v[102:105], v247, s[36:37]
	s_add_u32 s36, s36, 0x4000
	s_addc_u32 s37, s37, 0
	global_load_dwordx4 v[106:109], v247, s[36:37]
	s_add_u32 s36, s36, 0x4000
	s_addc_u32 s37, s37, 0
	global_load_dwordx4 v[110:113], v247, s[36:37]
	s_add_u32 s36, s36, 0x4000
	s_addc_u32 s37, s37, 0
	s_waitcnt lgkmcnt(0)
	ds_read_b128 v[228:231], v210 offset:0
	ds_read_b128 v[238:241], v211 offset:1024
	s_waitcnt vmcnt(31) lgkmcnt(1)
	v_pk_add_f32 v[130:131], v[228:229], v[130:131]
	v_pk_add_f32 v[132:133], v[230:231], v[132:133]
	ds_read_b128 v[228:231], v215 offset:2048
	global_store_dwordx4 v247, v[130:133], s[38:39] nt
	s_add_u32 s38, s38, 0x4000
	s_addc_u32 s39, s39, 0
	s_waitcnt vmcnt(31) lgkmcnt(1)
	v_pk_add_f32 v[134:135], v[238:239], v[134:135]
	v_pk_add_f32 v[136:137], v[240:241], v[136:137]
	ds_read_b128 v[238:241], v237 offset:3072
	global_store_dwordx4 v247, v[134:137], s[38:39] nt
	s_add_u32 s38, s38, 0x4000
	s_addc_u32 s39, s39, 0
	s_waitcnt vmcnt(31) lgkmcnt(1)
	v_pk_add_f32 v[138:139], v[228:229], v[138:139]
	v_pk_add_f32 v[140:141], v[230:231], v[140:141]
	ds_read_b128 v[228:231], v210 offset:4096
	global_store_dwordx4 v247, v[138:141], s[38:39] nt
	s_add_u32 s38, s38, 0x4000
	s_addc_u32 s39, s39, 0
	s_waitcnt vmcnt(31) lgkmcnt(1)
	v_pk_add_f32 v[142:143], v[238:239], v[142:143]
	v_pk_add_f32 v[144:145], v[240:241], v[144:145]
	ds_read_b128 v[238:241], v211 offset:5120
	global_store_dwordx4 v247, v[142:145], s[38:39] nt
	s_add_u32 s38, s38, 0x4000
	s_addc_u32 s39, s39, 0
	s_waitcnt vmcnt(31) lgkmcnt(1)
	v_pk_add_f32 v[146:147], v[228:229], v[146:147]
	v_pk_add_f32 v[148:149], v[230:231], v[148:149]
	ds_read_b128 v[228:231], v215 offset:6144
	global_store_dwordx4 v247, v[146:149], s[38:39] nt
	s_add_u32 s38, s38, 0x4000
	s_addc_u32 s39, s39, 0
	s_waitcnt vmcnt(31) lgkmcnt(1)
	v_pk_add_f32 v[150:151], v[238:239], v[150:151]
	v_pk_add_f32 v[152:153], v[240:241], v[152:153]
	ds_read_b128 v[238:241], v237 offset:7168
	global_store_dwordx4 v247, v[150:153], s[38:39] nt
	s_add_u32 s38, s38, 0x4000
	s_addc_u32 s39, s39, 0
	s_waitcnt vmcnt(31) lgkmcnt(1)
	v_pk_add_f32 v[154:155], v[228:229], v[154:155]
	v_pk_add_f32 v[156:157], v[230:231], v[156:157]
	ds_read_b128 v[228:231], v210 offset:8192
	global_store_dwordx4 v247, v[154:157], s[38:39] nt
	s_add_u32 s38, s38, 0x4000
	s_addc_u32 s39, s39, 0
	s_waitcnt vmcnt(31) lgkmcnt(1)
	v_pk_add_f32 v[158:159], v[238:239], v[158:159]
	v_pk_add_f32 v[160:161], v[240:241], v[160:161]
	ds_read_b128 v[238:241], v211 offset:9216
	global_store_dwordx4 v247, v[158:161], s[38:39] nt
	s_add_u32 s38, s38, 0x4000
	s_addc_u32 s39, s39, 0
	s_waitcnt vmcnt(31) lgkmcnt(1)
	v_pk_add_f32 v[162:163], v[228:229], v[162:163]
	v_pk_add_f32 v[164:165], v[230:231], v[164:165]
	ds_read_b128 v[228:231], v215 offset:10240
	global_store_dwordx4 v247, v[162:165], s[38:39] nt
	s_add_u32 s38, s38, 0x4000
	s_addc_u32 s39, s39, 0
	s_waitcnt vmcnt(31) lgkmcnt(1)
	v_pk_add_f32 v[166:167], v[238:239], v[166:167]
	v_pk_add_f32 v[168:169], v[240:241], v[168:169]
	ds_read_b128 v[238:241], v237 offset:11264
	global_store_dwordx4 v247, v[166:169], s[38:39] nt
	s_add_u32 s38, s38, 0x4000
	s_addc_u32 s39, s39, 0
	s_waitcnt vmcnt(31) lgkmcnt(1)
	v_pk_add_f32 v[192:193], v[228:229], v[192:193]
	v_pk_add_f32 v[194:195], v[230:231], v[194:195]
	ds_read_b128 v[228:231], v210 offset:12288
	global_store_dwordx4 v247, v[192:195], s[38:39] nt
	s_add_u32 s38, s38, 0x4000
	s_addc_u32 s39, s39, 0
	s_waitcnt vmcnt(31) lgkmcnt(1)
	v_pk_add_f32 v[196:197], v[238:239], v[196:197]
	v_pk_add_f32 v[198:199], v[240:241], v[198:199]
	ds_read_b128 v[238:241], v211 offset:13312
	global_store_dwordx4 v247, v[196:199], s[38:39] nt
	s_add_u32 s38, s38, 0x4000
	s_addc_u32 s39, s39, 0
	s_waitcnt vmcnt(31) lgkmcnt(1)
	v_pk_add_f32 v[200:201], v[228:229], v[200:201]
	v_pk_add_f32 v[202:203], v[230:231], v[202:203]
	ds_read_b128 v[228:231], v215 offset:14336
	global_store_dwordx4 v247, v[200:203], s[38:39] nt
	s_add_u32 s38, s38, 0x4000
	s_addc_u32 s39, s39, 0
	s_waitcnt vmcnt(31) lgkmcnt(1)
	v_pk_add_f32 v[216:217], v[238:239], v[216:217]
	v_pk_add_f32 v[218:219], v[240:241], v[218:219]
	ds_read_b128 v[238:241], v237 offset:15360
	global_store_dwordx4 v247, v[216:219], s[38:39] nt
	s_add_u32 s38, s38, 0x4000
	s_addc_u32 s39, s39, 0
	s_waitcnt vmcnt(31) lgkmcnt(1)
	v_pk_add_f32 v[220:221], v[228:229], v[220:221]
	v_pk_add_f32 v[222:223], v[230:231], v[222:223]
	global_store_dwordx4 v247, v[220:223], s[38:39] nt
	s_add_u32 s38, s38, 0x4000
	s_addc_u32 s39, s39, 0
	s_waitcnt vmcnt(31) lgkmcnt(0)
	v_pk_add_f32 v[224:225], v[238:239], v[224:225]
	v_pk_add_f32 v[226:227], v[240:241], v[226:227]
	global_store_dwordx4 v247, v[224:227], s[38:39] nt
	s_add_u32 s38, s38, 0x4000
	s_addc_u32 s39, s39, 0
	s_add_u32 s34, s34, 0x1000
	s_addc_u32 s35, s35, 0
	v_and_b32_e32 v238, 15, v170
	v_xor_b32_e32 v238, v238, v171
	v_lshl_add_u32 v239, v170, 8, s40
	v_xor_b32_e32 v228, 0, v238
	v_lshl_add_u32 v228, v228, 4, v239
	v_xor_b32_e32 v229, 2, v238
	v_lshl_add_u32 v229, v229, 4, v239
	v_xor_b32_e32 v230, 4, v238
	v_lshl_add_u32 v230, v230, 4, v239
	v_xor_b32_e32 v231, 6, v238
	v_lshl_add_u32 v231, v231, 4, v239
	v_xor_b32_e32 v232, 8, v238
	v_lshl_add_u32 v232, v232, 4, v239
	v_xor_b32_e32 v233, 10, v238
	v_lshl_add_u32 v233, v233, 4, v239
	v_xor_b32_e32 v234, 12, v238
	v_lshl_add_u32 v234, v234, 4, v239
	v_xor_b32_e32 v235, 14, v238
	v_lshl_add_u32 v235, v235, 4, v239
	ds_write_b128 v228, v[18:21]
	ds_write_b128 v229, v[22:25]
	ds_write_b128 v230, v[26:29]
	ds_write_b128 v231, v[30:33]
	ds_write_b128 v232, v[50:53]
	ds_write_b128 v233, v[54:57]
	ds_write_b128 v234, v[58:61]
	ds_write_b128 v235, v[62:65]
	ds_write_b128 v228, v[2:5] offset:8192
	ds_write_b128 v229, v[6:9] offset:8192
	ds_write_b128 v230, v[10:13] offset:8192
	ds_write_b128 v231, v[14:17] offset:8192
	ds_write_b128 v232, v[34:37] offset:8192
	ds_write_b128 v233, v[38:41] offset:8192
	ds_write_b128 v234, v[42:45] offset:8192
	ds_write_b128 v235, v[46:49] offset:8192
	s_waitcnt lgkmcnt(0)
	ds_read_b128 v[228:231], v210 offset:0
	ds_read_b128 v[238:241], v211 offset:1024
	s_waitcnt vmcnt(31) lgkmcnt(1)
	v_pk_add_f32 v[66:67], v[228:229], v[66:67]
	v_pk_add_f32 v[68:69], v[230:231], v[68:69]
	ds_read_b128 v[228:231], v215 offset:2048
	global_store_dwordx4 v247, v[66:69], s[38:39] nt
	s_add_u32 s38, s38, 0x4000
	s_addc_u32 s39, s39, 0
	s_waitcnt vmcnt(31) lgkmcnt(1)
	v_pk_add_f32 v[70:71], v[238:239], v[70:71]
	v_pk_add_f32 v[72:73], v[240:241], v[72:73]
	ds_read_b128 v[238:241], v237 offset:3072
	global_store_dwordx4 v247, v[70:73], s[38:39] nt
	s_add_u32 s38, s38, 0x4000
	s_addc_u32 s39, s39, 0
	s_waitcnt vmcnt(31) lgkmcnt(1)
	v_pk_add_f32 v[74:75], v[228:229], v[74:75]
	v_pk_add_f32 v[76:77], v[230:231], v[76:77]
	ds_read_b128 v[228:231], v210 offset:4096
	global_store_dwordx4 v247, v[74:77], s[38:39] nt
	s_add_u32 s38, s38, 0x4000
	s_addc_u32 s39, s39, 0
	s_waitcnt vmcnt(31) lgkmcnt(1)
	v_pk_add_f32 v[78:79], v[238:239], v[78:79]
	v_pk_add_f32 v[80:81], v[240:241], v[80:81]
	ds_read_b128 v[238:241], v211 offset:5120
	global_store_dwordx4 v247, v[78:81], s[38:39] nt
	s_add_u32 s38, s38, 0x4000
	s_addc_u32 s39, s39, 0
	s_waitcnt vmcnt(31) lgkmcnt(1)
	v_pk_add_f32 v[114:115], v[228:229], v[114:115]
	v_pk_add_f32 v[116:117], v[230:231], v[116:117]
	ds_read_b128 v[228:231], v215 offset:6144
	global_store_dwordx4 v247, v[114:117], s[38:39] nt
	s_add_u32 s38, s38, 0x4000
	s_addc_u32 s39, s39, 0
	s_waitcnt vmcnt(31) lgkmcnt(1)
	v_pk_add_f32 v[118:119], v[238:239], v[118:119]
	v_pk_add_f32 v[120:121], v[240:241], v[120:121]
	ds_read_b128 v[238:241], v237 offset:7168
	global_store_dwordx4 v247, v[118:121], s[38:39] nt
	s_add_u32 s38, s38, 0x4000
	s_addc_u32 s39, s39, 0
	s_waitcnt vmcnt(31) lgkmcnt(1)
	v_pk_add_f32 v[122:123], v[228:229], v[122:123]
	v_pk_add_f32 v[124:125], v[230:231], v[124:125]
	ds_read_b128 v[228:231], v210 offset:8192
	global_store_dwordx4 v247, v[122:125], s[38:39] nt
	s_add_u32 s38, s38, 0x4000
	s_addc_u32 s39, s39, 0
	s_waitcnt vmcnt(31) lgkmcnt(1)
	v_pk_add_f32 v[126:127], v[238:239], v[126:127]
	v_pk_add_f32 v[128:129], v[240:241], v[128:129]
	ds_read_b128 v[238:241], v211 offset:9216
	global_store_dwordx4 v247, v[126:129], s[38:39] nt
	s_add_u32 s38, s38, 0x4000
	s_addc_u32 s39, s39, 0
	s_waitcnt vmcnt(31) lgkmcnt(1)
	v_pk_add_f32 v[82:83], v[228:229], v[82:83]
	v_pk_add_f32 v[84:85], v[230:231], v[84:85]
	ds_read_b128 v[228:231], v215 offset:10240
	global_store_dwordx4 v247, v[82:85], s[38:39] nt
	s_add_u32 s38, s38, 0x4000
	s_addc_u32 s39, s39, 0
	s_waitcnt vmcnt(31) lgkmcnt(1)
	v_pk_add_f32 v[86:87], v[238:239], v[86:87]
	v_pk_add_f32 v[88:89], v[240:241], v[88:89]
	ds_read_b128 v[238:241], v237 offset:11264
	global_store_dwordx4 v247, v[86:89], s[38:39] nt
	s_add_u32 s38, s38, 0x4000
	s_addc_u32 s39, s39, 0
	s_waitcnt vmcnt(31) lgkmcnt(1)
	v_pk_add_f32 v[90:91], v[228:229], v[90:91]
	v_pk_add_f32 v[92:93], v[230:231], v[92:93]
	ds_read_b128 v[228:231], v210 offset:12288
	global_store_dwordx4 v247, v[90:93], s[38:39] nt
	s_add_u32 s38, s38, 0x4000
	s_addc_u32 s39, s39, 0
	s_waitcnt vmcnt(31) lgkmcnt(1)
	v_pk_add_f32 v[94:95], v[238:239], v[94:95]
	v_pk_add_f32 v[96:97], v[240:241], v[96:97]
	ds_read_b128 v[238:241], v211 offset:13312
	global_store_dwordx4 v247, v[94:97], s[38:39] nt
	s_add_u32 s38, s38, 0x4000
	s_addc_u32 s39, s39, 0
	s_waitcnt vmcnt(31) lgkmcnt(1)
	v_pk_add_f32 v[98:99], v[228:229], v[98:99]
	v_pk_add_f32 v[100:101], v[230:231], v[100:101]
	ds_read_b128 v[228:231], v215 offset:14336
	global_store_dwordx4 v247, v[98:101], s[38:39] nt
	s_add_u32 s38, s38, 0x4000
	s_addc_u32 s39, s39, 0
	s_waitcnt vmcnt(31) lgkmcnt(1)
	v_pk_add_f32 v[102:103], v[238:239], v[102:103]
	v_pk_add_f32 v[104:105], v[240:241], v[104:105]
	ds_read_b128 v[238:241], v237 offset:15360
	global_store_dwordx4 v247, v[102:105], s[38:39] nt
	s_add_u32 s38, s38, 0x4000
	s_addc_u32 s39, s39, 0
	s_waitcnt vmcnt(31) lgkmcnt(1)
	v_pk_add_f32 v[106:107], v[228:229], v[106:107]
	v_pk_add_f32 v[108:109], v[230:231], v[108:109]
	global_store_dwordx4 v247, v[106:109], s[38:39] nt
	s_add_u32 s38, s38, 0x4000
	s_addc_u32 s39, s39, 0
	s_waitcnt vmcnt(31) lgkmcnt(0)
	v_pk_add_f32 v[110:111], v[238:239], v[110:111]
	v_pk_add_f32 v[112:113], v[240:241], v[112:113]
	global_store_dwordx4 v247, v[110:113], s[38:39] nt
	s_add_u32 s38, s38, 0x4000
	s_addc_u32 s39, s39, 0
	s_waitcnt lgkmcnt(0)
	s_branch .LBB0_1677
